# hgwait + GEMM K-loops: removed the pre-barrier lgkmcnt(0) drains (LDS fragment reads now complete behind the barrier; the post-barrier lgkmcnt(0) before the MFMAs stays)
# baseline (speedup 1.0000x reference)
; #define PG8_STAGE(bufoff, gbase, voff) do { _Pragma("unroll") for (int _i = 0; _i < 2; ++_i) \
;         __builtin_amdgcn_global_load_lds((const unsigned*)((const char*)(gbase) + (voff)[_i]), (PG8_LAS unsigned*)(lds + (bufoff) + ldsw + _i * 8192), 16, 0, 0); } while (0)
; #define PG8_LDA(dst, b, h) do { _Pragma("unroll") for (int m = 0; m < 4; ++m) _Pragma("unroll") for (int k = 0; k < 2; ++k) dst[m][k] = *(const PG8_LAS bf16x8*)(lds + PG8_SA(b, h) + aoff + m * 2048 + k * 1024); } while (0)
; #define PG8_LDB(dst, b, h) do { _Pragma("unroll") for (int n = 0; n < 2; ++n) _Pragma("unroll") for (int k = 0; k < 2; ++k) dst[n][k] = *(const PG8_LAS bf16x8*)(lds + PG8_SB(b, h) + boff + n * 2048 + k * 1024); } while (0)
; #define PG8_MMA(ai, bj, At, Bt) do { __builtin_amdgcn_s_setprio(1); _Pragma("unroll") for (int m = 0; m < 4; ++m) _Pragma("unroll") for (int n = 0; n < 2; ++n) _Pragma("unroll") for (int k = 0; k < 2; ++k) \
;         acc[ai][bj][m][n] = __builtin_amdgcn_mfma_f32_16x16x32_bf16(Bt[n][k], At[m][k], acc[ai][bj][m][n], 0, 0, 0); __builtin_amdgcn_s_setprio(0); } while (0)
; #define PG8_WAIT_V(n) asm volatile("s_waitcnt vmcnt(" #n ")" ::: "memory")
; #define PG8_WAIT_L(n) asm volatile("s_waitcnt lgkmcnt(" #n ")" ::: "memory")
; #define PG8_BAR __builtin_amdgcn_s_barrier()
; #define PG8_SCHED __builtin_amdgcn_sched_barrier(0)
; template <class Epi, class Sched, bool ALIGN_EPI = false, bool SP2 = false>
; __device__ __forceinline__ void gemm_phase(PG8_LAS unsigned char* lds, const Gemm g, const Sched& S, const Epi& E) {
;     ...
;             PG8_LDB(B0, 0, 0); PG8_LDB(B1, 0, 1); PG8_SCHED; PG8_LDA(At, 0, 0); PG8_STAGE(PG8_SA(1, 1), a1 + hstep, voffA);
;             PG8_WAIT_V(8); PG8_WAIT_L(0); PG8_BAR; PG8_MMA(0, 0, At, B0); PG8_MMA(0, 1, At, B1); PG8_BAR; PG8_SCHED;
;             PG8_LDA(At, 0, 1); PG8_STAGE(PG8_SB(0, 0), b2, voffB); PG8_STAGE(PG8_SB(0, 1), b2 + hstep, voffB); PG8_STAGE(PG8_SA(0, 0), a2, voffA);
;             PG8_WAIT_V(8); PG8_WAIT_L(0); PG8_BAR; PG8_MMA(1, 0, At, B0); PG8_MMA(1, 1, At, B1); PG8_BAR; PG8_SCHED;
.Lpeel_g1o:
	s_add_u32 s5, s44, 0xfffc0080
	s_addc_u32 s8, s45, -1
	s_add_i32 s10, 0, 0x10000
	s_cmp_eq_u32 s76, 12
	s_cselect_b32 s67, s26, s8
	s_cselect_b32 s66, s27, s5
	v_add_u32_e32 v154, s10, v157
	s_cselect_b32 s65, s36, s59
	s_cselect_b32 s64, s39, s57
	s_add_i32 s5, 0, 0x14000
	ds_read_b128 v[162:165], v154
	ds_read_b128 v[166:169], v154 offset:1024
	ds_read_b128 v[170:173], v154 offset:2048
	ds_read_b128 v[174:177], v154 offset:3072
	v_add_u32_e32 v154, s5, v157
	ds_read_b128 v[178:181], v154
	ds_read_b128 v[182:185], v154 offset:1024
	ds_read_b128 v[186:189], v154 offset:2048
	ds_read_b128 v[190:193], v154 offset:3072
	v_lshl_add_u64 v[194:195], s[44:45], 0, v[140:141]
	s_add_i32 m0, s69, 0xc000
	ds_read_b128 v[200:203], v161
	ds_read_b128 v[204:207], v161 offset:1024
	ds_read_b128 v[208:211], v161 offset:2048
	ds_read_b128 v[212:215], v161 offset:3072
	ds_read_b128 v[216:219], v161 offset:4096
	ds_read_b128 v[220:223], v161 offset:5120
	ds_read_b128 v[224:227], v161 offset:6144
	ds_read_b128 v[228:231], v161 offset:7168
	global_load_lds_dwordx4 v[194:195], off
	v_lshl_add_u64 v[194:195], s[44:45], 0, v[138:139]
	s_add_i32 m0, s69, 0xe000
	s_nop 0
	global_load_lds_dwordx4 v[194:195], off
	s_waitcnt vmcnt(26)
	s_barrier
	s_setprio 1
	s_waitcnt lgkmcnt(0)
	v_mfma_f32_16x16x32_bf16 v[124:127], v[162:165], v[200:203], 0
	v_mfma_f32_16x16x32_bf16 v[120:123], v[170:173], v[200:203], 0
	v_mfma_f32_16x16x32_bf16 v[108:111], v[162:165], v[208:211], 0
	v_mfma_f32_16x16x32_bf16 v[104:107], v[170:173], v[208:211], 0
	v_mfma_f32_16x16x32_bf16 v[92:95], v[162:165], v[216:219], 0
	v_mfma_f32_16x16x32_bf16 v[88:91], v[170:173], v[216:219], 0
	v_mfma_f32_16x16x32_bf16 v[76:79], v[162:165], v[224:227], 0
	v_mfma_f32_16x16x32_bf16 v[72:75], v[170:173], v[224:227], 0
	v_mfma_f32_16x16x32_bf16 v[124:127], v[166:169], v[204:207], v[124:127]
	v_mfma_f32_16x16x32_bf16 v[120:123], v[174:177], v[204:207], v[120:123]
	v_mfma_f32_16x16x32_bf16 v[108:111], v[166:169], v[212:215], v[108:111]
	v_mfma_f32_16x16x32_bf16 v[104:107], v[174:177], v[212:215], v[104:107]
	v_mfma_f32_16x16x32_bf16 v[92:95], v[166:169], v[220:223], v[92:95]
	v_mfma_f32_16x16x32_bf16 v[88:91], v[174:177], v[220:223], v[88:91]
	v_mfma_f32_16x16x32_bf16 v[76:79], v[166:169], v[228:231], v[76:79]
	v_mfma_f32_16x16x32_bf16 v[72:75], v[174:177], v[228:231], v[72:75]
	s_setprio 0
	s_setprio 1
	v_mfma_f32_16x16x32_bf16 v[116:119], v[178:181], v[200:203], 0
	v_mfma_f32_16x16x32_bf16 v[112:115], v[186:189], v[200:203], 0
	v_mfma_f32_16x16x32_bf16 v[100:103], v[178:181], v[208:211], 0
	v_mfma_f32_16x16x32_bf16 v[96:99], v[186:189], v[208:211], 0
	v_mfma_f32_16x16x32_bf16 v[84:87], v[178:181], v[216:219], 0
	v_mfma_f32_16x16x32_bf16 v[80:83], v[186:189], v[216:219], 0
	v_mfma_f32_16x16x32_bf16 v[68:71], v[178:181], v[224:227], 0
	v_mfma_f32_16x16x32_bf16 v[64:67], v[186:189], v[224:227], 0
	v_mfma_f32_16x16x32_bf16 v[116:119], v[182:185], v[204:207], v[116:119]
	v_mfma_f32_16x16x32_bf16 v[112:115], v[190:193], v[204:207], v[112:115]
	v_mfma_f32_16x16x32_bf16 v[100:103], v[182:185], v[212:215], v[100:103]
	v_mfma_f32_16x16x32_bf16 v[96:99], v[190:193], v[212:215], v[96:99]
	v_mfma_f32_16x16x32_bf16 v[84:87], v[182:185], v[220:223], v[84:87]
	v_mfma_f32_16x16x32_bf16 v[80:83], v[190:193], v[220:223], v[80:83]
	v_mfma_f32_16x16x32_bf16 v[68:71], v[182:185], v[228:231], v[68:71]
	v_mfma_f32_16x16x32_bf16 v[64:67], v[190:193], v[228:231], v[64:67]
	s_setprio 0
	s_barrier
	s_add_i32 s8, s10, s68
	v_lshl_add_u64 v[194:195], s[64:65], 0, v[132:133]
	s_mov_b32 m0, s8
	ds_read_b128 v[200:203], v161 offset:16384
	ds_read_b128 v[204:207], v161 offset:17408
	ds_read_b128 v[208:211], v161 offset:18432
	ds_read_b128 v[212:215], v161 offset:19456
	ds_read_b128 v[216:219], v161 offset:20480
	ds_read_b128 v[220:223], v161 offset:21504
	ds_read_b128 v[224:227], v161 offset:22528
	ds_read_b128 v[228:231], v161 offset:23552
	global_load_lds_dwordx4 v[194:195], off
	s_add_i32 m0, s8, 0x2000
	s_add_u32 s20, s64, 0x40000
	v_lshl_add_u64 v[240:241], s[64:65], 0, v[128:129]
	s_addc_u32 s21, s65, 0
	s_add_i32 s5, s5, s68
	global_load_lds_dwordx4 v[240:241], off
	v_lshl_add_u64 v[242:243], s[20:21], 0, v[132:133]
	s_mov_b32 m0, s5
	v_lshl_add_u64 v[244:245], s[66:67], 0, v[130:131]
	global_load_lds_dwordx4 v[242:243], off
	v_lshl_add_u64 v[242:243], s[20:21], 0, v[128:129]
	s_add_i32 m0, s5, 0x2000
	s_nop 0
	global_load_lds_dwordx4 v[242:243], off
	v_lshl_add_u64 v[242:243], s[66:67], 0, v[134:135]
	s_mov_b32 m0, s69
	s_nop 0
	global_load_lds_dwordx4 v[242:243], off
	s_mov_b32 m0, s70
	s_nop 0
	global_load_lds_dwordx4 v[244:245], off
	s_waitcnt vmcnt(26)
	s_barrier
	s_setprio 1
	s_waitcnt lgkmcnt(0)
	v_mfma_f32_16x16x32_bf16 v[60:63], v[162:165], v[200:203], 0
	v_mfma_f32_16x16x32_bf16 v[56:59], v[170:173], v[200:203], 0
	v_mfma_f32_16x16x32_bf16 v[44:47], v[162:165], v[208:211], 0
	v_mfma_f32_16x16x32_bf16 v[40:43], v[170:173], v[208:211], 0
	v_mfma_f32_16x16x32_bf16 v[28:31], v[162:165], v[216:219], 0
	v_mfma_f32_16x16x32_bf16 v[24:27], v[170:173], v[216:219], 0
	v_mfma_f32_16x16x32_bf16 v[12:15], v[162:165], v[224:227], 0
	v_mfma_f32_16x16x32_bf16 v[8:11], v[170:173], v[224:227], 0
	v_mfma_f32_16x16x32_bf16 v[60:63], v[166:169], v[204:207], v[60:63]
	v_mfma_f32_16x16x32_bf16 v[56:59], v[174:177], v[204:207], v[56:59]
	v_mfma_f32_16x16x32_bf16 v[44:47], v[166:169], v[212:215], v[44:47]
	v_mfma_f32_16x16x32_bf16 v[40:43], v[174:177], v[212:215], v[40:43]
	v_mfma_f32_16x16x32_bf16 v[28:31], v[166:169], v[220:223], v[28:31]
	v_mfma_f32_16x16x32_bf16 v[24:27], v[174:177], v[220:223], v[24:27]
	v_mfma_f32_16x16x32_bf16 v[12:15], v[166:169], v[228:231], v[12:15]
	v_mfma_f32_16x16x32_bf16 v[8:11], v[174:177], v[228:231], v[8:11]
	s_setprio 0
	s_setprio 1
	v_mfma_f32_16x16x32_bf16 v[52:55], v[178:181], v[200:203], 0
	v_mfma_f32_16x16x32_bf16 v[48:51], v[186:189], v[200:203], 0
	v_mfma_f32_16x16x32_bf16 v[36:39], v[178:181], v[208:211], 0
	v_mfma_f32_16x16x32_bf16 v[32:35], v[186:189], v[208:211], 0
	v_mfma_f32_16x16x32_bf16 v[20:23], v[178:181], v[216:219], 0
	v_mfma_f32_16x16x32_bf16 v[16:19], v[186:189], v[216:219], 0
	v_mfma_f32_16x16x32_bf16 v[4:7], v[178:181], v[224:227], 0
	v_mfma_f32_16x16x32_bf16 v[0:3], v[186:189], v[224:227], 0
	v_mfma_f32_16x16x32_bf16 v[52:55], v[182:185], v[204:207], v[52:55]
	v_mfma_f32_16x16x32_bf16 v[48:51], v[190:193], v[204:207], v[48:51]
	v_mfma_f32_16x16x32_bf16 v[36:39], v[182:185], v[212:215], v[36:39]
	v_mfma_f32_16x16x32_bf16 v[32:35], v[190:193], v[212:215], v[32:35]
	v_mfma_f32_16x16x32_bf16 v[20:23], v[182:185], v[220:223], v[20:23]
	v_mfma_f32_16x16x32_bf16 v[16:19], v[190:193], v[220:223], v[16:19]
	v_mfma_f32_16x16x32_bf16 v[4:7], v[182:185], v[228:231], v[4:7]
	v_mfma_f32_16x16x32_bf16 v[0:3], v[190:193], v[228:231], v[0:3]
	s_setprio 0
	s_barrier
	s_branch .Lmid_g1o

; #define PG8_STAGE(bufoff, gbase, voff) do { _Pragma("unroll") for (int _i = 0; _i < 2; ++_i) \
;         __builtin_amdgcn_global_load_lds((const unsigned*)((const char*)(gbase) + (voff)[_i]), (PG8_LAS unsigned*)(lds + (bufoff) + ldsw + _i * 8192), 16, 0, 0); } while (0)
; #define PG8_LDA(dst, b, h) do { _Pragma("unroll") for (int m = 0; m < 4; ++m) _Pragma("unroll") for (int k = 0; k < 2; ++k) dst[m][k] = *(const PG8_LAS bf16x8*)(lds + PG8_SA(b, h) + aoff + m * 2048 + k * 1024); } while (0)
; #define PG8_LDB(dst, b, h) do { _Pragma("unroll") for (int n = 0; n < 2; ++n) _Pragma("unroll") for (int k = 0; k < 2; ++k) dst[n][k] = *(const PG8_LAS bf16x8*)(lds + PG8_SB(b, h) + boff + n * 2048 + k * 1024); } while (0)
; #define PG8_MMA(ai, bj, At, Bt) do { __builtin_amdgcn_s_setprio(1); _Pragma("unroll") for (int m = 0; m < 4; ++m) _Pragma("unroll") for (int n = 0; n < 2; ++n) _Pragma("unroll") for (int k = 0; k < 2; ++k) \
;         acc[ai][bj][m][n] = __builtin_amdgcn_mfma_f32_16x16x32_bf16(Bt[n][k], At[m][k], acc[ai][bj][m][n], 0, 0, 0); __builtin_amdgcn_s_setprio(0); } while (0)
; #define PG8_WAIT_V(n) asm volatile("s_waitcnt vmcnt(" #n ")" ::: "memory")
; #define PG8_WAIT_L(n) asm volatile("s_waitcnt lgkmcnt(" #n ")" ::: "memory")
; #define PG8_BAR __builtin_amdgcn_s_barrier()
; #define PG8_SCHED __builtin_amdgcn_sched_barrier(0)
; template <class Epi, class Sched, bool ALIGN_EPI = false, bool SP2 = false>
; __device__ __forceinline__ void gemm_phase(PG8_LAS unsigned char* lds, const Gemm g, const Sched& S, const Epi& E) {
;     ...
;             PG8_LDB(B0, 0, 0); PG8_LDB(B1, 0, 1); PG8_SCHED; PG8_LDA(At, 0, 0); PG8_STAGE(PG8_SA(1, 1), a1 + hstep, voffA);
;             PG8_WAIT_V(8); PG8_WAIT_L(0); PG8_BAR; PG8_MMA(0, 0, At, B0); PG8_MMA(0, 1, At, B1); PG8_BAR; PG8_SCHED;
;             PG8_LDA(At, 0, 1); PG8_STAGE(PG8_SB(0, 0), b2, voffB); PG8_STAGE(PG8_SB(0, 1), b2 + hstep, voffB); PG8_STAGE(PG8_SA(0, 0), a2, voffA);
;             PG8_WAIT_V(8); PG8_WAIT_L(0); PG8_BAR; PG8_MMA(1, 0, At, B0); PG8_MMA(1, 1, At, B1); PG8_BAR; PG8_SCHED;
.LBB0_54:
	s_add_u32 s5, s44, 0xfffc0080
	s_addc_u32 s8, s45, -1
	s_add_i32 s10, 0, 0x10000
	s_cmp_eq_u32 s76, 12
	s_cselect_b32 s67, s26, s8
	s_cselect_b32 s66, s27, s5
	v_add_u32_e32 v154, s10, v157
	s_cselect_b32 s65, s36, s59
	s_cselect_b32 s64, s39, s57
	s_add_i32 s5, 0, 0x14000
	ds_read_b128 v[162:165], v154
	ds_read_b128 v[166:169], v154 offset:1024
	ds_read_b128 v[170:173], v154 offset:2048
	ds_read_b128 v[174:177], v154 offset:3072
	v_add_u32_e32 v154, s5, v157
	ds_read_b128 v[178:181], v154
	ds_read_b128 v[182:185], v154 offset:1024
	ds_read_b128 v[186:189], v154 offset:2048
	ds_read_b128 v[190:193], v154 offset:3072
	v_lshl_add_u64 v[194:195], s[44:45], 0, v[140:141]
	s_add_i32 m0, s69, 0xc000
	ds_read_b128 v[200:203], v161
	ds_read_b128 v[204:207], v161 offset:1024
	ds_read_b128 v[208:211], v161 offset:2048
	ds_read_b128 v[212:215], v161 offset:3072
	ds_read_b128 v[216:219], v161 offset:4096
	ds_read_b128 v[220:223], v161 offset:5120
	ds_read_b128 v[224:227], v161 offset:6144
	ds_read_b128 v[228:231], v161 offset:7168
	global_load_lds_dwordx4 v[194:195], off
	v_lshl_add_u64 v[194:195], s[44:45], 0, v[138:139]
	s_add_i32 m0, s69, 0xe000
	s_nop 0
	global_load_lds_dwordx4 v[194:195], off
	s_waitcnt vmcnt(8)
	s_barrier
	s_setprio 1
	s_waitcnt lgkmcnt(0)
	v_mfma_f32_16x16x32_bf16 v[124:127], v[162:165], v[200:203], v[124:127]
	v_mfma_f32_16x16x32_bf16 v[120:123], v[170:173], v[200:203], v[120:123]
	v_mfma_f32_16x16x32_bf16 v[108:111], v[162:165], v[208:211], v[108:111]
	v_mfma_f32_16x16x32_bf16 v[104:107], v[170:173], v[208:211], v[104:107]
	v_mfma_f32_16x16x32_bf16 v[92:95], v[162:165], v[216:219], v[92:95]
	v_mfma_f32_16x16x32_bf16 v[88:91], v[170:173], v[216:219], v[88:91]
	v_mfma_f32_16x16x32_bf16 v[76:79], v[162:165], v[224:227], v[76:79]
	v_mfma_f32_16x16x32_bf16 v[72:75], v[170:173], v[224:227], v[72:75]
	v_mfma_f32_16x16x32_bf16 v[124:127], v[166:169], v[204:207], v[124:127]
	v_mfma_f32_16x16x32_bf16 v[120:123], v[174:177], v[204:207], v[120:123]
	v_mfma_f32_16x16x32_bf16 v[108:111], v[166:169], v[212:215], v[108:111]
	v_mfma_f32_16x16x32_bf16 v[104:107], v[174:177], v[212:215], v[104:107]
	v_mfma_f32_16x16x32_bf16 v[92:95], v[166:169], v[220:223], v[92:95]
	v_mfma_f32_16x16x32_bf16 v[88:91], v[174:177], v[220:223], v[88:91]
	v_mfma_f32_16x16x32_bf16 v[76:79], v[166:169], v[228:231], v[76:79]
	v_mfma_f32_16x16x32_bf16 v[72:75], v[174:177], v[228:231], v[72:75]
	s_setprio 0
	s_setprio 1
	v_mfma_f32_16x16x32_bf16 v[116:119], v[178:181], v[200:203], v[116:119]
	v_mfma_f32_16x16x32_bf16 v[112:115], v[186:189], v[200:203], v[112:115]
	v_mfma_f32_16x16x32_bf16 v[100:103], v[178:181], v[208:211], v[100:103]
	v_mfma_f32_16x16x32_bf16 v[96:99], v[186:189], v[208:211], v[96:99]
	v_mfma_f32_16x16x32_bf16 v[84:87], v[178:181], v[216:219], v[84:87]
	v_mfma_f32_16x16x32_bf16 v[80:83], v[186:189], v[216:219], v[80:83]
	v_mfma_f32_16x16x32_bf16 v[68:71], v[178:181], v[224:227], v[68:71]
	v_mfma_f32_16x16x32_bf16 v[64:67], v[186:189], v[224:227], v[64:67]
	v_mfma_f32_16x16x32_bf16 v[116:119], v[182:185], v[204:207], v[116:119]
	v_mfma_f32_16x16x32_bf16 v[112:115], v[190:193], v[204:207], v[112:115]
	v_mfma_f32_16x16x32_bf16 v[100:103], v[182:185], v[212:215], v[100:103]
	v_mfma_f32_16x16x32_bf16 v[96:99], v[190:193], v[212:215], v[96:99]
	v_mfma_f32_16x16x32_bf16 v[84:87], v[182:185], v[220:223], v[84:87]
	v_mfma_f32_16x16x32_bf16 v[80:83], v[190:193], v[220:223], v[80:83]
	v_mfma_f32_16x16x32_bf16 v[68:71], v[182:185], v[228:231], v[68:71]
	v_mfma_f32_16x16x32_bf16 v[64:67], v[190:193], v[228:231], v[64:67]
	s_setprio 0
	s_barrier
	s_add_i32 s8, s10, s68
	v_lshl_add_u64 v[194:195], s[64:65], 0, v[132:133]
	s_mov_b32 m0, s8
	ds_read_b128 v[200:203], v161 offset:16384
	ds_read_b128 v[204:207], v161 offset:17408
	ds_read_b128 v[208:211], v161 offset:18432
	ds_read_b128 v[212:215], v161 offset:19456
	ds_read_b128 v[216:219], v161 offset:20480
	ds_read_b128 v[220:223], v161 offset:21504
	ds_read_b128 v[224:227], v161 offset:22528
	ds_read_b128 v[228:231], v161 offset:23552
	global_load_lds_dwordx4 v[194:195], off
	s_add_i32 m0, s8, 0x2000
	s_add_u32 s20, s64, 0x40000
	v_lshl_add_u64 v[240:241], s[64:65], 0, v[128:129]
	s_addc_u32 s21, s65, 0
	s_add_i32 s5, s5, s68
	global_load_lds_dwordx4 v[240:241], off
	v_lshl_add_u64 v[242:243], s[20:21], 0, v[132:133]
	s_mov_b32 m0, s5
	v_lshl_add_u64 v[244:245], s[66:67], 0, v[130:131]
	global_load_lds_dwordx4 v[242:243], off
	v_lshl_add_u64 v[242:243], s[20:21], 0, v[128:129]
	s_add_i32 m0, s5, 0x2000
	s_nop 0
	global_load_lds_dwordx4 v[242:243], off
	v_lshl_add_u64 v[242:243], s[66:67], 0, v[134:135]
	s_mov_b32 m0, s69
	s_nop 0
	global_load_lds_dwordx4 v[242:243], off
	s_mov_b32 m0, s70
	s_nop 0
	global_load_lds_dwordx4 v[244:245], off
	s_waitcnt vmcnt(8)
	s_barrier
; #define PG8_STAGE(bufoff, gbase, voff) do { _Pragma("unroll") for (int _i = 0; _i < 2; ++_i) \
;         __builtin_amdgcn_global_load_lds((const unsigned*)((const char*)(gbase) + (voff)[_i]), (PG8_LAS unsigned*)(lds + (bufoff) + ldsw + _i * 8192), 16, 0, 0); } while (0)
; #define PG8_LDA(dst, b, h) do { _Pragma("unroll") for (int m = 0; m < 4; ++m) _Pragma("unroll") for (int k = 0; k < 2; ++k) dst[m][k] = *(const PG8_LAS bf16x8*)(lds + PG8_SA(b, h) + aoff + m * 2048 + k * 1024); } while (0)
; #define PG8_LDB(dst, b, h) do { _Pragma("unroll") for (int n = 0; n < 2; ++n) _Pragma("unroll") for (int k = 0; k < 2; ++k) dst[n][k] = *(const PG8_LAS bf16x8*)(lds + PG8_SB(b, h) + boff + n * 2048 + k * 1024); } while (0)
; #define PG8_MMA(ai, bj, At, Bt) do { __builtin_amdgcn_s_setprio(1); _Pragma("unroll") for (int m = 0; m < 4; ++m) _Pragma("unroll") for (int n = 0; n < 2; ++n) _Pragma("unroll") for (int k = 0; k < 2; ++k) \
;         acc[ai][bj][m][n] = __builtin_amdgcn_mfma_f32_16x16x32_bf16(Bt[n][k], At[m][k], acc[ai][bj][m][n], 0, 0, 0); __builtin_amdgcn_s_setprio(0); } while (0)
; #define PG8_WAIT_V(n) asm volatile("s_waitcnt vmcnt(" #n ")" ::: "memory")
; #define PG8_WAIT_L(n) asm volatile("s_waitcnt lgkmcnt(" #n ")" ::: "memory")
; #define PG8_BAR __builtin_amdgcn_s_barrier()
; #define PG8_SCHED __builtin_amdgcn_sched_barrier(0)
; template <class Epi, class Sched, bool ALIGN_EPI = false, bool SP2 = false>
; __device__ __forceinline__ void gemm_phase(PG8_LAS unsigned char* lds, const Gemm g, const Sched& S, const Epi& E) {
;     ...
;             PG8_WAIT_V(8); PG8_WAIT_L(0); PG8_BAR; PG8_MMA(1, 0, At, B0); PG8_MMA(1, 1, At, B1); PG8_BAR; PG8_SCHED;
;             PG8_LDB(B0, 1, 0); PG8_LDB(B1, 1, 1); PG8_SCHED; PG8_LDA(At, 1, 0); PG8_STAGE(PG8_SA(0, 1), a2 + hstep, voffA);
;             PG8_WAIT_V(8); PG8_WAIT_L(0); PG8_BAR; PG8_MMA(0, 0, At, B0); PG8_MMA(0, 1, At, B1); PG8_BAR; PG8_SCHED;
	s_setprio 1
	s_waitcnt lgkmcnt(0)
	v_mfma_f32_16x16x32_bf16 v[60:63], v[162:165], v[200:203], v[60:63]
	v_mfma_f32_16x16x32_bf16 v[56:59], v[170:173], v[200:203], v[56:59]
	v_mfma_f32_16x16x32_bf16 v[44:47], v[162:165], v[208:211], v[44:47]
	v_mfma_f32_16x16x32_bf16 v[40:43], v[170:173], v[208:211], v[40:43]
	v_mfma_f32_16x16x32_bf16 v[28:31], v[162:165], v[216:219], v[28:31]
	v_mfma_f32_16x16x32_bf16 v[24:27], v[170:173], v[216:219], v[24:27]
	v_mfma_f32_16x16x32_bf16 v[12:15], v[162:165], v[224:227], v[12:15]
	v_mfma_f32_16x16x32_bf16 v[8:11], v[170:173], v[224:227], v[8:11]
	v_mfma_f32_16x16x32_bf16 v[60:63], v[166:169], v[204:207], v[60:63]
	v_mfma_f32_16x16x32_bf16 v[56:59], v[174:177], v[204:207], v[56:59]
	v_mfma_f32_16x16x32_bf16 v[44:47], v[166:169], v[212:215], v[44:47]
	v_mfma_f32_16x16x32_bf16 v[40:43], v[174:177], v[212:215], v[40:43]
	v_mfma_f32_16x16x32_bf16 v[28:31], v[166:169], v[220:223], v[28:31]
	v_mfma_f32_16x16x32_bf16 v[24:27], v[174:177], v[220:223], v[24:27]
	v_mfma_f32_16x16x32_bf16 v[12:15], v[166:169], v[228:231], v[12:15]
	v_mfma_f32_16x16x32_bf16 v[8:11], v[174:177], v[228:231], v[8:11]
	s_setprio 0
	s_setprio 1
	v_mfma_f32_16x16x32_bf16 v[52:55], v[178:181], v[200:203], v[52:55]
	v_mfma_f32_16x16x32_bf16 v[48:51], v[186:189], v[200:203], v[48:51]
	v_mfma_f32_16x16x32_bf16 v[36:39], v[178:181], v[208:211], v[36:39]
	v_mfma_f32_16x16x32_bf16 v[32:35], v[186:189], v[208:211], v[32:35]
	v_mfma_f32_16x16x32_bf16 v[20:23], v[178:181], v[216:219], v[20:23]
	v_mfma_f32_16x16x32_bf16 v[16:19], v[186:189], v[216:219], v[16:19]
	v_mfma_f32_16x16x32_bf16 v[4:7], v[178:181], v[224:227], v[4:7]
	v_mfma_f32_16x16x32_bf16 v[0:3], v[186:189], v[224:227], v[0:3]
	v_mfma_f32_16x16x32_bf16 v[52:55], v[182:185], v[204:207], v[52:55]
	v_mfma_f32_16x16x32_bf16 v[48:51], v[190:193], v[204:207], v[48:51]
	v_mfma_f32_16x16x32_bf16 v[36:39], v[182:185], v[212:215], v[36:39]
	v_mfma_f32_16x16x32_bf16 v[32:35], v[190:193], v[212:215], v[32:35]
	v_mfma_f32_16x16x32_bf16 v[20:23], v[182:185], v[220:223], v[20:23]
	v_mfma_f32_16x16x32_bf16 v[16:19], v[190:193], v[220:223], v[16:19]
	v_mfma_f32_16x16x32_bf16 v[4:7], v[182:185], v[228:231], v[4:7]
	v_mfma_f32_16x16x32_bf16 v[0:3], v[190:193], v[228:231], v[0:3]
	s_setprio 0
	s_barrier
.Lmid_g1o:
	s_add_i32 s5, 0, 0x18000
	v_add_u32_e32 v154, s5, v157
	s_add_i32 s8, 0, 0x1c000
	ds_read_b128 v[162:165], v154
	ds_read_b128 v[166:169], v154 offset:1024
	ds_read_b128 v[170:173], v154 offset:2048
	ds_read_b128 v[174:177], v154 offset:3072
	v_add_u32_e32 v154, s8, v157
	ds_read_b128 v[178:181], v154
	ds_read_b128 v[182:185], v154 offset:1024
	ds_read_b128 v[186:189], v154 offset:2048
	ds_read_b128 v[190:193], v154 offset:3072
	s_add_u32 s20, s66, 0x40000
	s_addc_u32 s21, s67, 0
	s_mov_b32 m0, s71
	v_lshl_add_u64 v[246:247], s[20:21], 0, v[134:135]
	ds_read_b128 v[200:203], v161 offset:32768
	ds_read_b128 v[204:207], v161 offset:33792
	ds_read_b128 v[208:211], v161 offset:34816
	ds_read_b128 v[212:215], v161 offset:35840
	ds_read_b128 v[216:219], v161 offset:36864
	ds_read_b128 v[220:223], v161 offset:37888
	ds_read_b128 v[224:227], v161 offset:38912
	ds_read_b128 v[228:231], v161 offset:39936
	global_load_lds_dwordx4 v[246:247], off
	v_lshl_add_u64 v[246:247], s[20:21], 0, v[130:131]
	s_mov_b32 m0, s72
	s_nop 0
	global_load_lds_dwordx4 v[246:247], off
	s_waitcnt vmcnt(8)
	s_barrier
	s_setprio 1
	s_waitcnt lgkmcnt(0)
	v_mfma_f32_16x16x32_bf16 v[124:127], v[162:165], v[200:203], v[124:127]
	v_mfma_f32_16x16x32_bf16 v[120:123], v[170:173], v[200:203], v[120:123]
	v_mfma_f32_16x16x32_bf16 v[108:111], v[162:165], v[208:211], v[108:111]
	v_mfma_f32_16x16x32_bf16 v[104:107], v[170:173], v[208:211], v[104:107]
	v_mfma_f32_16x16x32_bf16 v[92:95], v[162:165], v[216:219], v[92:95]
	v_mfma_f32_16x16x32_bf16 v[88:91], v[170:173], v[216:219], v[88:91]
	v_mfma_f32_16x16x32_bf16 v[76:79], v[162:165], v[224:227], v[76:79]
	v_mfma_f32_16x16x32_bf16 v[72:75], v[170:173], v[224:227], v[72:75]
	v_mfma_f32_16x16x32_bf16 v[124:127], v[166:169], v[204:207], v[124:127]
	v_mfma_f32_16x16x32_bf16 v[120:123], v[174:177], v[204:207], v[120:123]
	v_mfma_f32_16x16x32_bf16 v[108:111], v[166:169], v[212:215], v[108:111]
	v_mfma_f32_16x16x32_bf16 v[104:107], v[174:177], v[212:215], v[104:107]
	v_mfma_f32_16x16x32_bf16 v[92:95], v[166:169], v[220:223], v[92:95]
	v_mfma_f32_16x16x32_bf16 v[88:91], v[174:177], v[220:223], v[88:91]
	v_mfma_f32_16x16x32_bf16 v[76:79], v[166:169], v[228:231], v[76:79]
	v_mfma_f32_16x16x32_bf16 v[72:75], v[174:177], v[228:231], v[72:75]
	s_setprio 0
	s_setprio 1
	v_mfma_f32_16x16x32_bf16 v[116:119], v[178:181], v[200:203], v[116:119]
	v_mfma_f32_16x16x32_bf16 v[112:115], v[186:189], v[200:203], v[112:115]
	v_mfma_f32_16x16x32_bf16 v[100:103], v[178:181], v[208:211], v[100:103]
	v_mfma_f32_16x16x32_bf16 v[96:99], v[186:189], v[208:211], v[96:99]
	v_mfma_f32_16x16x32_bf16 v[84:87], v[178:181], v[216:219], v[84:87]
	v_mfma_f32_16x16x32_bf16 v[80:83], v[186:189], v[216:219], v[80:83]
	v_mfma_f32_16x16x32_bf16 v[68:71], v[178:181], v[224:227], v[68:71]
	v_mfma_f32_16x16x32_bf16 v[64:67], v[186:189], v[224:227], v[64:67]
	v_mfma_f32_16x16x32_bf16 v[116:119], v[182:185], v[204:207], v[116:119]
	v_mfma_f32_16x16x32_bf16 v[112:115], v[190:193], v[204:207], v[112:115]
	v_mfma_f32_16x16x32_bf16 v[100:103], v[182:185], v[212:215], v[100:103]
	v_mfma_f32_16x16x32_bf16 v[96:99], v[190:193], v[212:215], v[96:99]
	v_mfma_f32_16x16x32_bf16 v[84:87], v[182:185], v[220:223], v[84:87]
	v_mfma_f32_16x16x32_bf16 v[80:83], v[190:193], v[220:223], v[80:83]
	v_mfma_f32_16x16x32_bf16 v[68:71], v[182:185], v[228:231], v[68:71]
	v_mfma_f32_16x16x32_bf16 v[64:67], v[190:193], v[228:231], v[64:67]
	s_setprio 0
	s_barrier
; #define PG8_STAGE(bufoff, gbase, voff) do { _Pragma("unroll") for (int _i = 0; _i < 2; ++_i) \
;         __builtin_amdgcn_global_load_lds((const unsigned*)((const char*)(gbase) + (voff)[_i]), (PG8_LAS unsigned*)(lds + (bufoff) + ldsw + _i * 8192), 16, 0, 0); } while (0)
; #define PG8_LDA(dst, b, h) do { _Pragma("unroll") for (int m = 0; m < 4; ++m) _Pragma("unroll") for (int k = 0; k < 2; ++k) dst[m][k] = *(const PG8_LAS bf16x8*)(lds + PG8_SA(b, h) + aoff + m * 2048 + k * 1024); } while (0)
; #define PG8_MMA(ai, bj, At, Bt) do { __builtin_amdgcn_s_setprio(1); _Pragma("unroll") for (int m = 0; m < 4; ++m) _Pragma("unroll") for (int n = 0; n < 2; ++n) _Pragma("unroll") for (int k = 0; k < 2; ++k) \
;         acc[ai][bj][m][n] = __builtin_amdgcn_mfma_f32_16x16x32_bf16(Bt[n][k], At[m][k], acc[ai][bj][m][n], 0, 0, 0); __builtin_amdgcn_s_setprio(0); } while (0)
; #define PG8_WAIT_V(n) asm volatile("s_waitcnt vmcnt(" #n ")" ::: "memory")
; #define PG8_WAIT_L(n) asm volatile("s_waitcnt lgkmcnt(" #n ")" ::: "memory")
; #define PG8_BAR __builtin_amdgcn_s_barrier()
; #define PG8_SCHED __builtin_amdgcn_sched_barrier(0)
; template <class Epi, class Sched, bool ALIGN_EPI = false, bool SP2 = false>
; __device__ __forceinline__ void gemm_phase(PG8_LAS unsigned char* lds, const Gemm g, const Sched& S, const Epi& E) {
;     ...
;             PG8_LDA(At, 1, 1); PG8_STAGE(PG8_SB(1, 0), b3, voffB); PG8_STAGE(PG8_SB(1, 1), b3 + hstep, voffB); PG8_STAGE(PG8_SA(1, 0), a3, voffA);
;             PG8_WAIT_V(8); PG8_WAIT_L(0); PG8_BAR; PG8_MMA(1, 0, At, B0); PG8_MMA(1, 1, At, B1); PG8_BAR; PG8_SCHED;
;     ...
;         if constexpr (ALIGN_EPI) { if (wr == 0) PG8_BAR; }
	s_add_i32 s5, s5, s68
	v_lshl_add_u64 v[194:195], v[194:195], 0, s[22:23]
	s_mov_b32 m0, s5
	ds_read_b128 v[200:203], v161 offset:49152
	ds_read_b128 v[204:207], v161 offset:50176
	ds_read_b128 v[208:211], v161 offset:51200
	ds_read_b128 v[212:215], v161 offset:52224
	ds_read_b128 v[216:219], v161 offset:53248
	ds_read_b128 v[220:223], v161 offset:54272
	ds_read_b128 v[224:227], v161 offset:55296
	ds_read_b128 v[228:231], v161 offset:56320
	global_load_lds_dwordx4 v[194:195], off
	s_add_i32 m0, s5, 0x2000
	s_add_u32 s20, s64, 0x40080
	v_lshl_add_u64 v[194:195], v[240:241], 0, s[22:23]
	s_addc_u32 s21, s65, 0
	s_add_i32 s5, s8, s68
	global_load_lds_dwordx4 v[194:195], off
	v_lshl_add_u64 v[194:195], s[20:21], 0, v[132:133]
	s_mov_b32 m0, s5
	s_nop 0
	global_load_lds_dwordx4 v[194:195], off
	v_lshl_add_u64 v[194:195], s[20:21], 0, v[128:129]
	s_add_i32 m0, s5, 0x2000
	s_nop 0
	global_load_lds_dwordx4 v[194:195], off
	v_lshl_add_u64 v[194:195], v[242:243], 0, s[22:23]
	s_mov_b32 m0, s73
	s_nop 0
	global_load_lds_dwordx4 v[194:195], off
	v_lshl_add_u64 v[194:195], v[244:245], 0, s[22:23]
	s_mov_b32 m0, s74
	s_nop 0
	global_load_lds_dwordx4 v[194:195], off
	s_waitcnt vmcnt(8)
	s_barrier
	s_setprio 1
	s_waitcnt lgkmcnt(0)
	v_mfma_f32_16x16x32_bf16 v[60:63], v[162:165], v[200:203], v[60:63]
	v_mfma_f32_16x16x32_bf16 v[56:59], v[170:173], v[200:203], v[56:59]
	v_mfma_f32_16x16x32_bf16 v[44:47], v[162:165], v[208:211], v[44:47]
	v_mfma_f32_16x16x32_bf16 v[40:43], v[170:173], v[208:211], v[40:43]
	v_mfma_f32_16x16x32_bf16 v[28:31], v[162:165], v[216:219], v[28:31]
	v_mfma_f32_16x16x32_bf16 v[24:27], v[170:173], v[216:219], v[24:27]
	v_mfma_f32_16x16x32_bf16 v[12:15], v[162:165], v[224:227], v[12:15]
	v_mfma_f32_16x16x32_bf16 v[8:11], v[170:173], v[224:227], v[8:11]
	v_mfma_f32_16x16x32_bf16 v[60:63], v[166:169], v[204:207], v[60:63]
	v_mfma_f32_16x16x32_bf16 v[56:59], v[174:177], v[204:207], v[56:59]
	v_mfma_f32_16x16x32_bf16 v[44:47], v[166:169], v[212:215], v[44:47]
	v_mfma_f32_16x16x32_bf16 v[40:43], v[174:177], v[212:215], v[40:43]
	v_mfma_f32_16x16x32_bf16 v[28:31], v[166:169], v[220:223], v[28:31]
	v_mfma_f32_16x16x32_bf16 v[24:27], v[174:177], v[220:223], v[24:27]
	v_mfma_f32_16x16x32_bf16 v[12:15], v[166:169], v[228:231], v[12:15]
	v_mfma_f32_16x16x32_bf16 v[8:11], v[174:177], v[228:231], v[8:11]
	s_setprio 0
	s_setprio 1
	v_mfma_f32_16x16x32_bf16 v[52:55], v[178:181], v[200:203], v[52:55]
	v_mfma_f32_16x16x32_bf16 v[48:51], v[186:189], v[200:203], v[48:51]
	v_mfma_f32_16x16x32_bf16 v[36:39], v[178:181], v[208:211], v[36:39]
	v_mfma_f32_16x16x32_bf16 v[32:35], v[186:189], v[208:211], v[32:35]
	v_mfma_f32_16x16x32_bf16 v[20:23], v[178:181], v[216:219], v[20:23]
	v_mfma_f32_16x16x32_bf16 v[16:19], v[186:189], v[216:219], v[16:19]
	v_mfma_f32_16x16x32_bf16 v[4:7], v[178:181], v[224:227], v[4:7]
	v_mfma_f32_16x16x32_bf16 v[0:3], v[186:189], v[224:227], v[0:3]
	v_mfma_f32_16x16x32_bf16 v[52:55], v[182:185], v[204:207], v[52:55]
	v_mfma_f32_16x16x32_bf16 v[48:51], v[190:193], v[204:207], v[48:51]
	v_mfma_f32_16x16x32_bf16 v[36:39], v[182:185], v[212:215], v[36:39]
	v_mfma_f32_16x16x32_bf16 v[32:35], v[190:193], v[212:215], v[32:35]
	v_mfma_f32_16x16x32_bf16 v[20:23], v[182:185], v[220:223], v[20:23]
	v_mfma_f32_16x16x32_bf16 v[16:19], v[190:193], v[220:223], v[16:19]
	v_mfma_f32_16x16x32_bf16 v[4:7], v[182:185], v[228:231], v[4:7]
	v_mfma_f32_16x16x32_bf16 v[0:3], v[190:193], v[228:231], v[0:3]
	s_setprio 0
	s_barrier
	s_add_i32 s76, s76, 2
	s_add_u32 s57, s57, 0x100
	s_addc_u32 s59, s59, 0
	s_add_u32 s44, s44, 0x100
	s_addc_u32 s45, s45, 0
	s_cmp_gt_u32 s76, 13
	s_cbranch_scc0 .LBB0_54
	s_and_b64 vcc, exec, s[54:55]
	s_cbranch_vccz .LBB0_57
	s_barrier

; #define PG8_STAGE(bufoff, gbase, voff) do { _Pragma("unroll") for (int _i = 0; _i < 2; ++_i) \
;         __builtin_amdgcn_global_load_lds((const unsigned*)((const char*)(gbase) + (voff)[_i]), (PG8_LAS unsigned*)(lds + (bufoff) + ldsw + _i * 8192), 16, 0, 0); } while (0)
; #define PG8_LDA(dst, b, h) do { _Pragma("unroll") for (int m = 0; m < 4; ++m) _Pragma("unroll") for (int k = 0; k < 2; ++k) dst[m][k] = *(const PG8_LAS bf16x8*)(lds + PG8_SA(b, h) + aoff + m * 2048 + k * 1024); } while (0)
; #define PG8_LDB(dst, b, h) do { _Pragma("unroll") for (int n = 0; n < 2; ++n) _Pragma("unroll") for (int k = 0; k < 2; ++k) dst[n][k] = *(const PG8_LAS bf16x8*)(lds + PG8_SB(b, h) + boff + n * 2048 + k * 1024); } while (0)
; #define PG8_MMA(ai, bj, At, Bt) do { __builtin_amdgcn_s_setprio(1); _Pragma("unroll") for (int m = 0; m < 4; ++m) _Pragma("unroll") for (int n = 0; n < 2; ++n) _Pragma("unroll") for (int k = 0; k < 2; ++k) \
;         acc[ai][bj][m][n] = __builtin_amdgcn_mfma_f32_16x16x32_bf16(Bt[n][k], At[m][k], acc[ai][bj][m][n], 0, 0, 0); __builtin_amdgcn_s_setprio(0); } while (0)
; #define PG8_WAIT_V(n) asm volatile("s_waitcnt vmcnt(" #n ")" ::: "memory")
; #define PG8_WAIT_L(n) asm volatile("s_waitcnt lgkmcnt(" #n ")" ::: "memory")
; template <class Epi, class Sched, bool ALIGN_EPI = false, bool SP2 = false>
; __device__ __forceinline__ void gemm_phase(PG8_LAS unsigned char* lds, const Gemm g, const Sched& S, const Epi& E) {
;     ...
;             const bool last = (t == nt - 2);
;             const char* a1 = cA + (size_t)(t + 1) * kstep;
;             const char* a2 = last ? nA : cA + (size_t)(t + 2) * kstep; const char* b2 = last ? nB : cB + (size_t)(t + 2) * kstep;
;             const char* a3 = a2 + kstep; const char* b3 = b2 + kstep;
;             if (last && has_next) S.a_ready(nxt);
;             if constexpr (SP2) {
;             PG8_LDB(B0, 0, 0); PG8_LDB(B1, 0, 1); PG8_SCHED; PG8_LDA(At, 0, 0); PG8_STAGE(PG8_SA(1, 1), a1 + hstep, voffA);
;             PG8_WAIT_V(8); PG8_WAIT_L(0); PG8_BAR; PG8_MMA(0, 0, At, B0); PG8_MMA(0, 1, At, B1); PG8_BAR; PG8_SCHED;
;             PG8_LDA(At, 0, 1); PG8_STAGE(PG8_SB(0, 0), b2, voffB); PG8_STAGE(PG8_SB(0, 1), b2 + hstep, voffB); PG8_STAGE(PG8_SA(0, 0), a2, voffA);
;             PG8_WAIT_V(8); PG8_WAIT_L(0); PG8_BAR; PG8_MMA(1, 0, At, B0); PG8_MMA(1, 1, At, B1); PG8_BAR; PG8_SCHED;
.Lpeel_g4:
	s_add_u32 s60, s58, 0x100
	s_addc_u32 s61, s59, 0
	s_add_i32 s5, 0, 0x10000
	s_cmp_eq_u32 s39, 40
	s_cselect_b32 s65, s1, s61
	s_cselect_b32 s64, s0, s60
	s_cselect_b32 s63, s57, s27
	s_cselect_b32 s62, s56, s26
	s_add_i32 s8, 0, 0x14000
	v_add_u32_e32 v124, s5, v240
	v_add_u32_e32 v156, s8, v240
	ds_read_b128 v[112:115], v124
	ds_read_b128 v[116:119], v124 offset:1024
	ds_read_b128 v[120:123], v124 offset:2048
	ds_read_b128 v[124:127], v124 offset:3072
	ds_read_b128 v[132:135], v156
	ds_read_b128 v[140:143], v156 offset:1024
	ds_read_b128 v[152:155], v156 offset:2048
	ds_read_b128 v[156:159], v156 offset:3072
	v_lshl_add_u64 v[214:215], s[58:59], 0, v[208:209]
	s_add_i32 m0, s67, 0xc000
	ds_read_b128 v[164:167], v242
	ds_read_b128 v[172:175], v242 offset:1024
	ds_read_b128 v[176:179], v242 offset:2048
	ds_read_b128 v[180:183], v242 offset:3072
	ds_read_b128 v[184:187], v242 offset:4096
	ds_read_b128 v[188:191], v242 offset:5120
	ds_read_b128 v[192:195], v242 offset:6144
	ds_read_b128 v[210:213], v242 offset:7168
	global_load_lds_dwordx4 v[214:215], off
	v_lshl_add_u64 v[214:215], s[58:59], 0, v[206:207]
	s_add_i32 m0, s67, 0xe000
	s_nop 0
	global_load_lds_dwordx4 v[214:215], off
	s_waitcnt vmcnt(32)
	s_barrier
	s_setprio 1
	s_waitcnt lgkmcnt(0)
	v_mfma_f32_16x16x32_bf16 v[168:171], v[112:115], v[164:167], 0
	v_mfma_f32_16x16x32_bf16 v[160:163], v[120:123], v[164:167], 0
	v_mfma_f32_16x16x32_bf16 v[108:111], v[112:115], v[176:179], 0
	v_mfma_f32_16x16x32_bf16 v[104:107], v[120:123], v[176:179], 0
	v_mfma_f32_16x16x32_bf16 v[92:95], v[112:115], v[184:187], 0
	v_mfma_f32_16x16x32_bf16 v[88:91], v[120:123], v[184:187], 0
	v_mfma_f32_16x16x32_bf16 v[76:79], v[112:115], v[192:195], 0
	v_mfma_f32_16x16x32_bf16 v[72:75], v[120:123], v[192:195], 0
	v_mfma_f32_16x16x32_bf16 v[168:171], v[116:119], v[172:175], v[168:171]
	v_mfma_f32_16x16x32_bf16 v[160:163], v[124:127], v[172:175], v[160:163]
	v_mfma_f32_16x16x32_bf16 v[108:111], v[116:119], v[180:183], v[108:111]
	v_mfma_f32_16x16x32_bf16 v[104:107], v[124:127], v[180:183], v[104:107]
	v_mfma_f32_16x16x32_bf16 v[92:95], v[116:119], v[188:191], v[92:95]
	v_mfma_f32_16x16x32_bf16 v[88:91], v[124:127], v[188:191], v[88:91]
	v_mfma_f32_16x16x32_bf16 v[76:79], v[116:119], v[210:213], v[76:79]
	v_mfma_f32_16x16x32_bf16 v[72:75], v[124:127], v[210:213], v[72:75]
	s_setprio 0
	s_setprio 1
	v_mfma_f32_16x16x32_bf16 v[136:139], v[132:135], v[164:167], 0
	v_mfma_f32_16x16x32_bf16 v[128:131], v[152:155], v[164:167], 0
	v_mfma_f32_16x16x32_bf16 v[100:103], v[132:135], v[176:179], 0
	v_mfma_f32_16x16x32_bf16 v[96:99], v[152:155], v[176:179], 0
	v_mfma_f32_16x16x32_bf16 v[84:87], v[132:135], v[184:187], 0
	v_mfma_f32_16x16x32_bf16 v[80:83], v[152:155], v[184:187], 0
	v_mfma_f32_16x16x32_bf16 v[68:71], v[132:135], v[192:195], 0
	v_mfma_f32_16x16x32_bf16 v[64:67], v[152:155], v[192:195], 0
	v_mfma_f32_16x16x32_bf16 v[136:139], v[140:143], v[172:175], v[136:139]
	v_mfma_f32_16x16x32_bf16 v[128:131], v[156:159], v[172:175], v[128:131]
	v_mfma_f32_16x16x32_bf16 v[100:103], v[140:143], v[180:183], v[100:103]
	v_mfma_f32_16x16x32_bf16 v[96:99], v[156:159], v[180:183], v[96:99]
	v_mfma_f32_16x16x32_bf16 v[84:87], v[140:143], v[188:191], v[84:87]
	v_mfma_f32_16x16x32_bf16 v[80:83], v[156:159], v[188:191], v[80:83]
	v_mfma_f32_16x16x32_bf16 v[68:71], v[140:143], v[210:213], v[68:71]
	v_mfma_f32_16x16x32_bf16 v[64:67], v[156:159], v[210:213], v[64:67]
	s_setprio 0
	s_barrier
	s_add_i32 s5, s5, s66
	v_lshl_add_u64 v[214:215], s[62:63], 0, v[202:203]
	s_mov_b32 m0, s5
	ds_read_b128 v[164:167], v242 offset:16384
	ds_read_b128 v[172:175], v242 offset:17408
	ds_read_b128 v[176:179], v242 offset:18432
	ds_read_b128 v[180:183], v242 offset:19456
	ds_read_b128 v[184:187], v242 offset:20480
	ds_read_b128 v[188:191], v242 offset:21504
	ds_read_b128 v[192:195], v242 offset:22528
	ds_read_b128 v[210:213], v242 offset:23552
	global_load_lds_dwordx4 v[214:215], off
	s_add_i32 m0, s5, 0x2000
	s_add_u32 s20, s62, 0xb0000
	v_lshl_add_u64 v[216:217], s[62:63], 0, v[146:147]
	s_addc_u32 s21, s63, 0
	s_add_i32 s5, s8, s66
	global_load_lds_dwordx4 v[216:217], off
	v_lshl_add_u64 v[218:219], s[20:21], 0, v[202:203]
	s_mov_b32 m0, s5
	v_lshl_add_u64 v[220:221], s[64:65], 0, v[200:201]
	global_load_lds_dwordx4 v[218:219], off
	v_lshl_add_u64 v[218:219], s[20:21], 0, v[146:147]
	s_add_i32 m0, s5, 0x2000
	s_nop 0
	global_load_lds_dwordx4 v[218:219], off
	v_lshl_add_u64 v[218:219], s[64:65], 0, v[204:205]
	s_mov_b32 m0, s67
	s_nop 0
	global_load_lds_dwordx4 v[218:219], off
	s_mov_b32 m0, s68
	s_nop 0
	global_load_lds_dwordx4 v[220:221], off
	s_waitcnt vmcnt(32)
	s_barrier
	s_setprio 1
	s_waitcnt lgkmcnt(0)
	v_mfma_f32_16x16x32_bf16 v[60:63], v[112:115], v[164:167], 0
	v_mfma_f32_16x16x32_bf16 v[56:59], v[120:123], v[164:167], 0
	v_mfma_f32_16x16x32_bf16 v[44:47], v[112:115], v[176:179], 0
	v_mfma_f32_16x16x32_bf16 v[40:43], v[120:123], v[176:179], 0
	v_mfma_f32_16x16x32_bf16 v[28:31], v[112:115], v[184:187], 0
	v_mfma_f32_16x16x32_bf16 v[24:27], v[120:123], v[184:187], 0
	v_mfma_f32_16x16x32_bf16 v[12:15], v[112:115], v[192:195], 0
	v_mfma_f32_16x16x32_bf16 v[8:11], v[120:123], v[192:195], 0
	v_mfma_f32_16x16x32_bf16 v[60:63], v[116:119], v[172:175], v[60:63]
	v_mfma_f32_16x16x32_bf16 v[56:59], v[124:127], v[172:175], v[56:59]
	v_mfma_f32_16x16x32_bf16 v[44:47], v[116:119], v[180:183], v[44:47]
	v_mfma_f32_16x16x32_bf16 v[40:43], v[124:127], v[180:183], v[40:43]
	v_mfma_f32_16x16x32_bf16 v[28:31], v[116:119], v[188:191], v[28:31]
	v_mfma_f32_16x16x32_bf16 v[24:27], v[124:127], v[188:191], v[24:27]
	v_mfma_f32_16x16x32_bf16 v[12:15], v[116:119], v[210:213], v[12:15]
	v_mfma_f32_16x16x32_bf16 v[8:11], v[124:127], v[210:213], v[8:11]
	s_setprio 0
	s_setprio 1
	v_mfma_f32_16x16x32_bf16 v[52:55], v[132:135], v[164:167], 0
	v_mfma_f32_16x16x32_bf16 v[48:51], v[152:155], v[164:167], 0
	v_mfma_f32_16x16x32_bf16 v[36:39], v[132:135], v[176:179], 0
	v_mfma_f32_16x16x32_bf16 v[32:35], v[152:155], v[176:179], 0
	v_mfma_f32_16x16x32_bf16 v[20:23], v[132:135], v[184:187], 0
	v_mfma_f32_16x16x32_bf16 v[16:19], v[152:155], v[184:187], 0
	v_mfma_f32_16x16x32_bf16 v[4:7], v[132:135], v[192:195], 0
	v_mfma_f32_16x16x32_bf16 v[0:3], v[152:155], v[192:195], 0
	v_mfma_f32_16x16x32_bf16 v[52:55], v[140:143], v[172:175], v[52:55]
	v_mfma_f32_16x16x32_bf16 v[48:51], v[156:159], v[172:175], v[48:51]
	v_mfma_f32_16x16x32_bf16 v[36:39], v[140:143], v[180:183], v[36:39]
	v_mfma_f32_16x16x32_bf16 v[32:35], v[156:159], v[180:183], v[32:35]
	v_mfma_f32_16x16x32_bf16 v[20:23], v[140:143], v[188:191], v[20:23]
	v_mfma_f32_16x16x32_bf16 v[16:19], v[156:159], v[188:191], v[16:19]
	v_mfma_f32_16x16x32_bf16 v[4:7], v[140:143], v[210:213], v[4:7]
	v_mfma_f32_16x16x32_bf16 v[0:3], v[156:159], v[210:213], v[0:3]
	s_setprio 0
	s_barrier
	s_branch .Lmid_g4

; #define PG8_STAGE(bufoff, gbase, voff) do { _Pragma("unroll") for (int _i = 0; _i < 2; ++_i) \
;         __builtin_amdgcn_global_load_lds((const unsigned*)((const char*)(gbase) + (voff)[_i]), (PG8_LAS unsigned*)(lds + (bufoff) + ldsw + _i * 8192), 16, 0, 0); } while (0)
; #define PG8_LDA(dst, b, h) do { _Pragma("unroll") for (int m = 0; m < 4; ++m) _Pragma("unroll") for (int k = 0; k < 2; ++k) dst[m][k] = *(const PG8_LAS bf16x8*)(lds + PG8_SA(b, h) + aoff + m * 2048 + k * 1024); } while (0)
; #define PG8_LDB(dst, b, h) do { _Pragma("unroll") for (int n = 0; n < 2; ++n) _Pragma("unroll") for (int k = 0; k < 2; ++k) dst[n][k] = *(const PG8_LAS bf16x8*)(lds + PG8_SB(b, h) + boff + n * 2048 + k * 1024); } while (0)
; #define PG8_MMA(ai, bj, At, Bt) do { __builtin_amdgcn_s_setprio(1); _Pragma("unroll") for (int m = 0; m < 4; ++m) _Pragma("unroll") for (int n = 0; n < 2; ++n) _Pragma("unroll") for (int k = 0; k < 2; ++k) \
;         acc[ai][bj][m][n] = __builtin_amdgcn_mfma_f32_16x16x32_bf16(Bt[n][k], At[m][k], acc[ai][bj][m][n], 0, 0, 0); __builtin_amdgcn_s_setprio(0); } while (0)
; #define PG8_WAIT_V(n) asm volatile("s_waitcnt vmcnt(" #n ")" ::: "memory")
; #define PG8_WAIT_L(n) asm volatile("s_waitcnt lgkmcnt(" #n ")" ::: "memory")
; #define PG8_BAR __builtin_amdgcn_s_barrier()
; #define PG8_SCHED __builtin_amdgcn_sched_barrier(0)
; template <class Epi, class Sched, bool ALIGN_EPI = false, bool SP2 = false>
; __device__ __forceinline__ void gemm_phase(PG8_LAS unsigned char* lds, const Gemm g, const Sched& S, const Epi& E) {
;     ...
;             PG8_LDB(B0, 0, 0); PG8_LDB(B1, 0, 1); PG8_SCHED; PG8_LDA(At, 0, 0); PG8_STAGE(PG8_SA(1, 1), a1 + hstep, voffA);
;             PG8_WAIT_V(8); PG8_WAIT_L(0); PG8_BAR; PG8_MMA(0, 0, At, B0); PG8_MMA(0, 1, At, B1); PG8_BAR; PG8_SCHED;
;             PG8_LDA(At, 0, 1); PG8_STAGE(PG8_SB(0, 0), b2, voffB); PG8_STAGE(PG8_SB(0, 1), b2 + hstep, voffB); PG8_STAGE(PG8_SA(0, 0), a2, voffA);
;             PG8_WAIT_V(8); PG8_WAIT_L(0); PG8_BAR; PG8_MMA(1, 0, At, B0); PG8_MMA(1, 1, At, B1); PG8_BAR; PG8_SCHED;
.LBB0_112:
	s_add_u32 s60, s58, 0x100
	s_addc_u32 s61, s59, 0
	s_add_i32 s5, 0, 0x10000
	s_cmp_eq_u32 s39, 40
	s_cselect_b32 s65, s1, s61
	s_cselect_b32 s64, s0, s60
	s_cselect_b32 s63, s57, s27
	s_cselect_b32 s62, s56, s26
	s_add_i32 s8, 0, 0x14000
	v_add_u32_e32 v124, s5, v240
	v_add_u32_e32 v156, s8, v240
	ds_read_b128 v[112:115], v124
	ds_read_b128 v[116:119], v124 offset:1024
	ds_read_b128 v[120:123], v124 offset:2048
	ds_read_b128 v[124:127], v124 offset:3072
	ds_read_b128 v[132:135], v156
	ds_read_b128 v[140:143], v156 offset:1024
	ds_read_b128 v[152:155], v156 offset:2048
	ds_read_b128 v[156:159], v156 offset:3072
	v_lshl_add_u64 v[214:215], s[58:59], 0, v[208:209]
	s_add_i32 m0, s67, 0xc000
	ds_read_b128 v[164:167], v242
	ds_read_b128 v[172:175], v242 offset:1024
	ds_read_b128 v[176:179], v242 offset:2048
	ds_read_b128 v[180:183], v242 offset:3072
	ds_read_b128 v[184:187], v242 offset:4096
	ds_read_b128 v[188:191], v242 offset:5120
	ds_read_b128 v[192:195], v242 offset:6144
	ds_read_b128 v[210:213], v242 offset:7168
	global_load_lds_dwordx4 v[214:215], off
	v_lshl_add_u64 v[214:215], s[58:59], 0, v[206:207]
	s_add_i32 m0, s67, 0xe000
	s_nop 0
	global_load_lds_dwordx4 v[214:215], off
	s_waitcnt vmcnt(8)
	s_barrier
	s_setprio 1
	s_waitcnt lgkmcnt(0)
	v_mfma_f32_16x16x32_bf16 v[168:171], v[112:115], v[164:167], v[168:171]
	v_mfma_f32_16x16x32_bf16 v[160:163], v[120:123], v[164:167], v[160:163]
	v_mfma_f32_16x16x32_bf16 v[108:111], v[112:115], v[176:179], v[108:111]
	v_mfma_f32_16x16x32_bf16 v[104:107], v[120:123], v[176:179], v[104:107]
	v_mfma_f32_16x16x32_bf16 v[92:95], v[112:115], v[184:187], v[92:95]
	v_mfma_f32_16x16x32_bf16 v[88:91], v[120:123], v[184:187], v[88:91]
	v_mfma_f32_16x16x32_bf16 v[76:79], v[112:115], v[192:195], v[76:79]
	v_mfma_f32_16x16x32_bf16 v[72:75], v[120:123], v[192:195], v[72:75]
	v_mfma_f32_16x16x32_bf16 v[168:171], v[116:119], v[172:175], v[168:171]
	v_mfma_f32_16x16x32_bf16 v[160:163], v[124:127], v[172:175], v[160:163]
	v_mfma_f32_16x16x32_bf16 v[108:111], v[116:119], v[180:183], v[108:111]
	v_mfma_f32_16x16x32_bf16 v[104:107], v[124:127], v[180:183], v[104:107]
	v_mfma_f32_16x16x32_bf16 v[92:95], v[116:119], v[188:191], v[92:95]
	v_mfma_f32_16x16x32_bf16 v[88:91], v[124:127], v[188:191], v[88:91]
	v_mfma_f32_16x16x32_bf16 v[76:79], v[116:119], v[210:213], v[76:79]
	v_mfma_f32_16x16x32_bf16 v[72:75], v[124:127], v[210:213], v[72:75]
	s_setprio 0
	s_setprio 1
	v_mfma_f32_16x16x32_bf16 v[136:139], v[132:135], v[164:167], v[136:139]
	v_mfma_f32_16x16x32_bf16 v[128:131], v[152:155], v[164:167], v[128:131]
	v_mfma_f32_16x16x32_bf16 v[100:103], v[132:135], v[176:179], v[100:103]
	v_mfma_f32_16x16x32_bf16 v[96:99], v[152:155], v[176:179], v[96:99]
	v_mfma_f32_16x16x32_bf16 v[84:87], v[132:135], v[184:187], v[84:87]
	v_mfma_f32_16x16x32_bf16 v[80:83], v[152:155], v[184:187], v[80:83]
	v_mfma_f32_16x16x32_bf16 v[68:71], v[132:135], v[192:195], v[68:71]
	v_mfma_f32_16x16x32_bf16 v[64:67], v[152:155], v[192:195], v[64:67]
	v_mfma_f32_16x16x32_bf16 v[136:139], v[140:143], v[172:175], v[136:139]
	v_mfma_f32_16x16x32_bf16 v[128:131], v[156:159], v[172:175], v[128:131]
	v_mfma_f32_16x16x32_bf16 v[100:103], v[140:143], v[180:183], v[100:103]
	v_mfma_f32_16x16x32_bf16 v[96:99], v[156:159], v[180:183], v[96:99]
	v_mfma_f32_16x16x32_bf16 v[84:87], v[140:143], v[188:191], v[84:87]
	v_mfma_f32_16x16x32_bf16 v[80:83], v[156:159], v[188:191], v[80:83]
	v_mfma_f32_16x16x32_bf16 v[68:71], v[140:143], v[210:213], v[68:71]
	v_mfma_f32_16x16x32_bf16 v[64:67], v[156:159], v[210:213], v[64:67]
	s_setprio 0
	s_barrier
	s_add_i32 s5, s5, s66
	v_lshl_add_u64 v[214:215], s[62:63], 0, v[202:203]
	s_mov_b32 m0, s5
	ds_read_b128 v[164:167], v242 offset:16384
	ds_read_b128 v[172:175], v242 offset:17408
	ds_read_b128 v[176:179], v242 offset:18432
	ds_read_b128 v[180:183], v242 offset:19456
	ds_read_b128 v[184:187], v242 offset:20480
	ds_read_b128 v[188:191], v242 offset:21504
	ds_read_b128 v[192:195], v242 offset:22528
	ds_read_b128 v[210:213], v242 offset:23552
	global_load_lds_dwordx4 v[214:215], off
	s_add_i32 m0, s5, 0x2000
	s_add_u32 s20, s62, 0xb0000
	v_lshl_add_u64 v[216:217], s[62:63], 0, v[146:147]
	s_addc_u32 s21, s63, 0
	s_add_i32 s5, s8, s66
	global_load_lds_dwordx4 v[216:217], off
	v_lshl_add_u64 v[218:219], s[20:21], 0, v[202:203]
	s_mov_b32 m0, s5
	v_lshl_add_u64 v[220:221], s[64:65], 0, v[200:201]
	global_load_lds_dwordx4 v[218:219], off
	v_lshl_add_u64 v[218:219], s[20:21], 0, v[146:147]
	s_add_i32 m0, s5, 0x2000
	s_nop 0
	global_load_lds_dwordx4 v[218:219], off
	v_lshl_add_u64 v[218:219], s[64:65], 0, v[204:205]
	s_mov_b32 m0, s67
	s_nop 0
	global_load_lds_dwordx4 v[218:219], off
	s_mov_b32 m0, s68
	s_nop 0
	global_load_lds_dwordx4 v[220:221], off
	s_waitcnt vmcnt(8)
	s_barrier
; #define PG8_STAGE(bufoff, gbase, voff) do { _Pragma("unroll") for (int _i = 0; _i < 2; ++_i) \
;         __builtin_amdgcn_global_load_lds((const unsigned*)((const char*)(gbase) + (voff)[_i]), (PG8_LAS unsigned*)(lds + (bufoff) + ldsw + _i * 8192), 16, 0, 0); } while (0)
; #define PG8_LDA(dst, b, h) do { _Pragma("unroll") for (int m = 0; m < 4; ++m) _Pragma("unroll") for (int k = 0; k < 2; ++k) dst[m][k] = *(const PG8_LAS bf16x8*)(lds + PG8_SA(b, h) + aoff + m * 2048 + k * 1024); } while (0)
; #define PG8_LDB(dst, b, h) do { _Pragma("unroll") for (int n = 0; n < 2; ++n) _Pragma("unroll") for (int k = 0; k < 2; ++k) dst[n][k] = *(const PG8_LAS bf16x8*)(lds + PG8_SB(b, h) + boff + n * 2048 + k * 1024); } while (0)
; #define PG8_MMA(ai, bj, At, Bt) do { __builtin_amdgcn_s_setprio(1); _Pragma("unroll") for (int m = 0; m < 4; ++m) _Pragma("unroll") for (int n = 0; n < 2; ++n) _Pragma("unroll") for (int k = 0; k < 2; ++k) \
;         acc[ai][bj][m][n] = __builtin_amdgcn_mfma_f32_16x16x32_bf16(Bt[n][k], At[m][k], acc[ai][bj][m][n], 0, 0, 0); __builtin_amdgcn_s_setprio(0); } while (0)
; #define PG8_WAIT_V(n) asm volatile("s_waitcnt vmcnt(" #n ")" ::: "memory")
; #define PG8_WAIT_L(n) asm volatile("s_waitcnt lgkmcnt(" #n ")" ::: "memory")
; #define PG8_BAR __builtin_amdgcn_s_barrier()
; #define PG8_SCHED __builtin_amdgcn_sched_barrier(0)
; template <class Epi, class Sched, bool ALIGN_EPI = false, bool SP2 = false>
; __device__ __forceinline__ void gemm_phase(PG8_LAS unsigned char* lds, const Gemm g, const Sched& S, const Epi& E) {
;     ...
;             PG8_WAIT_V(8); PG8_WAIT_L(0); PG8_BAR; PG8_MMA(1, 0, At, B0); PG8_MMA(1, 1, At, B1); PG8_BAR; PG8_SCHED;
;             PG8_LDB(B0, 1, 0); PG8_LDB(B1, 1, 1); PG8_SCHED; PG8_LDA(At, 1, 0); PG8_STAGE(PG8_SA(0, 1), a2 + hstep, voffA);
;             PG8_WAIT_V(8); PG8_WAIT_L(0); PG8_BAR; PG8_MMA(0, 0, At, B0); PG8_MMA(0, 1, At, B1); PG8_BAR; PG8_SCHED;
	s_setprio 1
	s_waitcnt lgkmcnt(0)
	v_mfma_f32_16x16x32_bf16 v[60:63], v[112:115], v[164:167], v[60:63]
	v_mfma_f32_16x16x32_bf16 v[56:59], v[120:123], v[164:167], v[56:59]
	v_mfma_f32_16x16x32_bf16 v[44:47], v[112:115], v[176:179], v[44:47]
	v_mfma_f32_16x16x32_bf16 v[40:43], v[120:123], v[176:179], v[40:43]
	v_mfma_f32_16x16x32_bf16 v[28:31], v[112:115], v[184:187], v[28:31]
	v_mfma_f32_16x16x32_bf16 v[24:27], v[120:123], v[184:187], v[24:27]
	v_mfma_f32_16x16x32_bf16 v[12:15], v[112:115], v[192:195], v[12:15]
	v_mfma_f32_16x16x32_bf16 v[8:11], v[120:123], v[192:195], v[8:11]
	v_mfma_f32_16x16x32_bf16 v[60:63], v[116:119], v[172:175], v[60:63]
	v_mfma_f32_16x16x32_bf16 v[56:59], v[124:127], v[172:175], v[56:59]
	v_mfma_f32_16x16x32_bf16 v[44:47], v[116:119], v[180:183], v[44:47]
	v_mfma_f32_16x16x32_bf16 v[40:43], v[124:127], v[180:183], v[40:43]
	v_mfma_f32_16x16x32_bf16 v[28:31], v[116:119], v[188:191], v[28:31]
	v_mfma_f32_16x16x32_bf16 v[24:27], v[124:127], v[188:191], v[24:27]
	v_mfma_f32_16x16x32_bf16 v[12:15], v[116:119], v[210:213], v[12:15]
	v_mfma_f32_16x16x32_bf16 v[8:11], v[124:127], v[210:213], v[8:11]
	s_setprio 0
	s_setprio 1
	v_mfma_f32_16x16x32_bf16 v[52:55], v[132:135], v[164:167], v[52:55]
	v_mfma_f32_16x16x32_bf16 v[48:51], v[152:155], v[164:167], v[48:51]
	v_mfma_f32_16x16x32_bf16 v[36:39], v[132:135], v[176:179], v[36:39]
	v_mfma_f32_16x16x32_bf16 v[32:35], v[152:155], v[176:179], v[32:35]
	v_mfma_f32_16x16x32_bf16 v[20:23], v[132:135], v[184:187], v[20:23]
	v_mfma_f32_16x16x32_bf16 v[16:19], v[152:155], v[184:187], v[16:19]
	v_mfma_f32_16x16x32_bf16 v[4:7], v[132:135], v[192:195], v[4:7]
	v_mfma_f32_16x16x32_bf16 v[0:3], v[152:155], v[192:195], v[0:3]
	v_mfma_f32_16x16x32_bf16 v[52:55], v[140:143], v[172:175], v[52:55]
	v_mfma_f32_16x16x32_bf16 v[48:51], v[156:159], v[172:175], v[48:51]
	v_mfma_f32_16x16x32_bf16 v[36:39], v[140:143], v[180:183], v[36:39]
	v_mfma_f32_16x16x32_bf16 v[32:35], v[156:159], v[180:183], v[32:35]
	v_mfma_f32_16x16x32_bf16 v[20:23], v[140:143], v[188:191], v[20:23]
	v_mfma_f32_16x16x32_bf16 v[16:19], v[156:159], v[188:191], v[16:19]
	v_mfma_f32_16x16x32_bf16 v[4:7], v[140:143], v[210:213], v[4:7]
	v_mfma_f32_16x16x32_bf16 v[0:3], v[156:159], v[210:213], v[0:3]
	s_setprio 0
	s_barrier
.Lmid_g4:
	s_add_i32 s5, 0, 0x18000
	s_add_i32 s8, 0, 0x1c000
	v_add_u32_e32 v124, s5, v240
	v_add_u32_e32 v156, s8, v240
	ds_read_b128 v[112:115], v124
	ds_read_b128 v[116:119], v124 offset:1024
	ds_read_b128 v[120:123], v124 offset:2048
	ds_read_b128 v[124:127], v124 offset:3072
	ds_read_b128 v[132:135], v156
	ds_read_b128 v[140:143], v156 offset:1024
	ds_read_b128 v[152:155], v156 offset:2048
	ds_read_b128 v[156:159], v156 offset:3072
	s_add_u32 s20, s64, 0xb0000
	s_addc_u32 s21, s65, 0
	s_mov_b32 m0, s69
	v_lshl_add_u64 v[222:223], s[20:21], 0, v[204:205]
	ds_read_b128 v[164:167], v242 offset:32768
	ds_read_b128 v[172:175], v242 offset:33792
	ds_read_b128 v[176:179], v242 offset:34816
	ds_read_b128 v[180:183], v242 offset:35840
	ds_read_b128 v[184:187], v242 offset:36864
	ds_read_b128 v[188:191], v242 offset:37888
	ds_read_b128 v[192:195], v242 offset:38912
	ds_read_b128 v[210:213], v242 offset:39936
	global_load_lds_dwordx4 v[222:223], off
	v_lshl_add_u64 v[222:223], s[20:21], 0, v[200:201]
	s_mov_b32 m0, s70
	s_nop 0
	global_load_lds_dwordx4 v[222:223], off
	s_waitcnt vmcnt(8)
	s_barrier
	s_setprio 1
	s_waitcnt lgkmcnt(0)
	v_mfma_f32_16x16x32_bf16 v[168:171], v[112:115], v[164:167], v[168:171]
	v_mfma_f32_16x16x32_bf16 v[160:163], v[120:123], v[164:167], v[160:163]
	v_mfma_f32_16x16x32_bf16 v[108:111], v[112:115], v[176:179], v[108:111]
	v_mfma_f32_16x16x32_bf16 v[104:107], v[120:123], v[176:179], v[104:107]
	v_mfma_f32_16x16x32_bf16 v[92:95], v[112:115], v[184:187], v[92:95]
	v_mfma_f32_16x16x32_bf16 v[88:91], v[120:123], v[184:187], v[88:91]
	v_mfma_f32_16x16x32_bf16 v[76:79], v[112:115], v[192:195], v[76:79]
	v_mfma_f32_16x16x32_bf16 v[72:75], v[120:123], v[192:195], v[72:75]
	v_mfma_f32_16x16x32_bf16 v[168:171], v[116:119], v[172:175], v[168:171]
	v_mfma_f32_16x16x32_bf16 v[160:163], v[124:127], v[172:175], v[160:163]
	v_mfma_f32_16x16x32_bf16 v[108:111], v[116:119], v[180:183], v[108:111]
	v_mfma_f32_16x16x32_bf16 v[104:107], v[124:127], v[180:183], v[104:107]
	v_mfma_f32_16x16x32_bf16 v[92:95], v[116:119], v[188:191], v[92:95]
	v_mfma_f32_16x16x32_bf16 v[88:91], v[124:127], v[188:191], v[88:91]
	v_mfma_f32_16x16x32_bf16 v[76:79], v[116:119], v[210:213], v[76:79]
	v_mfma_f32_16x16x32_bf16 v[72:75], v[124:127], v[210:213], v[72:75]
	s_setprio 0
	s_setprio 1
	v_mfma_f32_16x16x32_bf16 v[136:139], v[132:135], v[164:167], v[136:139]
	v_mfma_f32_16x16x32_bf16 v[128:131], v[152:155], v[164:167], v[128:131]
	v_mfma_f32_16x16x32_bf16 v[100:103], v[132:135], v[176:179], v[100:103]
	v_mfma_f32_16x16x32_bf16 v[96:99], v[152:155], v[176:179], v[96:99]
	v_mfma_f32_16x16x32_bf16 v[84:87], v[132:135], v[184:187], v[84:87]
	v_mfma_f32_16x16x32_bf16 v[80:83], v[152:155], v[184:187], v[80:83]
	v_mfma_f32_16x16x32_bf16 v[68:71], v[132:135], v[192:195], v[68:71]
	v_mfma_f32_16x16x32_bf16 v[64:67], v[152:155], v[192:195], v[64:67]
	v_mfma_f32_16x16x32_bf16 v[136:139], v[140:143], v[172:175], v[136:139]
	v_mfma_f32_16x16x32_bf16 v[128:131], v[156:159], v[172:175], v[128:131]
	v_mfma_f32_16x16x32_bf16 v[100:103], v[140:143], v[180:183], v[100:103]
	v_mfma_f32_16x16x32_bf16 v[96:99], v[156:159], v[180:183], v[96:99]
	v_mfma_f32_16x16x32_bf16 v[84:87], v[140:143], v[188:191], v[84:87]
	v_mfma_f32_16x16x32_bf16 v[80:83], v[156:159], v[188:191], v[80:83]
	v_mfma_f32_16x16x32_bf16 v[68:71], v[140:143], v[210:213], v[68:71]
	v_mfma_f32_16x16x32_bf16 v[64:67], v[156:159], v[210:213], v[64:67]
	s_setprio 0
	s_barrier
; #define PG8_STAGE(bufoff, gbase, voff) do { _Pragma("unroll") for (int _i = 0; _i < 2; ++_i) \
;         __builtin_amdgcn_global_load_lds((const unsigned*)((const char*)(gbase) + (voff)[_i]), (PG8_LAS unsigned*)(lds + (bufoff) + ldsw + _i * 8192), 16, 0, 0); } while (0)
; #define PG8_LDA(dst, b, h) do { _Pragma("unroll") for (int m = 0; m < 4; ++m) _Pragma("unroll") for (int k = 0; k < 2; ++k) dst[m][k] = *(const PG8_LAS bf16x8*)(lds + PG8_SA(b, h) + aoff + m * 2048 + k * 1024); } while (0)
; #define PG8_MMA(ai, bj, At, Bt) do { __builtin_amdgcn_s_setprio(1); _Pragma("unroll") for (int m = 0; m < 4; ++m) _Pragma("unroll") for (int n = 0; n < 2; ++n) _Pragma("unroll") for (int k = 0; k < 2; ++k) \
;         acc[ai][bj][m][n] = __builtin_amdgcn_mfma_f32_16x16x32_bf16(Bt[n][k], At[m][k], acc[ai][bj][m][n], 0, 0, 0); __builtin_amdgcn_s_setprio(0); } while (0)
; #define PG8_WAIT_V(n) asm volatile("s_waitcnt vmcnt(" #n ")" ::: "memory")
; #define PG8_WAIT_L(n) asm volatile("s_waitcnt lgkmcnt(" #n ")" ::: "memory")
; #define PG8_BAR __builtin_amdgcn_s_barrier()
; #define PG8_SCHED __builtin_amdgcn_sched_barrier(0)
; template <class Epi, class Sched, bool ALIGN_EPI = false, bool SP2 = false>
; __device__ __forceinline__ void gemm_phase(PG8_LAS unsigned char* lds, const Gemm g, const Sched& S, const Epi& E) {
;     ...
;             PG8_LDA(At, 1, 1); PG8_STAGE(PG8_SB(1, 0), b3, voffB); PG8_STAGE(PG8_SB(1, 1), b3 + hstep, voffB); PG8_STAGE(PG8_SA(1, 0), a3, voffA);
;             PG8_WAIT_V(8); PG8_WAIT_L(0); PG8_BAR; PG8_MMA(1, 0, At, B0); PG8_MMA(1, 1, At, B1); PG8_BAR; PG8_SCHED;
;     ...
;         if constexpr (ALIGN_EPI) { if (wr == 0) PG8_BAR; }
	s_add_i32 s5, s5, s66
	v_lshl_add_u64 v[214:215], v[214:215], 0, s[22:23]
	s_mov_b32 m0, s5
	ds_read_b128 v[164:167], v242 offset:49152
	ds_read_b128 v[172:175], v242 offset:50176
	ds_read_b128 v[176:179], v242 offset:51200
	ds_read_b128 v[180:183], v242 offset:52224
	ds_read_b128 v[184:187], v242 offset:53248
	ds_read_b128 v[188:191], v242 offset:54272
	ds_read_b128 v[192:195], v242 offset:55296
	ds_read_b128 v[210:213], v242 offset:56320
	global_load_lds_dwordx4 v[214:215], off
	s_add_i32 m0, s5, 0x2000
	s_add_u32 s20, s62, 0xb0080
	v_lshl_add_u64 v[214:215], v[216:217], 0, s[22:23]
	s_addc_u32 s21, s63, 0
	s_add_i32 s5, s8, s66
	global_load_lds_dwordx4 v[214:215], off
	v_lshl_add_u64 v[214:215], s[20:21], 0, v[202:203]
	s_mov_b32 m0, s5
	s_nop 0
	global_load_lds_dwordx4 v[214:215], off
	v_lshl_add_u64 v[214:215], s[20:21], 0, v[146:147]
	s_add_i32 m0, s5, 0x2000
	s_nop 0
	global_load_lds_dwordx4 v[214:215], off
	v_lshl_add_u64 v[214:215], v[218:219], 0, s[22:23]
	s_mov_b32 m0, s71
	s_nop 0
	global_load_lds_dwordx4 v[214:215], off
	v_lshl_add_u64 v[214:215], v[220:221], 0, s[22:23]
	s_mov_b32 m0, s72
	s_nop 0
	global_load_lds_dwordx4 v[214:215], off
	s_waitcnt vmcnt(8)
	s_barrier
	s_setprio 1
	s_waitcnt lgkmcnt(0)
	v_mfma_f32_16x16x32_bf16 v[60:63], v[112:115], v[164:167], v[60:63]
	v_mfma_f32_16x16x32_bf16 v[56:59], v[120:123], v[164:167], v[56:59]
	v_mfma_f32_16x16x32_bf16 v[44:47], v[112:115], v[176:179], v[44:47]
	v_mfma_f32_16x16x32_bf16 v[40:43], v[120:123], v[176:179], v[40:43]
	v_mfma_f32_16x16x32_bf16 v[28:31], v[112:115], v[184:187], v[28:31]
	v_mfma_f32_16x16x32_bf16 v[24:27], v[120:123], v[184:187], v[24:27]
	v_mfma_f32_16x16x32_bf16 v[12:15], v[112:115], v[192:195], v[12:15]
	v_mfma_f32_16x16x32_bf16 v[8:11], v[120:123], v[192:195], v[8:11]
	v_mfma_f32_16x16x32_bf16 v[60:63], v[116:119], v[172:175], v[60:63]
	v_mfma_f32_16x16x32_bf16 v[56:59], v[124:127], v[172:175], v[56:59]
	v_mfma_f32_16x16x32_bf16 v[44:47], v[116:119], v[180:183], v[44:47]
	v_mfma_f32_16x16x32_bf16 v[40:43], v[124:127], v[180:183], v[40:43]
	v_mfma_f32_16x16x32_bf16 v[28:31], v[116:119], v[188:191], v[28:31]
	v_mfma_f32_16x16x32_bf16 v[24:27], v[124:127], v[188:191], v[24:27]
	v_mfma_f32_16x16x32_bf16 v[12:15], v[116:119], v[210:213], v[12:15]
	v_mfma_f32_16x16x32_bf16 v[8:11], v[124:127], v[210:213], v[8:11]
	s_setprio 0
	s_setprio 1
	v_mfma_f32_16x16x32_bf16 v[52:55], v[132:135], v[164:167], v[52:55]
	v_mfma_f32_16x16x32_bf16 v[48:51], v[152:155], v[164:167], v[48:51]
	v_mfma_f32_16x16x32_bf16 v[36:39], v[132:135], v[176:179], v[36:39]
	v_mfma_f32_16x16x32_bf16 v[32:35], v[152:155], v[176:179], v[32:35]
	v_mfma_f32_16x16x32_bf16 v[20:23], v[132:135], v[184:187], v[20:23]
	v_mfma_f32_16x16x32_bf16 v[16:19], v[152:155], v[184:187], v[16:19]
	v_mfma_f32_16x16x32_bf16 v[4:7], v[132:135], v[192:195], v[4:7]
	v_mfma_f32_16x16x32_bf16 v[0:3], v[152:155], v[192:195], v[0:3]
	v_mfma_f32_16x16x32_bf16 v[52:55], v[140:143], v[172:175], v[52:55]
	v_mfma_f32_16x16x32_bf16 v[48:51], v[156:159], v[172:175], v[48:51]
	v_mfma_f32_16x16x32_bf16 v[36:39], v[140:143], v[180:183], v[36:39]
	v_mfma_f32_16x16x32_bf16 v[32:35], v[156:159], v[180:183], v[32:35]
	v_mfma_f32_16x16x32_bf16 v[20:23], v[140:143], v[188:191], v[20:23]
	v_mfma_f32_16x16x32_bf16 v[16:19], v[156:159], v[188:191], v[16:19]
	v_mfma_f32_16x16x32_bf16 v[4:7], v[140:143], v[210:213], v[4:7]
	v_mfma_f32_16x16x32_bf16 v[0:3], v[156:159], v[210:213], v[0:3]
	s_setprio 0
	s_barrier
	s_add_i32 s39, s39, 2
	s_add_u32 s26, s26, 0x100
	s_addc_u32 s27, s27, 0
	s_cmp_gt_u32 s39, 41
	s_mov_b64 s[58:59], s[60:61]
	s_cbranch_scc0 .LBB0_112
	s_and_b64 vcc, exec, s[54:55]
	s_cbranch_vccz .LBB0_115
	s_barrier

; #define PG8_STAGE(bufoff, gbase, voff) do { _Pragma("unroll") for (int _i = 0; _i < 2; ++_i) \
;         __builtin_amdgcn_global_load_lds((const unsigned*)((const char*)(gbase) + (voff)[_i]), (PG8_LAS unsigned*)(lds + (bufoff) + ldsw + _i * 8192), 16, 0, 0); } while (0)
; #define PG8_LDA(dst, b, h) do { _Pragma("unroll") for (int m = 0; m < 4; ++m) _Pragma("unroll") for (int k = 0; k < 2; ++k) dst[m][k] = *(const PG8_LAS bf16x8*)(lds + PG8_SA(b, h) + aoff + m * 2048 + k * 1024); } while (0)
; #define PG8_LDB(dst, b, h) do { _Pragma("unroll") for (int n = 0; n < 2; ++n) _Pragma("unroll") for (int k = 0; k < 2; ++k) dst[n][k] = *(const PG8_LAS bf16x8*)(lds + PG8_SB(b, h) + boff + n * 2048 + k * 1024); } while (0)
; #define PG8_MMA(ai, bj, At, Bt) do { __builtin_amdgcn_s_setprio(1); _Pragma("unroll") for (int m = 0; m < 4; ++m) _Pragma("unroll") for (int n = 0; n < 2; ++n) _Pragma("unroll") for (int k = 0; k < 2; ++k) \
;         acc[ai][bj][m][n] = __builtin_amdgcn_mfma_f32_16x16x32_bf16(Bt[n][k], At[m][k], acc[ai][bj][m][n], 0, 0, 0); __builtin_amdgcn_s_setprio(0); } while (0)
; #define PG8_WAIT_V(n) asm volatile("s_waitcnt vmcnt(" #n ")" ::: "memory")
; #define PG8_WAIT_L(n) asm volatile("s_waitcnt lgkmcnt(" #n ")" ::: "memory")
; template <class Epi, class Sched, bool ALIGN_EPI = false, bool SP2 = false>
; __device__ __forceinline__ void gemm_phase(PG8_LAS unsigned char* lds, const Gemm g, const Sched& S, const Epi& E) {
;     ...
;             const bool last = (t == nt - 2);
;             const char* a1 = cA + (size_t)(t + 1) * kstep;
;             const char* a2 = last ? nA : cA + (size_t)(t + 2) * kstep; const char* b2 = last ? nB : cB + (size_t)(t + 2) * kstep;
;             const char* a3 = a2 + kstep; const char* b3 = b2 + kstep;
;             if (last && has_next) S.a_ready(nxt);
;             if constexpr (SP2) {
;             PG8_LDB(B0, 0, 0); PG8_LDB(B1, 0, 1); PG8_SCHED; PG8_LDA(At, 0, 0); PG8_STAGE(PG8_SA(1, 1), a1 + hstep, voffA);
;             PG8_WAIT_V(8); PG8_WAIT_L(0); PG8_BAR; PG8_MMA(0, 0, At, B0); PG8_MMA(0, 1, At, B1); PG8_BAR; PG8_SCHED;
;             PG8_LDA(At, 0, 1); PG8_STAGE(PG8_SB(0, 0), b2, voffB); PG8_STAGE(PG8_SB(0, 1), b2 + hstep, voffB); PG8_STAGE(PG8_SA(0, 0), a2, voffA);
;             PG8_WAIT_V(8); PG8_WAIT_L(0); PG8_BAR; PG8_MMA(1, 0, At, B0); PG8_MMA(1, 1, At, B1); PG8_BAR; PG8_SCHED;
.Lpeel_g3:
	s_add_u32 s5, s58, 0xfffc0080
	s_addc_u32 s8, s59, -1
	s_add_i32 s10, 0, 0x10000
	s_cmp_eq_u32 s72, 12
	s_cselect_b32 s63, s26, s8
	s_cselect_b32 s62, s27, s5
	v_add_u32_e32 v143, s10, v157
	s_cselect_b32 s61, s36, s53
	s_cselect_b32 s60, s39, s51
	s_add_i32 s5, 0, 0x14000
	ds_read_b128 v[162:165], v143
	ds_read_b128 v[166:169], v143 offset:1024
	ds_read_b128 v[170:173], v143 offset:2048
	ds_read_b128 v[174:177], v143 offset:3072
	v_add_u32_e32 v143, s5, v157
	ds_read_b128 v[178:181], v143
	ds_read_b128 v[182:185], v143 offset:1024
	ds_read_b128 v[186:189], v143 offset:2048
	ds_read_b128 v[190:193], v143 offset:3072
	v_lshl_add_u64 v[194:195], s[58:59], 0, v[140:141]
	s_add_i32 m0, s65, 0xc000
	ds_read_b128 v[200:203], v161
	ds_read_b128 v[204:207], v161 offset:1024
	ds_read_b128 v[208:211], v161 offset:2048
	ds_read_b128 v[212:215], v161 offset:3072
	ds_read_b128 v[216:219], v161 offset:4096
	ds_read_b128 v[220:223], v161 offset:5120
	ds_read_b128 v[224:227], v161 offset:6144
	ds_read_b128 v[228:231], v161 offset:7168
	global_load_lds_dwordx4 v[194:195], off
	v_lshl_add_u64 v[194:195], s[58:59], 0, v[138:139]
	s_add_i32 m0, s65, 0xe000
	s_nop 0
	global_load_lds_dwordx4 v[194:195], off
	s_waitcnt vmcnt(18)
	s_barrier
	s_setprio 1
	s_waitcnt lgkmcnt(0)
	v_mfma_f32_16x16x32_bf16 v[124:127], v[162:165], v[200:203], 0
	v_mfma_f32_16x16x32_bf16 v[120:123], v[170:173], v[200:203], 0
	v_mfma_f32_16x16x32_bf16 v[108:111], v[162:165], v[208:211], 0
	v_mfma_f32_16x16x32_bf16 v[104:107], v[170:173], v[208:211], 0
	v_mfma_f32_16x16x32_bf16 v[92:95], v[162:165], v[216:219], 0
	v_mfma_f32_16x16x32_bf16 v[88:91], v[170:173], v[216:219], 0
	v_mfma_f32_16x16x32_bf16 v[76:79], v[162:165], v[224:227], 0
	v_mfma_f32_16x16x32_bf16 v[72:75], v[170:173], v[224:227], 0
	v_mfma_f32_16x16x32_bf16 v[124:127], v[166:169], v[204:207], v[124:127]
	v_mfma_f32_16x16x32_bf16 v[120:123], v[174:177], v[204:207], v[120:123]
	v_mfma_f32_16x16x32_bf16 v[108:111], v[166:169], v[212:215], v[108:111]
	v_mfma_f32_16x16x32_bf16 v[104:107], v[174:177], v[212:215], v[104:107]
	v_mfma_f32_16x16x32_bf16 v[92:95], v[166:169], v[220:223], v[92:95]
	v_mfma_f32_16x16x32_bf16 v[88:91], v[174:177], v[220:223], v[88:91]
	v_mfma_f32_16x16x32_bf16 v[76:79], v[166:169], v[228:231], v[76:79]
	v_mfma_f32_16x16x32_bf16 v[72:75], v[174:177], v[228:231], v[72:75]
	s_setprio 0
	s_setprio 1
	v_mfma_f32_16x16x32_bf16 v[116:119], v[178:181], v[200:203], 0
	v_mfma_f32_16x16x32_bf16 v[112:115], v[186:189], v[200:203], 0
	v_mfma_f32_16x16x32_bf16 v[100:103], v[178:181], v[208:211], 0
	v_mfma_f32_16x16x32_bf16 v[96:99], v[186:189], v[208:211], 0
	v_mfma_f32_16x16x32_bf16 v[84:87], v[178:181], v[216:219], 0
	v_mfma_f32_16x16x32_bf16 v[80:83], v[186:189], v[216:219], 0
	v_mfma_f32_16x16x32_bf16 v[68:71], v[178:181], v[224:227], 0
	v_mfma_f32_16x16x32_bf16 v[64:67], v[186:189], v[224:227], 0
	v_mfma_f32_16x16x32_bf16 v[116:119], v[182:185], v[204:207], v[116:119]
	v_mfma_f32_16x16x32_bf16 v[112:115], v[190:193], v[204:207], v[112:115]
	v_mfma_f32_16x16x32_bf16 v[100:103], v[182:185], v[212:215], v[100:103]
	v_mfma_f32_16x16x32_bf16 v[96:99], v[190:193], v[212:215], v[96:99]
	v_mfma_f32_16x16x32_bf16 v[84:87], v[182:185], v[220:223], v[84:87]
	v_mfma_f32_16x16x32_bf16 v[80:83], v[190:193], v[220:223], v[80:83]
	v_mfma_f32_16x16x32_bf16 v[68:71], v[182:185], v[228:231], v[68:71]
	v_mfma_f32_16x16x32_bf16 v[64:67], v[190:193], v[228:231], v[64:67]
	s_setprio 0
	s_barrier
	s_add_i32 s8, s10, s64
	v_lshl_add_u64 v[194:195], s[60:61], 0, v[132:133]
	s_mov_b32 m0, s8
	ds_read_b128 v[200:203], v161 offset:16384
	ds_read_b128 v[204:207], v161 offset:17408
	ds_read_b128 v[208:211], v161 offset:18432
	ds_read_b128 v[212:215], v161 offset:19456
	ds_read_b128 v[216:219], v161 offset:20480
	ds_read_b128 v[220:223], v161 offset:21504
	ds_read_b128 v[224:227], v161 offset:22528
	ds_read_b128 v[228:231], v161 offset:23552
	global_load_lds_dwordx4 v[194:195], off
	s_add_i32 m0, s8, 0x2000
	s_add_u32 s20, s60, 0x40000
	v_lshl_add_u64 v[240:241], s[60:61], 0, v[128:129]
	s_addc_u32 s21, s61, 0
	s_add_i32 s5, s5, s64
	global_load_lds_dwordx4 v[240:241], off
	v_lshl_add_u64 v[242:243], s[20:21], 0, v[132:133]
	s_mov_b32 m0, s5
	v_lshl_add_u64 v[244:245], s[62:63], 0, v[130:131]
	global_load_lds_dwordx4 v[242:243], off
	v_lshl_add_u64 v[242:243], s[20:21], 0, v[128:129]
	s_add_i32 m0, s5, 0x2000
	s_nop 0
	global_load_lds_dwordx4 v[242:243], off
	v_lshl_add_u64 v[242:243], s[62:63], 0, v[134:135]
	s_mov_b32 m0, s65
	s_nop 0
	global_load_lds_dwordx4 v[242:243], off
	s_mov_b32 m0, s66
	s_nop 0
	global_load_lds_dwordx4 v[244:245], off
	s_waitcnt vmcnt(18)
	s_barrier
	s_setprio 1
	s_waitcnt lgkmcnt(0)
	v_mfma_f32_16x16x32_bf16 v[60:63], v[162:165], v[200:203], 0
	v_mfma_f32_16x16x32_bf16 v[56:59], v[170:173], v[200:203], 0
	v_mfma_f32_16x16x32_bf16 v[44:47], v[162:165], v[208:211], 0
	v_mfma_f32_16x16x32_bf16 v[40:43], v[170:173], v[208:211], 0
	v_mfma_f32_16x16x32_bf16 v[28:31], v[162:165], v[216:219], 0
	v_mfma_f32_16x16x32_bf16 v[24:27], v[170:173], v[216:219], 0
	v_mfma_f32_16x16x32_bf16 v[12:15], v[162:165], v[224:227], 0
	v_mfma_f32_16x16x32_bf16 v[8:11], v[170:173], v[224:227], 0
	v_mfma_f32_16x16x32_bf16 v[60:63], v[166:169], v[204:207], v[60:63]
	v_mfma_f32_16x16x32_bf16 v[56:59], v[174:177], v[204:207], v[56:59]
	v_mfma_f32_16x16x32_bf16 v[44:47], v[166:169], v[212:215], v[44:47]
	v_mfma_f32_16x16x32_bf16 v[40:43], v[174:177], v[212:215], v[40:43]
	v_mfma_f32_16x16x32_bf16 v[28:31], v[166:169], v[220:223], v[28:31]
	v_mfma_f32_16x16x32_bf16 v[24:27], v[174:177], v[220:223], v[24:27]
	v_mfma_f32_16x16x32_bf16 v[12:15], v[166:169], v[228:231], v[12:15]
	v_mfma_f32_16x16x32_bf16 v[8:11], v[174:177], v[228:231], v[8:11]
	s_setprio 0
	s_setprio 1
	v_mfma_f32_16x16x32_bf16 v[52:55], v[178:181], v[200:203], 0
	v_mfma_f32_16x16x32_bf16 v[48:51], v[186:189], v[200:203], 0
	v_mfma_f32_16x16x32_bf16 v[36:39], v[178:181], v[208:211], 0
	v_mfma_f32_16x16x32_bf16 v[32:35], v[186:189], v[208:211], 0
	v_mfma_f32_16x16x32_bf16 v[20:23], v[178:181], v[216:219], 0
	v_mfma_f32_16x16x32_bf16 v[16:19], v[186:189], v[216:219], 0
	v_mfma_f32_16x16x32_bf16 v[4:7], v[178:181], v[224:227], 0
	v_mfma_f32_16x16x32_bf16 v[0:3], v[186:189], v[224:227], 0
	v_mfma_f32_16x16x32_bf16 v[52:55], v[182:185], v[204:207], v[52:55]
	v_mfma_f32_16x16x32_bf16 v[48:51], v[190:193], v[204:207], v[48:51]
	v_mfma_f32_16x16x32_bf16 v[36:39], v[182:185], v[212:215], v[36:39]
	v_mfma_f32_16x16x32_bf16 v[32:35], v[190:193], v[212:215], v[32:35]
	v_mfma_f32_16x16x32_bf16 v[20:23], v[182:185], v[220:223], v[20:23]
	v_mfma_f32_16x16x32_bf16 v[16:19], v[190:193], v[220:223], v[16:19]
	v_mfma_f32_16x16x32_bf16 v[4:7], v[182:185], v[228:231], v[4:7]
	v_mfma_f32_16x16x32_bf16 v[0:3], v[190:193], v[228:231], v[0:3]
	s_setprio 0
	s_barrier
	s_branch .Lmid_g3

; #define PG8_STAGE(bufoff, gbase, voff) do { _Pragma("unroll") for (int _i = 0; _i < 2; ++_i) \
;         __builtin_amdgcn_global_load_lds((const unsigned*)((const char*)(gbase) + (voff)[_i]), (PG8_LAS unsigned*)(lds + (bufoff) + ldsw + _i * 8192), 16, 0, 0); } while (0)
; #define PG8_LDA(dst, b, h) do { _Pragma("unroll") for (int m = 0; m < 4; ++m) _Pragma("unroll") for (int k = 0; k < 2; ++k) dst[m][k] = *(const PG8_LAS bf16x8*)(lds + PG8_SA(b, h) + aoff + m * 2048 + k * 1024); } while (0)
; #define PG8_LDB(dst, b, h) do { _Pragma("unroll") for (int n = 0; n < 2; ++n) _Pragma("unroll") for (int k = 0; k < 2; ++k) dst[n][k] = *(const PG8_LAS bf16x8*)(lds + PG8_SB(b, h) + boff + n * 2048 + k * 1024); } while (0)
; #define PG8_MMA(ai, bj, At, Bt) do { __builtin_amdgcn_s_setprio(1); _Pragma("unroll") for (int m = 0; m < 4; ++m) _Pragma("unroll") for (int n = 0; n < 2; ++n) _Pragma("unroll") for (int k = 0; k < 2; ++k) \
;         acc[ai][bj][m][n] = __builtin_amdgcn_mfma_f32_16x16x32_bf16(Bt[n][k], At[m][k], acc[ai][bj][m][n], 0, 0, 0); __builtin_amdgcn_s_setprio(0); } while (0)
; #define PG8_WAIT_V(n) asm volatile("s_waitcnt vmcnt(" #n ")" ::: "memory")
; #define PG8_WAIT_L(n) asm volatile("s_waitcnt lgkmcnt(" #n ")" ::: "memory")
; #define PG8_BAR __builtin_amdgcn_s_barrier()
; #define PG8_SCHED __builtin_amdgcn_sched_barrier(0)
; template <class Epi, class Sched, bool ALIGN_EPI = false, bool SP2 = false>
; __device__ __forceinline__ void gemm_phase(PG8_LAS unsigned char* lds, const Gemm g, const Sched& S, const Epi& E) {
;     ...
;             PG8_LDB(B0, 0, 0); PG8_LDB(B1, 0, 1); PG8_SCHED; PG8_LDA(At, 0, 0); PG8_STAGE(PG8_SA(1, 1), a1 + hstep, voffA);
;             PG8_WAIT_V(8); PG8_WAIT_L(0); PG8_BAR; PG8_MMA(0, 0, At, B0); PG8_MMA(0, 1, At, B1); PG8_BAR; PG8_SCHED;
;             PG8_LDA(At, 0, 1); PG8_STAGE(PG8_SB(0, 0), b2, voffB); PG8_STAGE(PG8_SB(0, 1), b2 + hstep, voffB); PG8_STAGE(PG8_SA(0, 0), a2, voffA);
;             PG8_WAIT_V(8); PG8_WAIT_L(0); PG8_BAR; PG8_MMA(1, 0, At, B0); PG8_MMA(1, 1, At, B1); PG8_BAR; PG8_SCHED;
.LBB0_152:
	s_add_u32 s5, s58, 0xfffc0080
	s_addc_u32 s8, s59, -1
	s_add_i32 s10, 0, 0x10000
	s_cmp_eq_u32 s72, 12
	s_cselect_b32 s63, s26, s8
	s_cselect_b32 s62, s27, s5
	v_add_u32_e32 v143, s10, v157
	s_cselect_b32 s61, s36, s53
	s_cselect_b32 s60, s39, s51
	s_add_i32 s5, 0, 0x14000
	ds_read_b128 v[162:165], v143
	ds_read_b128 v[166:169], v143 offset:1024
	ds_read_b128 v[170:173], v143 offset:2048
	ds_read_b128 v[174:177], v143 offset:3072
	v_add_u32_e32 v143, s5, v157
	ds_read_b128 v[178:181], v143
	ds_read_b128 v[182:185], v143 offset:1024
	ds_read_b128 v[186:189], v143 offset:2048
	ds_read_b128 v[190:193], v143 offset:3072
	v_lshl_add_u64 v[194:195], s[58:59], 0, v[140:141]
	s_add_i32 m0, s65, 0xc000
	ds_read_b128 v[200:203], v161
	ds_read_b128 v[204:207], v161 offset:1024
	ds_read_b128 v[208:211], v161 offset:2048
	ds_read_b128 v[212:215], v161 offset:3072
	ds_read_b128 v[216:219], v161 offset:4096
	ds_read_b128 v[220:223], v161 offset:5120
	ds_read_b128 v[224:227], v161 offset:6144
	ds_read_b128 v[228:231], v161 offset:7168
	global_load_lds_dwordx4 v[194:195], off
	v_lshl_add_u64 v[194:195], s[58:59], 0, v[138:139]
	s_add_i32 m0, s65, 0xe000
	s_nop 0
	global_load_lds_dwordx4 v[194:195], off
	s_waitcnt vmcnt(8)
	s_barrier
	s_setprio 1
	s_waitcnt lgkmcnt(0)
	v_mfma_f32_16x16x32_bf16 v[124:127], v[162:165], v[200:203], v[124:127]
	v_mfma_f32_16x16x32_bf16 v[120:123], v[170:173], v[200:203], v[120:123]
	v_mfma_f32_16x16x32_bf16 v[108:111], v[162:165], v[208:211], v[108:111]
	v_mfma_f32_16x16x32_bf16 v[104:107], v[170:173], v[208:211], v[104:107]
	v_mfma_f32_16x16x32_bf16 v[92:95], v[162:165], v[216:219], v[92:95]
	v_mfma_f32_16x16x32_bf16 v[88:91], v[170:173], v[216:219], v[88:91]
	v_mfma_f32_16x16x32_bf16 v[76:79], v[162:165], v[224:227], v[76:79]
	v_mfma_f32_16x16x32_bf16 v[72:75], v[170:173], v[224:227], v[72:75]
	v_mfma_f32_16x16x32_bf16 v[124:127], v[166:169], v[204:207], v[124:127]
	v_mfma_f32_16x16x32_bf16 v[120:123], v[174:177], v[204:207], v[120:123]
	v_mfma_f32_16x16x32_bf16 v[108:111], v[166:169], v[212:215], v[108:111]
	v_mfma_f32_16x16x32_bf16 v[104:107], v[174:177], v[212:215], v[104:107]
	v_mfma_f32_16x16x32_bf16 v[92:95], v[166:169], v[220:223], v[92:95]
	v_mfma_f32_16x16x32_bf16 v[88:91], v[174:177], v[220:223], v[88:91]
	v_mfma_f32_16x16x32_bf16 v[76:79], v[166:169], v[228:231], v[76:79]
	v_mfma_f32_16x16x32_bf16 v[72:75], v[174:177], v[228:231], v[72:75]
	s_setprio 0
	s_setprio 1
	v_mfma_f32_16x16x32_bf16 v[116:119], v[178:181], v[200:203], v[116:119]
	v_mfma_f32_16x16x32_bf16 v[112:115], v[186:189], v[200:203], v[112:115]
	v_mfma_f32_16x16x32_bf16 v[100:103], v[178:181], v[208:211], v[100:103]
	v_mfma_f32_16x16x32_bf16 v[96:99], v[186:189], v[208:211], v[96:99]
	v_mfma_f32_16x16x32_bf16 v[84:87], v[178:181], v[216:219], v[84:87]
	v_mfma_f32_16x16x32_bf16 v[80:83], v[186:189], v[216:219], v[80:83]
	v_mfma_f32_16x16x32_bf16 v[68:71], v[178:181], v[224:227], v[68:71]
	v_mfma_f32_16x16x32_bf16 v[64:67], v[186:189], v[224:227], v[64:67]
	v_mfma_f32_16x16x32_bf16 v[116:119], v[182:185], v[204:207], v[116:119]
	v_mfma_f32_16x16x32_bf16 v[112:115], v[190:193], v[204:207], v[112:115]
	v_mfma_f32_16x16x32_bf16 v[100:103], v[182:185], v[212:215], v[100:103]
	v_mfma_f32_16x16x32_bf16 v[96:99], v[190:193], v[212:215], v[96:99]
	v_mfma_f32_16x16x32_bf16 v[84:87], v[182:185], v[220:223], v[84:87]
	v_mfma_f32_16x16x32_bf16 v[80:83], v[190:193], v[220:223], v[80:83]
	v_mfma_f32_16x16x32_bf16 v[68:71], v[182:185], v[228:231], v[68:71]
	v_mfma_f32_16x16x32_bf16 v[64:67], v[190:193], v[228:231], v[64:67]
	s_setprio 0
	s_barrier
	s_add_i32 s8, s10, s64
	v_lshl_add_u64 v[194:195], s[60:61], 0, v[132:133]
	s_mov_b32 m0, s8
	ds_read_b128 v[200:203], v161 offset:16384
	ds_read_b128 v[204:207], v161 offset:17408
	ds_read_b128 v[208:211], v161 offset:18432
	ds_read_b128 v[212:215], v161 offset:19456
	ds_read_b128 v[216:219], v161 offset:20480
	ds_read_b128 v[220:223], v161 offset:21504
	ds_read_b128 v[224:227], v161 offset:22528
	ds_read_b128 v[228:231], v161 offset:23552
	global_load_lds_dwordx4 v[194:195], off
	s_add_i32 m0, s8, 0x2000
	s_add_u32 s20, s60, 0x40000
	v_lshl_add_u64 v[240:241], s[60:61], 0, v[128:129]
	s_addc_u32 s21, s61, 0
	s_add_i32 s5, s5, s64
	global_load_lds_dwordx4 v[240:241], off
	v_lshl_add_u64 v[242:243], s[20:21], 0, v[132:133]
	s_mov_b32 m0, s5
	v_lshl_add_u64 v[244:245], s[62:63], 0, v[130:131]
	global_load_lds_dwordx4 v[242:243], off
	v_lshl_add_u64 v[242:243], s[20:21], 0, v[128:129]
	s_add_i32 m0, s5, 0x2000
	s_nop 0
	global_load_lds_dwordx4 v[242:243], off
	v_lshl_add_u64 v[242:243], s[62:63], 0, v[134:135]
	s_mov_b32 m0, s65
	s_nop 0
	global_load_lds_dwordx4 v[242:243], off
	s_mov_b32 m0, s66
	s_nop 0
	global_load_lds_dwordx4 v[244:245], off
	s_waitcnt vmcnt(8)
	s_barrier
; #define PG8_STAGE(bufoff, gbase, voff) do { _Pragma("unroll") for (int _i = 0; _i < 2; ++_i) \
;         __builtin_amdgcn_global_load_lds((const unsigned*)((const char*)(gbase) + (voff)[_i]), (PG8_LAS unsigned*)(lds + (bufoff) + ldsw + _i * 8192), 16, 0, 0); } while (0)
; #define PG8_LDA(dst, b, h) do { _Pragma("unroll") for (int m = 0; m < 4; ++m) _Pragma("unroll") for (int k = 0; k < 2; ++k) dst[m][k] = *(const PG8_LAS bf16x8*)(lds + PG8_SA(b, h) + aoff + m * 2048 + k * 1024); } while (0)
; #define PG8_LDB(dst, b, h) do { _Pragma("unroll") for (int n = 0; n < 2; ++n) _Pragma("unroll") for (int k = 0; k < 2; ++k) dst[n][k] = *(const PG8_LAS bf16x8*)(lds + PG8_SB(b, h) + boff + n * 2048 + k * 1024); } while (0)
; #define PG8_MMA(ai, bj, At, Bt) do { __builtin_amdgcn_s_setprio(1); _Pragma("unroll") for (int m = 0; m < 4; ++m) _Pragma("unroll") for (int n = 0; n < 2; ++n) _Pragma("unroll") for (int k = 0; k < 2; ++k) \
;         acc[ai][bj][m][n] = __builtin_amdgcn_mfma_f32_16x16x32_bf16(Bt[n][k], At[m][k], acc[ai][bj][m][n], 0, 0, 0); __builtin_amdgcn_s_setprio(0); } while (0)
; #define PG8_WAIT_V(n) asm volatile("s_waitcnt vmcnt(" #n ")" ::: "memory")
; #define PG8_WAIT_L(n) asm volatile("s_waitcnt lgkmcnt(" #n ")" ::: "memory")
; #define PG8_BAR __builtin_amdgcn_s_barrier()
; #define PG8_SCHED __builtin_amdgcn_sched_barrier(0)
; template <class Epi, class Sched, bool ALIGN_EPI = false, bool SP2 = false>
; __device__ __forceinline__ void gemm_phase(PG8_LAS unsigned char* lds, const Gemm g, const Sched& S, const Epi& E) {
;     ...
;             PG8_WAIT_V(8); PG8_WAIT_L(0); PG8_BAR; PG8_MMA(1, 0, At, B0); PG8_MMA(1, 1, At, B1); PG8_BAR; PG8_SCHED;
;             PG8_LDB(B0, 1, 0); PG8_LDB(B1, 1, 1); PG8_SCHED; PG8_LDA(At, 1, 0); PG8_STAGE(PG8_SA(0, 1), a2 + hstep, voffA);
;             PG8_WAIT_V(8); PG8_WAIT_L(0); PG8_BAR; PG8_MMA(0, 0, At, B0); PG8_MMA(0, 1, At, B1); PG8_BAR; PG8_SCHED;
	s_setprio 1
	s_waitcnt lgkmcnt(0)
	v_mfma_f32_16x16x32_bf16 v[60:63], v[162:165], v[200:203], v[60:63]
	v_mfma_f32_16x16x32_bf16 v[56:59], v[170:173], v[200:203], v[56:59]
	v_mfma_f32_16x16x32_bf16 v[44:47], v[162:165], v[208:211], v[44:47]
	v_mfma_f32_16x16x32_bf16 v[40:43], v[170:173], v[208:211], v[40:43]
	v_mfma_f32_16x16x32_bf16 v[28:31], v[162:165], v[216:219], v[28:31]
	v_mfma_f32_16x16x32_bf16 v[24:27], v[170:173], v[216:219], v[24:27]
	v_mfma_f32_16x16x32_bf16 v[12:15], v[162:165], v[224:227], v[12:15]
	v_mfma_f32_16x16x32_bf16 v[8:11], v[170:173], v[224:227], v[8:11]
	v_mfma_f32_16x16x32_bf16 v[60:63], v[166:169], v[204:207], v[60:63]
	v_mfma_f32_16x16x32_bf16 v[56:59], v[174:177], v[204:207], v[56:59]
	v_mfma_f32_16x16x32_bf16 v[44:47], v[166:169], v[212:215], v[44:47]
	v_mfma_f32_16x16x32_bf16 v[40:43], v[174:177], v[212:215], v[40:43]
	v_mfma_f32_16x16x32_bf16 v[28:31], v[166:169], v[220:223], v[28:31]
	v_mfma_f32_16x16x32_bf16 v[24:27], v[174:177], v[220:223], v[24:27]
	v_mfma_f32_16x16x32_bf16 v[12:15], v[166:169], v[228:231], v[12:15]
	v_mfma_f32_16x16x32_bf16 v[8:11], v[174:177], v[228:231], v[8:11]
	s_setprio 0
	s_setprio 1
	v_mfma_f32_16x16x32_bf16 v[52:55], v[178:181], v[200:203], v[52:55]
	v_mfma_f32_16x16x32_bf16 v[48:51], v[186:189], v[200:203], v[48:51]
	v_mfma_f32_16x16x32_bf16 v[36:39], v[178:181], v[208:211], v[36:39]
	v_mfma_f32_16x16x32_bf16 v[32:35], v[186:189], v[208:211], v[32:35]
	v_mfma_f32_16x16x32_bf16 v[20:23], v[178:181], v[216:219], v[20:23]
	v_mfma_f32_16x16x32_bf16 v[16:19], v[186:189], v[216:219], v[16:19]
	v_mfma_f32_16x16x32_bf16 v[4:7], v[178:181], v[224:227], v[4:7]
	v_mfma_f32_16x16x32_bf16 v[0:3], v[186:189], v[224:227], v[0:3]
	v_mfma_f32_16x16x32_bf16 v[52:55], v[182:185], v[204:207], v[52:55]
	v_mfma_f32_16x16x32_bf16 v[48:51], v[190:193], v[204:207], v[48:51]
	v_mfma_f32_16x16x32_bf16 v[36:39], v[182:185], v[212:215], v[36:39]
	v_mfma_f32_16x16x32_bf16 v[32:35], v[190:193], v[212:215], v[32:35]
	v_mfma_f32_16x16x32_bf16 v[20:23], v[182:185], v[220:223], v[20:23]
	v_mfma_f32_16x16x32_bf16 v[16:19], v[190:193], v[220:223], v[16:19]
	v_mfma_f32_16x16x32_bf16 v[4:7], v[182:185], v[228:231], v[4:7]
	v_mfma_f32_16x16x32_bf16 v[0:3], v[190:193], v[228:231], v[0:3]
	s_setprio 0
	s_barrier
.Lmid_g3:
	s_add_i32 s5, 0, 0x18000
	v_add_u32_e32 v143, s5, v157
	s_add_i32 s8, 0, 0x1c000
	ds_read_b128 v[162:165], v143
	ds_read_b128 v[166:169], v143 offset:1024
	ds_read_b128 v[170:173], v143 offset:2048
	ds_read_b128 v[174:177], v143 offset:3072
	v_add_u32_e32 v143, s8, v157
	ds_read_b128 v[178:181], v143
	ds_read_b128 v[182:185], v143 offset:1024
	ds_read_b128 v[186:189], v143 offset:2048
	ds_read_b128 v[190:193], v143 offset:3072
	s_add_u32 s20, s62, 0x40000
	s_addc_u32 s21, s63, 0
	s_mov_b32 m0, s67
	v_lshl_add_u64 v[246:247], s[20:21], 0, v[134:135]
	ds_read_b128 v[200:203], v161 offset:32768
	ds_read_b128 v[204:207], v161 offset:33792
	ds_read_b128 v[208:211], v161 offset:34816
	ds_read_b128 v[212:215], v161 offset:35840
	ds_read_b128 v[216:219], v161 offset:36864
	ds_read_b128 v[220:223], v161 offset:37888
	ds_read_b128 v[224:227], v161 offset:38912
	ds_read_b128 v[228:231], v161 offset:39936
	global_load_lds_dwordx4 v[246:247], off
	v_lshl_add_u64 v[246:247], s[20:21], 0, v[130:131]
	s_mov_b32 m0, s68
	s_nop 0
	global_load_lds_dwordx4 v[246:247], off
	s_waitcnt vmcnt(8)
	s_barrier
	s_setprio 1
	s_waitcnt lgkmcnt(0)
	v_mfma_f32_16x16x32_bf16 v[124:127], v[162:165], v[200:203], v[124:127]
	v_mfma_f32_16x16x32_bf16 v[120:123], v[170:173], v[200:203], v[120:123]
	v_mfma_f32_16x16x32_bf16 v[108:111], v[162:165], v[208:211], v[108:111]
	v_mfma_f32_16x16x32_bf16 v[104:107], v[170:173], v[208:211], v[104:107]
	v_mfma_f32_16x16x32_bf16 v[92:95], v[162:165], v[216:219], v[92:95]
	v_mfma_f32_16x16x32_bf16 v[88:91], v[170:173], v[216:219], v[88:91]
	v_mfma_f32_16x16x32_bf16 v[76:79], v[162:165], v[224:227], v[76:79]
	v_mfma_f32_16x16x32_bf16 v[72:75], v[170:173], v[224:227], v[72:75]
	v_mfma_f32_16x16x32_bf16 v[124:127], v[166:169], v[204:207], v[124:127]
	v_mfma_f32_16x16x32_bf16 v[120:123], v[174:177], v[204:207], v[120:123]
	v_mfma_f32_16x16x32_bf16 v[108:111], v[166:169], v[212:215], v[108:111]
	v_mfma_f32_16x16x32_bf16 v[104:107], v[174:177], v[212:215], v[104:107]
	v_mfma_f32_16x16x32_bf16 v[92:95], v[166:169], v[220:223], v[92:95]
	v_mfma_f32_16x16x32_bf16 v[88:91], v[174:177], v[220:223], v[88:91]
	v_mfma_f32_16x16x32_bf16 v[76:79], v[166:169], v[228:231], v[76:79]
	v_mfma_f32_16x16x32_bf16 v[72:75], v[174:177], v[228:231], v[72:75]
	s_setprio 0
	s_setprio 1
	v_mfma_f32_16x16x32_bf16 v[116:119], v[178:181], v[200:203], v[116:119]
	v_mfma_f32_16x16x32_bf16 v[112:115], v[186:189], v[200:203], v[112:115]
	v_mfma_f32_16x16x32_bf16 v[100:103], v[178:181], v[208:211], v[100:103]
	v_mfma_f32_16x16x32_bf16 v[96:99], v[186:189], v[208:211], v[96:99]
	v_mfma_f32_16x16x32_bf16 v[84:87], v[178:181], v[216:219], v[84:87]
	v_mfma_f32_16x16x32_bf16 v[80:83], v[186:189], v[216:219], v[80:83]
	v_mfma_f32_16x16x32_bf16 v[68:71], v[178:181], v[224:227], v[68:71]
	v_mfma_f32_16x16x32_bf16 v[64:67], v[186:189], v[224:227], v[64:67]
	v_mfma_f32_16x16x32_bf16 v[116:119], v[182:185], v[204:207], v[116:119]
	v_mfma_f32_16x16x32_bf16 v[112:115], v[190:193], v[204:207], v[112:115]
	v_mfma_f32_16x16x32_bf16 v[100:103], v[182:185], v[212:215], v[100:103]
	v_mfma_f32_16x16x32_bf16 v[96:99], v[190:193], v[212:215], v[96:99]
	v_mfma_f32_16x16x32_bf16 v[84:87], v[182:185], v[220:223], v[84:87]
	v_mfma_f32_16x16x32_bf16 v[80:83], v[190:193], v[220:223], v[80:83]
	v_mfma_f32_16x16x32_bf16 v[68:71], v[182:185], v[228:231], v[68:71]
	v_mfma_f32_16x16x32_bf16 v[64:67], v[190:193], v[228:231], v[64:67]
	s_setprio 0
	s_barrier
; #define PG8_STAGE(bufoff, gbase, voff) do { _Pragma("unroll") for (int _i = 0; _i < 2; ++_i) \
;         __builtin_amdgcn_global_load_lds((const unsigned*)((const char*)(gbase) + (voff)[_i]), (PG8_LAS unsigned*)(lds + (bufoff) + ldsw + _i * 8192), 16, 0, 0); } while (0)
; #define PG8_LDA(dst, b, h) do { _Pragma("unroll") for (int m = 0; m < 4; ++m) _Pragma("unroll") for (int k = 0; k < 2; ++k) dst[m][k] = *(const PG8_LAS bf16x8*)(lds + PG8_SA(b, h) + aoff + m * 2048 + k * 1024); } while (0)
; #define PG8_MMA(ai, bj, At, Bt) do { __builtin_amdgcn_s_setprio(1); _Pragma("unroll") for (int m = 0; m < 4; ++m) _Pragma("unroll") for (int n = 0; n < 2; ++n) _Pragma("unroll") for (int k = 0; k < 2; ++k) \
;         acc[ai][bj][m][n] = __builtin_amdgcn_mfma_f32_16x16x32_bf16(Bt[n][k], At[m][k], acc[ai][bj][m][n], 0, 0, 0); __builtin_amdgcn_s_setprio(0); } while (0)
; #define PG8_WAIT_V(n) asm volatile("s_waitcnt vmcnt(" #n ")" ::: "memory")
; #define PG8_WAIT_L(n) asm volatile("s_waitcnt lgkmcnt(" #n ")" ::: "memory")
; #define PG8_BAR __builtin_amdgcn_s_barrier()
; #define PG8_SCHED __builtin_amdgcn_sched_barrier(0)
; template <class Epi, class Sched, bool ALIGN_EPI = false, bool SP2 = false>
; __device__ __forceinline__ void gemm_phase(PG8_LAS unsigned char* lds, const Gemm g, const Sched& S, const Epi& E) {
;     ...
;             PG8_LDA(At, 1, 1); PG8_STAGE(PG8_SB(1, 0), b3, voffB); PG8_STAGE(PG8_SB(1, 1), b3 + hstep, voffB); PG8_STAGE(PG8_SA(1, 0), a3, voffA);
;             PG8_WAIT_V(8); PG8_WAIT_L(0); PG8_BAR; PG8_MMA(1, 0, At, B0); PG8_MMA(1, 1, At, B1); PG8_BAR; PG8_SCHED;
;     ...
;         if constexpr (ALIGN_EPI) { if (wr == 0) PG8_BAR; }
	s_add_i32 s5, s5, s64
	v_lshl_add_u64 v[194:195], v[194:195], 0, s[22:23]
	s_mov_b32 m0, s5
	ds_read_b128 v[200:203], v161 offset:49152
	ds_read_b128 v[204:207], v161 offset:50176
	ds_read_b128 v[208:211], v161 offset:51200
	ds_read_b128 v[212:215], v161 offset:52224
	ds_read_b128 v[216:219], v161 offset:53248
	ds_read_b128 v[220:223], v161 offset:54272
	ds_read_b128 v[224:227], v161 offset:55296
	ds_read_b128 v[228:231], v161 offset:56320
	global_load_lds_dwordx4 v[194:195], off
	s_add_i32 m0, s5, 0x2000
	s_add_u32 s20, s60, 0x40080
	v_lshl_add_u64 v[194:195], v[240:241], 0, s[22:23]
	s_addc_u32 s21, s61, 0
	s_add_i32 s5, s8, s64
	global_load_lds_dwordx4 v[194:195], off
	v_lshl_add_u64 v[194:195], s[20:21], 0, v[132:133]
	s_mov_b32 m0, s5
	s_nop 0
	global_load_lds_dwordx4 v[194:195], off
	v_lshl_add_u64 v[194:195], s[20:21], 0, v[128:129]
	s_add_i32 m0, s5, 0x2000
	s_nop 0
	global_load_lds_dwordx4 v[194:195], off
	v_lshl_add_u64 v[194:195], v[242:243], 0, s[22:23]
	s_mov_b32 m0, s69
	s_nop 0
	global_load_lds_dwordx4 v[194:195], off
	v_lshl_add_u64 v[194:195], v[244:245], 0, s[22:23]
	s_mov_b32 m0, s70
	s_nop 0
	global_load_lds_dwordx4 v[194:195], off
	s_waitcnt vmcnt(8)
	s_barrier
	s_setprio 1
	s_waitcnt lgkmcnt(0)
	v_mfma_f32_16x16x32_bf16 v[60:63], v[162:165], v[200:203], v[60:63]
	v_mfma_f32_16x16x32_bf16 v[56:59], v[170:173], v[200:203], v[56:59]
	v_mfma_f32_16x16x32_bf16 v[44:47], v[162:165], v[208:211], v[44:47]
	v_mfma_f32_16x16x32_bf16 v[40:43], v[170:173], v[208:211], v[40:43]
	v_mfma_f32_16x16x32_bf16 v[28:31], v[162:165], v[216:219], v[28:31]
	v_mfma_f32_16x16x32_bf16 v[24:27], v[170:173], v[216:219], v[24:27]
	v_mfma_f32_16x16x32_bf16 v[12:15], v[162:165], v[224:227], v[12:15]
	v_mfma_f32_16x16x32_bf16 v[8:11], v[170:173], v[224:227], v[8:11]
	v_mfma_f32_16x16x32_bf16 v[60:63], v[166:169], v[204:207], v[60:63]
	v_mfma_f32_16x16x32_bf16 v[56:59], v[174:177], v[204:207], v[56:59]
	v_mfma_f32_16x16x32_bf16 v[44:47], v[166:169], v[212:215], v[44:47]
	v_mfma_f32_16x16x32_bf16 v[40:43], v[174:177], v[212:215], v[40:43]
	v_mfma_f32_16x16x32_bf16 v[28:31], v[166:169], v[220:223], v[28:31]
	v_mfma_f32_16x16x32_bf16 v[24:27], v[174:177], v[220:223], v[24:27]
	v_mfma_f32_16x16x32_bf16 v[12:15], v[166:169], v[228:231], v[12:15]
	v_mfma_f32_16x16x32_bf16 v[8:11], v[174:177], v[228:231], v[8:11]
	s_setprio 0
	s_setprio 1
	v_mfma_f32_16x16x32_bf16 v[52:55], v[178:181], v[200:203], v[52:55]
	v_mfma_f32_16x16x32_bf16 v[48:51], v[186:189], v[200:203], v[48:51]
	v_mfma_f32_16x16x32_bf16 v[36:39], v[178:181], v[208:211], v[36:39]
	v_mfma_f32_16x16x32_bf16 v[32:35], v[186:189], v[208:211], v[32:35]
	v_mfma_f32_16x16x32_bf16 v[20:23], v[178:181], v[216:219], v[20:23]
	v_mfma_f32_16x16x32_bf16 v[16:19], v[186:189], v[216:219], v[16:19]
	v_mfma_f32_16x16x32_bf16 v[4:7], v[178:181], v[224:227], v[4:7]
	v_mfma_f32_16x16x32_bf16 v[0:3], v[186:189], v[224:227], v[0:3]
	v_mfma_f32_16x16x32_bf16 v[52:55], v[182:185], v[204:207], v[52:55]
	v_mfma_f32_16x16x32_bf16 v[48:51], v[190:193], v[204:207], v[48:51]
	v_mfma_f32_16x16x32_bf16 v[36:39], v[182:185], v[212:215], v[36:39]
	v_mfma_f32_16x16x32_bf16 v[32:35], v[190:193], v[212:215], v[32:35]
	v_mfma_f32_16x16x32_bf16 v[20:23], v[182:185], v[220:223], v[20:23]
	v_mfma_f32_16x16x32_bf16 v[16:19], v[190:193], v[220:223], v[16:19]
	v_mfma_f32_16x16x32_bf16 v[4:7], v[182:185], v[228:231], v[4:7]
	v_mfma_f32_16x16x32_bf16 v[0:3], v[190:193], v[228:231], v[0:3]
	s_setprio 0
	s_barrier
	s_add_i32 s72, s72, 2
	s_add_u32 s51, s51, 0x100
	s_addc_u32 s53, s53, 0
	s_add_u32 s58, s58, 0x100
	s_addc_u32 s59, s59, 0
	s_cmp_gt_u32 s72, 13
	s_cbranch_scc0 .LBB0_152
	s_and_b64 vcc, exec, s[48:49]
	s_cbranch_vccz .LBB0_155
	s_barrier

; #define PG8_STAGE(bufoff, gbase, voff) do { _Pragma("unroll") for (int _i = 0; _i < 2; ++_i) \
;         __builtin_amdgcn_global_load_lds((const unsigned*)((const char*)(gbase) + (voff)[_i]), (PG8_LAS unsigned*)(lds + (bufoff) + ldsw + _i * 8192), 16, 0, 0); } while (0)
; #define PG8_LDA(dst, b, h) do { _Pragma("unroll") for (int m = 0; m < 4; ++m) _Pragma("unroll") for (int k = 0; k < 2; ++k) dst[m][k] = *(const PG8_LAS bf16x8*)(lds + PG8_SA(b, h) + aoff + m * 2048 + k * 1024); } while (0)
; #define PG8_LDB(dst, b, h) do { _Pragma("unroll") for (int n = 0; n < 2; ++n) _Pragma("unroll") for (int k = 0; k < 2; ++k) dst[n][k] = *(const PG8_LAS bf16x8*)(lds + PG8_SB(b, h) + boff + n * 2048 + k * 1024); } while (0)
; #define PG8_MMA(ai, bj, At, Bt) do { __builtin_amdgcn_s_setprio(1); _Pragma("unroll") for (int m = 0; m < 4; ++m) _Pragma("unroll") for (int n = 0; n < 2; ++n) _Pragma("unroll") for (int k = 0; k < 2; ++k) \
;         acc[ai][bj][m][n] = __builtin_amdgcn_mfma_f32_16x16x32_bf16(Bt[n][k], At[m][k], acc[ai][bj][m][n], 0, 0, 0); __builtin_amdgcn_s_setprio(0); } while (0)
; #define PG8_WAIT_V(n) asm volatile("s_waitcnt vmcnt(" #n ")" ::: "memory")
; #define PG8_WAIT_L(n) asm volatile("s_waitcnt lgkmcnt(" #n ")" ::: "memory")
; template <class Epi, class Sched, bool ALIGN_EPI = false, bool SP2 = false>
; __device__ __forceinline__ void gemm_phase(PG8_LAS unsigned char* lds, const Gemm g, const Sched& S, const Epi& E) {
;     ...
;             const bool last = (t == nt - 2);
;             const char* a1 = cA + (size_t)(t + 1) * kstep;
;             const char* a2 = last ? nA : cA + (size_t)(t + 2) * kstep; const char* b2 = last ? nB : cB + (size_t)(t + 2) * kstep;
;             const char* a3 = a2 + kstep; const char* b3 = b2 + kstep;
;             if (last && has_next) S.a_ready(nxt);
;             if constexpr (SP2) {
;             PG8_LDB(B0, 0, 0); PG8_LDB(B1, 0, 1); PG8_SCHED; PG8_LDA(At, 0, 0); PG8_STAGE(PG8_SA(1, 1), a1 + hstep, voffA);
;             PG8_WAIT_V(8); PG8_WAIT_L(0); PG8_BAR; PG8_MMA(0, 0, At, B0); PG8_MMA(0, 1, At, B1); PG8_BAR; PG8_SCHED;
;             PG8_LDA(At, 0, 1); PG8_STAGE(PG8_SB(0, 0), b2, voffB); PG8_STAGE(PG8_SB(0, 1), b2 + hstep, voffB); PG8_STAGE(PG8_SA(0, 0), a2, voffA);
;             PG8_WAIT_V(8); PG8_WAIT_L(0); PG8_BAR; PG8_MMA(1, 0, At, B0); PG8_MMA(1, 1, At, B1); PG8_BAR; PG8_SCHED;
.Lpeel_g2:
	s_add_u32 s5, s60, 0xfffc0080
	s_addc_u32 s8, s61, -1
	s_add_i32 s10, 0, 0x10000
	s_cmp_eq_u32 s74, 12
	s_cselect_b32 s65, s26, s8
	s_cselect_b32 s64, s27, s5
	s_cselect_b32 s63, s39, s73
	s_cselect_b32 s62, s53, s55
	s_add_i32 s5, 0, 0x14000
	v_add_u32_e32 v124, s10, v240
	v_add_u32_e32 v156, s5, v240
	ds_read_b128 v[112:115], v124
	ds_read_b128 v[116:119], v124 offset:1024
	ds_read_b128 v[120:123], v124 offset:2048
	ds_read_b128 v[124:127], v124 offset:3072
	ds_read_b128 v[136:139], v156
	ds_read_b128 v[140:143], v156 offset:1024
	ds_read_b128 v[152:155], v156 offset:2048
	ds_read_b128 v[156:159], v156 offset:3072
	v_lshl_add_u64 v[214:215], s[60:61], 0, v[208:209]
	s_add_i32 m0, s67, 0xc000
	ds_read_b128 v[164:167], v242
	ds_read_b128 v[172:175], v242 offset:1024
	ds_read_b128 v[176:179], v242 offset:2048
	ds_read_b128 v[180:183], v242 offset:3072
	ds_read_b128 v[184:187], v242 offset:4096
	ds_read_b128 v[188:191], v242 offset:5120
	ds_read_b128 v[192:195], v242 offset:6144
	ds_read_b128 v[210:213], v242 offset:7168
	global_load_lds_dwordx4 v[214:215], off
	v_lshl_add_u64 v[214:215], s[60:61], 0, v[206:207]
	s_add_i32 m0, s67, 0xe000
	s_nop 0
	global_load_lds_dwordx4 v[214:215], off
	s_waitcnt vmcnt(32)
	s_barrier
	s_setprio 1
	s_waitcnt lgkmcnt(0)
	v_mfma_f32_16x16x32_bf16 v[168:171], v[112:115], v[164:167], 0
	v_mfma_f32_16x16x32_bf16 v[160:163], v[120:123], v[164:167], 0
	v_mfma_f32_16x16x32_bf16 v[108:111], v[112:115], v[176:179], 0
	v_mfma_f32_16x16x32_bf16 v[104:107], v[120:123], v[176:179], 0
	v_mfma_f32_16x16x32_bf16 v[92:95], v[112:115], v[184:187], 0
	v_mfma_f32_16x16x32_bf16 v[88:91], v[120:123], v[184:187], 0
	v_mfma_f32_16x16x32_bf16 v[76:79], v[112:115], v[192:195], 0
	v_mfma_f32_16x16x32_bf16 v[72:75], v[120:123], v[192:195], 0
	v_mfma_f32_16x16x32_bf16 v[168:171], v[116:119], v[172:175], v[168:171]
	v_mfma_f32_16x16x32_bf16 v[160:163], v[124:127], v[172:175], v[160:163]
	v_mfma_f32_16x16x32_bf16 v[108:111], v[116:119], v[180:183], v[108:111]
	v_mfma_f32_16x16x32_bf16 v[104:107], v[124:127], v[180:183], v[104:107]
	v_mfma_f32_16x16x32_bf16 v[92:95], v[116:119], v[188:191], v[92:95]
	v_mfma_f32_16x16x32_bf16 v[88:91], v[124:127], v[188:191], v[88:91]
	v_mfma_f32_16x16x32_bf16 v[76:79], v[116:119], v[210:213], v[76:79]
	v_mfma_f32_16x16x32_bf16 v[72:75], v[124:127], v[210:213], v[72:75]
	s_setprio 0
	s_setprio 1
	v_mfma_f32_16x16x32_bf16 v[132:135], v[136:139], v[164:167], 0
	v_mfma_f32_16x16x32_bf16 v[128:131], v[152:155], v[164:167], 0
	v_mfma_f32_16x16x32_bf16 v[100:103], v[136:139], v[176:179], 0
	v_mfma_f32_16x16x32_bf16 v[96:99], v[152:155], v[176:179], 0
	v_mfma_f32_16x16x32_bf16 v[84:87], v[136:139], v[184:187], 0
	v_mfma_f32_16x16x32_bf16 v[80:83], v[152:155], v[184:187], 0
	v_mfma_f32_16x16x32_bf16 v[68:71], v[136:139], v[192:195], 0
	v_mfma_f32_16x16x32_bf16 v[64:67], v[152:155], v[192:195], 0
	v_mfma_f32_16x16x32_bf16 v[132:135], v[140:143], v[172:175], v[132:135]
	v_mfma_f32_16x16x32_bf16 v[128:131], v[156:159], v[172:175], v[128:131]
	v_mfma_f32_16x16x32_bf16 v[100:103], v[140:143], v[180:183], v[100:103]
	v_mfma_f32_16x16x32_bf16 v[96:99], v[156:159], v[180:183], v[96:99]
	v_mfma_f32_16x16x32_bf16 v[84:87], v[140:143], v[188:191], v[84:87]
	v_mfma_f32_16x16x32_bf16 v[80:83], v[156:159], v[188:191], v[80:83]
	v_mfma_f32_16x16x32_bf16 v[68:71], v[140:143], v[210:213], v[68:71]
	v_mfma_f32_16x16x32_bf16 v[64:67], v[156:159], v[210:213], v[64:67]
	s_setprio 0
	s_barrier
	s_add_i32 s8, s10, s66
	v_lshl_add_u64 v[214:215], s[62:63], 0, v[202:203]
	s_mov_b32 m0, s8
	ds_read_b128 v[164:167], v242 offset:16384
	ds_read_b128 v[172:175], v242 offset:17408
	ds_read_b128 v[176:179], v242 offset:18432
	ds_read_b128 v[180:183], v242 offset:19456
	ds_read_b128 v[184:187], v242 offset:20480
	ds_read_b128 v[188:191], v242 offset:21504
	ds_read_b128 v[192:195], v242 offset:22528
	ds_read_b128 v[210:213], v242 offset:23552
	global_load_lds_dwordx4 v[214:215], off
	s_add_i32 m0, s8, 0x2000
	s_add_u32 s20, s62, 0x40000
	v_lshl_add_u64 v[216:217], s[62:63], 0, v[146:147]
	s_addc_u32 s21, s63, 0
	s_add_i32 s5, s5, s66
	global_load_lds_dwordx4 v[216:217], off
	v_lshl_add_u64 v[218:219], s[20:21], 0, v[202:203]
	s_mov_b32 m0, s5
	v_lshl_add_u64 v[220:221], s[64:65], 0, v[200:201]
	global_load_lds_dwordx4 v[218:219], off
	v_lshl_add_u64 v[218:219], s[20:21], 0, v[146:147]
	s_add_i32 m0, s5, 0x2000
	s_nop 0
	global_load_lds_dwordx4 v[218:219], off
	v_lshl_add_u64 v[218:219], s[64:65], 0, v[204:205]
	s_mov_b32 m0, s67
	s_nop 0
	global_load_lds_dwordx4 v[218:219], off
	s_mov_b32 m0, s68
	s_nop 0
	global_load_lds_dwordx4 v[220:221], off
	s_waitcnt vmcnt(32)
	s_barrier
	s_setprio 1
	s_waitcnt lgkmcnt(0)
	v_mfma_f32_16x16x32_bf16 v[60:63], v[112:115], v[164:167], 0
	v_mfma_f32_16x16x32_bf16 v[56:59], v[120:123], v[164:167], 0
	v_mfma_f32_16x16x32_bf16 v[44:47], v[112:115], v[176:179], 0
	v_mfma_f32_16x16x32_bf16 v[40:43], v[120:123], v[176:179], 0
	v_mfma_f32_16x16x32_bf16 v[28:31], v[112:115], v[184:187], 0
	v_mfma_f32_16x16x32_bf16 v[24:27], v[120:123], v[184:187], 0
	v_mfma_f32_16x16x32_bf16 v[12:15], v[112:115], v[192:195], 0
	v_mfma_f32_16x16x32_bf16 v[8:11], v[120:123], v[192:195], 0
	v_mfma_f32_16x16x32_bf16 v[60:63], v[116:119], v[172:175], v[60:63]
	v_mfma_f32_16x16x32_bf16 v[56:59], v[124:127], v[172:175], v[56:59]
	v_mfma_f32_16x16x32_bf16 v[44:47], v[116:119], v[180:183], v[44:47]
	v_mfma_f32_16x16x32_bf16 v[40:43], v[124:127], v[180:183], v[40:43]
	v_mfma_f32_16x16x32_bf16 v[28:31], v[116:119], v[188:191], v[28:31]
	v_mfma_f32_16x16x32_bf16 v[24:27], v[124:127], v[188:191], v[24:27]
	v_mfma_f32_16x16x32_bf16 v[12:15], v[116:119], v[210:213], v[12:15]
	v_mfma_f32_16x16x32_bf16 v[8:11], v[124:127], v[210:213], v[8:11]
	s_setprio 0
	s_setprio 1
	v_mfma_f32_16x16x32_bf16 v[52:55], v[136:139], v[164:167], 0
	v_mfma_f32_16x16x32_bf16 v[48:51], v[152:155], v[164:167], 0
	v_mfma_f32_16x16x32_bf16 v[36:39], v[136:139], v[176:179], 0
	v_mfma_f32_16x16x32_bf16 v[32:35], v[152:155], v[176:179], 0
	v_mfma_f32_16x16x32_bf16 v[20:23], v[136:139], v[184:187], 0
	v_mfma_f32_16x16x32_bf16 v[16:19], v[152:155], v[184:187], 0
	v_mfma_f32_16x16x32_bf16 v[4:7], v[136:139], v[192:195], 0
	v_mfma_f32_16x16x32_bf16 v[0:3], v[152:155], v[192:195], 0
	v_mfma_f32_16x16x32_bf16 v[52:55], v[140:143], v[172:175], v[52:55]
	v_mfma_f32_16x16x32_bf16 v[48:51], v[156:159], v[172:175], v[48:51]
	v_mfma_f32_16x16x32_bf16 v[36:39], v[140:143], v[180:183], v[36:39]
	v_mfma_f32_16x16x32_bf16 v[32:35], v[156:159], v[180:183], v[32:35]
	v_mfma_f32_16x16x32_bf16 v[20:23], v[140:143], v[188:191], v[20:23]
	v_mfma_f32_16x16x32_bf16 v[16:19], v[156:159], v[188:191], v[16:19]
	v_mfma_f32_16x16x32_bf16 v[4:7], v[140:143], v[210:213], v[4:7]
	v_mfma_f32_16x16x32_bf16 v[0:3], v[156:159], v[210:213], v[0:3]
	s_setprio 0
	s_barrier
	s_branch .Lmid_g2

; #define PG8_STAGE(bufoff, gbase, voff) do { _Pragma("unroll") for (int _i = 0; _i < 2; ++_i) \
;         __builtin_amdgcn_global_load_lds((const unsigned*)((const char*)(gbase) + (voff)[_i]), (PG8_LAS unsigned*)(lds + (bufoff) + ldsw + _i * 8192), 16, 0, 0); } while (0)
; #define PG8_LDA(dst, b, h) do { _Pragma("unroll") for (int m = 0; m < 4; ++m) _Pragma("unroll") for (int k = 0; k < 2; ++k) dst[m][k] = *(const PG8_LAS bf16x8*)(lds + PG8_SA(b, h) + aoff + m * 2048 + k * 1024); } while (0)
; #define PG8_LDB(dst, b, h) do { _Pragma("unroll") for (int n = 0; n < 2; ++n) _Pragma("unroll") for (int k = 0; k < 2; ++k) dst[n][k] = *(const PG8_LAS bf16x8*)(lds + PG8_SB(b, h) + boff + n * 2048 + k * 1024); } while (0)
; #define PG8_MMA(ai, bj, At, Bt) do { __builtin_amdgcn_s_setprio(1); _Pragma("unroll") for (int m = 0; m < 4; ++m) _Pragma("unroll") for (int n = 0; n < 2; ++n) _Pragma("unroll") for (int k = 0; k < 2; ++k) \
;         acc[ai][bj][m][n] = __builtin_amdgcn_mfma_f32_16x16x32_bf16(Bt[n][k], At[m][k], acc[ai][bj][m][n], 0, 0, 0); __builtin_amdgcn_s_setprio(0); } while (0)
; #define PG8_WAIT_V(n) asm volatile("s_waitcnt vmcnt(" #n ")" ::: "memory")
; #define PG8_WAIT_L(n) asm volatile("s_waitcnt lgkmcnt(" #n ")" ::: "memory")
; #define PG8_BAR __builtin_amdgcn_s_barrier()
; #define PG8_SCHED __builtin_amdgcn_sched_barrier(0)
; template <class Epi, class Sched, bool ALIGN_EPI = false, bool SP2 = false>
; __device__ __forceinline__ void gemm_phase(PG8_LAS unsigned char* lds, const Gemm g, const Sched& S, const Epi& E) {
;     ...
;             PG8_LDB(B0, 0, 0); PG8_LDB(B1, 0, 1); PG8_SCHED; PG8_LDA(At, 0, 0); PG8_STAGE(PG8_SA(1, 1), a1 + hstep, voffA);
;             PG8_WAIT_V(8); PG8_WAIT_L(0); PG8_BAR; PG8_MMA(0, 0, At, B0); PG8_MMA(0, 1, At, B1); PG8_BAR; PG8_SCHED;
;             PG8_LDA(At, 0, 1); PG8_STAGE(PG8_SB(0, 0), b2, voffB); PG8_STAGE(PG8_SB(0, 1), b2 + hstep, voffB); PG8_STAGE(PG8_SA(0, 0), a2, voffA);
;             PG8_WAIT_V(8); PG8_WAIT_L(0); PG8_BAR; PG8_MMA(1, 0, At, B0); PG8_MMA(1, 1, At, B1); PG8_BAR; PG8_SCHED;
.LBB0_174:
	s_add_u32 s5, s60, 0xfffc0080
	s_addc_u32 s8, s61, -1
	s_add_i32 s10, 0, 0x10000
	s_cmp_eq_u32 s74, 12
	s_cselect_b32 s65, s26, s8
	s_cselect_b32 s64, s27, s5
	s_cselect_b32 s63, s39, s73
	s_cselect_b32 s62, s53, s55
	s_add_i32 s5, 0, 0x14000
	v_add_u32_e32 v124, s10, v240
	v_add_u32_e32 v156, s5, v240
	ds_read_b128 v[112:115], v124
	ds_read_b128 v[116:119], v124 offset:1024
	ds_read_b128 v[120:123], v124 offset:2048
	ds_read_b128 v[124:127], v124 offset:3072
	ds_read_b128 v[136:139], v156
	ds_read_b128 v[140:143], v156 offset:1024
	ds_read_b128 v[152:155], v156 offset:2048
	ds_read_b128 v[156:159], v156 offset:3072
	v_lshl_add_u64 v[214:215], s[60:61], 0, v[208:209]
	s_add_i32 m0, s67, 0xc000
	ds_read_b128 v[164:167], v242
	ds_read_b128 v[172:175], v242 offset:1024
	ds_read_b128 v[176:179], v242 offset:2048
	ds_read_b128 v[180:183], v242 offset:3072
	ds_read_b128 v[184:187], v242 offset:4096
	ds_read_b128 v[188:191], v242 offset:5120
	ds_read_b128 v[192:195], v242 offset:6144
	ds_read_b128 v[210:213], v242 offset:7168
	global_load_lds_dwordx4 v[214:215], off
	v_lshl_add_u64 v[214:215], s[60:61], 0, v[206:207]
	s_add_i32 m0, s67, 0xe000
	s_nop 0
	global_load_lds_dwordx4 v[214:215], off
	s_waitcnt vmcnt(8)
	s_barrier
	s_setprio 1
	s_waitcnt lgkmcnt(0)
	v_mfma_f32_16x16x32_bf16 v[168:171], v[112:115], v[164:167], v[168:171]
	v_mfma_f32_16x16x32_bf16 v[160:163], v[120:123], v[164:167], v[160:163]
	v_mfma_f32_16x16x32_bf16 v[108:111], v[112:115], v[176:179], v[108:111]
	v_mfma_f32_16x16x32_bf16 v[104:107], v[120:123], v[176:179], v[104:107]
	v_mfma_f32_16x16x32_bf16 v[92:95], v[112:115], v[184:187], v[92:95]
	v_mfma_f32_16x16x32_bf16 v[88:91], v[120:123], v[184:187], v[88:91]
	v_mfma_f32_16x16x32_bf16 v[76:79], v[112:115], v[192:195], v[76:79]
	v_mfma_f32_16x16x32_bf16 v[72:75], v[120:123], v[192:195], v[72:75]
	v_mfma_f32_16x16x32_bf16 v[168:171], v[116:119], v[172:175], v[168:171]
	v_mfma_f32_16x16x32_bf16 v[160:163], v[124:127], v[172:175], v[160:163]
	v_mfma_f32_16x16x32_bf16 v[108:111], v[116:119], v[180:183], v[108:111]
	v_mfma_f32_16x16x32_bf16 v[104:107], v[124:127], v[180:183], v[104:107]
	v_mfma_f32_16x16x32_bf16 v[92:95], v[116:119], v[188:191], v[92:95]
	v_mfma_f32_16x16x32_bf16 v[88:91], v[124:127], v[188:191], v[88:91]
	v_mfma_f32_16x16x32_bf16 v[76:79], v[116:119], v[210:213], v[76:79]
	v_mfma_f32_16x16x32_bf16 v[72:75], v[124:127], v[210:213], v[72:75]
	s_setprio 0
	s_setprio 1
	v_mfma_f32_16x16x32_bf16 v[132:135], v[136:139], v[164:167], v[132:135]
	v_mfma_f32_16x16x32_bf16 v[128:131], v[152:155], v[164:167], v[128:131]
	v_mfma_f32_16x16x32_bf16 v[100:103], v[136:139], v[176:179], v[100:103]
	v_mfma_f32_16x16x32_bf16 v[96:99], v[152:155], v[176:179], v[96:99]
	v_mfma_f32_16x16x32_bf16 v[84:87], v[136:139], v[184:187], v[84:87]
	v_mfma_f32_16x16x32_bf16 v[80:83], v[152:155], v[184:187], v[80:83]
	v_mfma_f32_16x16x32_bf16 v[68:71], v[136:139], v[192:195], v[68:71]
	v_mfma_f32_16x16x32_bf16 v[64:67], v[152:155], v[192:195], v[64:67]
	v_mfma_f32_16x16x32_bf16 v[132:135], v[140:143], v[172:175], v[132:135]
	v_mfma_f32_16x16x32_bf16 v[128:131], v[156:159], v[172:175], v[128:131]
	v_mfma_f32_16x16x32_bf16 v[100:103], v[140:143], v[180:183], v[100:103]
	v_mfma_f32_16x16x32_bf16 v[96:99], v[156:159], v[180:183], v[96:99]
	v_mfma_f32_16x16x32_bf16 v[84:87], v[140:143], v[188:191], v[84:87]
	v_mfma_f32_16x16x32_bf16 v[80:83], v[156:159], v[188:191], v[80:83]
	v_mfma_f32_16x16x32_bf16 v[68:71], v[140:143], v[210:213], v[68:71]
	v_mfma_f32_16x16x32_bf16 v[64:67], v[156:159], v[210:213], v[64:67]
	s_setprio 0
	s_barrier
	s_add_i32 s8, s10, s66
	v_lshl_add_u64 v[214:215], s[62:63], 0, v[202:203]
	s_mov_b32 m0, s8
	ds_read_b128 v[164:167], v242 offset:16384
	ds_read_b128 v[172:175], v242 offset:17408
	ds_read_b128 v[176:179], v242 offset:18432
	ds_read_b128 v[180:183], v242 offset:19456
	ds_read_b128 v[184:187], v242 offset:20480
	ds_read_b128 v[188:191], v242 offset:21504
	ds_read_b128 v[192:195], v242 offset:22528
	ds_read_b128 v[210:213], v242 offset:23552
	global_load_lds_dwordx4 v[214:215], off
	s_add_i32 m0, s8, 0x2000
	s_add_u32 s20, s62, 0x40000
	v_lshl_add_u64 v[216:217], s[62:63], 0, v[146:147]
	s_addc_u32 s21, s63, 0
	s_add_i32 s5, s5, s66
	global_load_lds_dwordx4 v[216:217], off
	v_lshl_add_u64 v[218:219], s[20:21], 0, v[202:203]
	s_mov_b32 m0, s5
	v_lshl_add_u64 v[220:221], s[64:65], 0, v[200:201]
	global_load_lds_dwordx4 v[218:219], off
	v_lshl_add_u64 v[218:219], s[20:21], 0, v[146:147]
	s_add_i32 m0, s5, 0x2000
	s_nop 0
	global_load_lds_dwordx4 v[218:219], off
	v_lshl_add_u64 v[218:219], s[64:65], 0, v[204:205]
	s_mov_b32 m0, s67
	s_nop 0
	global_load_lds_dwordx4 v[218:219], off
	s_mov_b32 m0, s68
	s_nop 0
	global_load_lds_dwordx4 v[220:221], off
	s_waitcnt vmcnt(8)
	s_barrier
; #define PG8_STAGE(bufoff, gbase, voff) do { _Pragma("unroll") for (int _i = 0; _i < 2; ++_i) \
;         __builtin_amdgcn_global_load_lds((const unsigned*)((const char*)(gbase) + (voff)[_i]), (PG8_LAS unsigned*)(lds + (bufoff) + ldsw + _i * 8192), 16, 0, 0); } while (0)
; #define PG8_LDA(dst, b, h) do { _Pragma("unroll") for (int m = 0; m < 4; ++m) _Pragma("unroll") for (int k = 0; k < 2; ++k) dst[m][k] = *(const PG8_LAS bf16x8*)(lds + PG8_SA(b, h) + aoff + m * 2048 + k * 1024); } while (0)
; #define PG8_LDB(dst, b, h) do { _Pragma("unroll") for (int n = 0; n < 2; ++n) _Pragma("unroll") for (int k = 0; k < 2; ++k) dst[n][k] = *(const PG8_LAS bf16x8*)(lds + PG8_SB(b, h) + boff + n * 2048 + k * 1024); } while (0)
; #define PG8_MMA(ai, bj, At, Bt) do { __builtin_amdgcn_s_setprio(1); _Pragma("unroll") for (int m = 0; m < 4; ++m) _Pragma("unroll") for (int n = 0; n < 2; ++n) _Pragma("unroll") for (int k = 0; k < 2; ++k) \
;         acc[ai][bj][m][n] = __builtin_amdgcn_mfma_f32_16x16x32_bf16(Bt[n][k], At[m][k], acc[ai][bj][m][n], 0, 0, 0); __builtin_amdgcn_s_setprio(0); } while (0)
; #define PG8_WAIT_V(n) asm volatile("s_waitcnt vmcnt(" #n ")" ::: "memory")
; #define PG8_WAIT_L(n) asm volatile("s_waitcnt lgkmcnt(" #n ")" ::: "memory")
; #define PG8_BAR __builtin_amdgcn_s_barrier()
; #define PG8_SCHED __builtin_amdgcn_sched_barrier(0)
; template <class Epi, class Sched, bool ALIGN_EPI = false, bool SP2 = false>
; __device__ __forceinline__ void gemm_phase(PG8_LAS unsigned char* lds, const Gemm g, const Sched& S, const Epi& E) {
;     ...
;             PG8_WAIT_V(8); PG8_WAIT_L(0); PG8_BAR; PG8_MMA(1, 0, At, B0); PG8_MMA(1, 1, At, B1); PG8_BAR; PG8_SCHED;
;             PG8_LDB(B0, 1, 0); PG8_LDB(B1, 1, 1); PG8_SCHED; PG8_LDA(At, 1, 0); PG8_STAGE(PG8_SA(0, 1), a2 + hstep, voffA);
;             PG8_WAIT_V(8); PG8_WAIT_L(0); PG8_BAR; PG8_MMA(0, 0, At, B0); PG8_MMA(0, 1, At, B1); PG8_BAR; PG8_SCHED;
	s_setprio 1
	s_waitcnt lgkmcnt(0)
	v_mfma_f32_16x16x32_bf16 v[60:63], v[112:115], v[164:167], v[60:63]
	v_mfma_f32_16x16x32_bf16 v[56:59], v[120:123], v[164:167], v[56:59]
	v_mfma_f32_16x16x32_bf16 v[44:47], v[112:115], v[176:179], v[44:47]
	v_mfma_f32_16x16x32_bf16 v[40:43], v[120:123], v[176:179], v[40:43]
	v_mfma_f32_16x16x32_bf16 v[28:31], v[112:115], v[184:187], v[28:31]
	v_mfma_f32_16x16x32_bf16 v[24:27], v[120:123], v[184:187], v[24:27]
	v_mfma_f32_16x16x32_bf16 v[12:15], v[112:115], v[192:195], v[12:15]
	v_mfma_f32_16x16x32_bf16 v[8:11], v[120:123], v[192:195], v[8:11]
	v_mfma_f32_16x16x32_bf16 v[60:63], v[116:119], v[172:175], v[60:63]
	v_mfma_f32_16x16x32_bf16 v[56:59], v[124:127], v[172:175], v[56:59]
	v_mfma_f32_16x16x32_bf16 v[44:47], v[116:119], v[180:183], v[44:47]
	v_mfma_f32_16x16x32_bf16 v[40:43], v[124:127], v[180:183], v[40:43]
	v_mfma_f32_16x16x32_bf16 v[28:31], v[116:119], v[188:191], v[28:31]
	v_mfma_f32_16x16x32_bf16 v[24:27], v[124:127], v[188:191], v[24:27]
	v_mfma_f32_16x16x32_bf16 v[12:15], v[116:119], v[210:213], v[12:15]
	v_mfma_f32_16x16x32_bf16 v[8:11], v[124:127], v[210:213], v[8:11]
	s_setprio 0
	s_setprio 1
	v_mfma_f32_16x16x32_bf16 v[52:55], v[136:139], v[164:167], v[52:55]
	v_mfma_f32_16x16x32_bf16 v[48:51], v[152:155], v[164:167], v[48:51]
	v_mfma_f32_16x16x32_bf16 v[36:39], v[136:139], v[176:179], v[36:39]
	v_mfma_f32_16x16x32_bf16 v[32:35], v[152:155], v[176:179], v[32:35]
	v_mfma_f32_16x16x32_bf16 v[20:23], v[136:139], v[184:187], v[20:23]
	v_mfma_f32_16x16x32_bf16 v[16:19], v[152:155], v[184:187], v[16:19]
	v_mfma_f32_16x16x32_bf16 v[4:7], v[136:139], v[192:195], v[4:7]
	v_mfma_f32_16x16x32_bf16 v[0:3], v[152:155], v[192:195], v[0:3]
	v_mfma_f32_16x16x32_bf16 v[52:55], v[140:143], v[172:175], v[52:55]
	v_mfma_f32_16x16x32_bf16 v[48:51], v[156:159], v[172:175], v[48:51]
	v_mfma_f32_16x16x32_bf16 v[36:39], v[140:143], v[180:183], v[36:39]
	v_mfma_f32_16x16x32_bf16 v[32:35], v[156:159], v[180:183], v[32:35]
	v_mfma_f32_16x16x32_bf16 v[20:23], v[140:143], v[188:191], v[20:23]
	v_mfma_f32_16x16x32_bf16 v[16:19], v[156:159], v[188:191], v[16:19]
	v_mfma_f32_16x16x32_bf16 v[4:7], v[140:143], v[210:213], v[4:7]
	v_mfma_f32_16x16x32_bf16 v[0:3], v[156:159], v[210:213], v[0:3]
	s_setprio 0
	s_barrier
.Lmid_g2:
	s_add_i32 s5, 0, 0x18000
	s_add_i32 s8, 0, 0x1c000
	v_add_u32_e32 v124, s5, v240
	v_add_u32_e32 v156, s8, v240
	ds_read_b128 v[112:115], v124
	ds_read_b128 v[116:119], v124 offset:1024
	ds_read_b128 v[120:123], v124 offset:2048
	ds_read_b128 v[124:127], v124 offset:3072
	ds_read_b128 v[136:139], v156
	ds_read_b128 v[140:143], v156 offset:1024
	ds_read_b128 v[152:155], v156 offset:2048
	ds_read_b128 v[156:159], v156 offset:3072
	s_add_u32 s20, s64, 0x40000
	s_addc_u32 s21, s65, 0
	s_mov_b32 m0, s69
	v_lshl_add_u64 v[222:223], s[20:21], 0, v[204:205]
	ds_read_b128 v[164:167], v242 offset:32768
	ds_read_b128 v[172:175], v242 offset:33792
	ds_read_b128 v[176:179], v242 offset:34816
	ds_read_b128 v[180:183], v242 offset:35840
	ds_read_b128 v[184:187], v242 offset:36864
	ds_read_b128 v[188:191], v242 offset:37888
	ds_read_b128 v[192:195], v242 offset:38912
	ds_read_b128 v[210:213], v242 offset:39936
	global_load_lds_dwordx4 v[222:223], off
	v_lshl_add_u64 v[222:223], s[20:21], 0, v[200:201]
	s_mov_b32 m0, s70
	s_nop 0
	global_load_lds_dwordx4 v[222:223], off
	s_waitcnt vmcnt(8)
	s_barrier
	s_setprio 1
	s_waitcnt lgkmcnt(0)
	v_mfma_f32_16x16x32_bf16 v[168:171], v[112:115], v[164:167], v[168:171]
	v_mfma_f32_16x16x32_bf16 v[160:163], v[120:123], v[164:167], v[160:163]
	v_mfma_f32_16x16x32_bf16 v[108:111], v[112:115], v[176:179], v[108:111]
	v_mfma_f32_16x16x32_bf16 v[104:107], v[120:123], v[176:179], v[104:107]
	v_mfma_f32_16x16x32_bf16 v[92:95], v[112:115], v[184:187], v[92:95]
	v_mfma_f32_16x16x32_bf16 v[88:91], v[120:123], v[184:187], v[88:91]
	v_mfma_f32_16x16x32_bf16 v[76:79], v[112:115], v[192:195], v[76:79]
	v_mfma_f32_16x16x32_bf16 v[72:75], v[120:123], v[192:195], v[72:75]
	v_mfma_f32_16x16x32_bf16 v[168:171], v[116:119], v[172:175], v[168:171]
	v_mfma_f32_16x16x32_bf16 v[160:163], v[124:127], v[172:175], v[160:163]
	v_mfma_f32_16x16x32_bf16 v[108:111], v[116:119], v[180:183], v[108:111]
	v_mfma_f32_16x16x32_bf16 v[104:107], v[124:127], v[180:183], v[104:107]
	v_mfma_f32_16x16x32_bf16 v[92:95], v[116:119], v[188:191], v[92:95]
	v_mfma_f32_16x16x32_bf16 v[88:91], v[124:127], v[188:191], v[88:91]
	v_mfma_f32_16x16x32_bf16 v[76:79], v[116:119], v[210:213], v[76:79]
	v_mfma_f32_16x16x32_bf16 v[72:75], v[124:127], v[210:213], v[72:75]
	s_setprio 0
	s_setprio 1
	v_mfma_f32_16x16x32_bf16 v[132:135], v[136:139], v[164:167], v[132:135]
	v_mfma_f32_16x16x32_bf16 v[128:131], v[152:155], v[164:167], v[128:131]
	v_mfma_f32_16x16x32_bf16 v[100:103], v[136:139], v[176:179], v[100:103]
	v_mfma_f32_16x16x32_bf16 v[96:99], v[152:155], v[176:179], v[96:99]
	v_mfma_f32_16x16x32_bf16 v[84:87], v[136:139], v[184:187], v[84:87]
	v_mfma_f32_16x16x32_bf16 v[80:83], v[152:155], v[184:187], v[80:83]
	v_mfma_f32_16x16x32_bf16 v[68:71], v[136:139], v[192:195], v[68:71]
	v_mfma_f32_16x16x32_bf16 v[64:67], v[152:155], v[192:195], v[64:67]
	v_mfma_f32_16x16x32_bf16 v[132:135], v[140:143], v[172:175], v[132:135]
	v_mfma_f32_16x16x32_bf16 v[128:131], v[156:159], v[172:175], v[128:131]
	v_mfma_f32_16x16x32_bf16 v[100:103], v[140:143], v[180:183], v[100:103]
	v_mfma_f32_16x16x32_bf16 v[96:99], v[156:159], v[180:183], v[96:99]
	v_mfma_f32_16x16x32_bf16 v[84:87], v[140:143], v[188:191], v[84:87]
	v_mfma_f32_16x16x32_bf16 v[80:83], v[156:159], v[188:191], v[80:83]
	v_mfma_f32_16x16x32_bf16 v[68:71], v[140:143], v[210:213], v[68:71]
	v_mfma_f32_16x16x32_bf16 v[64:67], v[156:159], v[210:213], v[64:67]
	s_setprio 0
	s_barrier
; #define PG8_STAGE(bufoff, gbase, voff) do { _Pragma("unroll") for (int _i = 0; _i < 2; ++_i) \
;         __builtin_amdgcn_global_load_lds((const unsigned*)((const char*)(gbase) + (voff)[_i]), (PG8_LAS unsigned*)(lds + (bufoff) + ldsw + _i * 8192), 16, 0, 0); } while (0)
; #define PG8_LDA(dst, b, h) do { _Pragma("unroll") for (int m = 0; m < 4; ++m) _Pragma("unroll") for (int k = 0; k < 2; ++k) dst[m][k] = *(const PG8_LAS bf16x8*)(lds + PG8_SA(b, h) + aoff + m * 2048 + k * 1024); } while (0)
; #define PG8_MMA(ai, bj, At, Bt) do { __builtin_amdgcn_s_setprio(1); _Pragma("unroll") for (int m = 0; m < 4; ++m) _Pragma("unroll") for (int n = 0; n < 2; ++n) _Pragma("unroll") for (int k = 0; k < 2; ++k) \
;         acc[ai][bj][m][n] = __builtin_amdgcn_mfma_f32_16x16x32_bf16(Bt[n][k], At[m][k], acc[ai][bj][m][n], 0, 0, 0); __builtin_amdgcn_s_setprio(0); } while (0)
; #define PG8_WAIT_V(n) asm volatile("s_waitcnt vmcnt(" #n ")" ::: "memory")
; #define PG8_WAIT_L(n) asm volatile("s_waitcnt lgkmcnt(" #n ")" ::: "memory")
; #define PG8_BAR __builtin_amdgcn_s_barrier()
; #define PG8_SCHED __builtin_amdgcn_sched_barrier(0)
; template <class Epi, class Sched, bool ALIGN_EPI = false, bool SP2 = false>
; __device__ __forceinline__ void gemm_phase(PG8_LAS unsigned char* lds, const Gemm g, const Sched& S, const Epi& E) {
;     ...
;             PG8_LDA(At, 1, 1); PG8_STAGE(PG8_SB(1, 0), b3, voffB); PG8_STAGE(PG8_SB(1, 1), b3 + hstep, voffB); PG8_STAGE(PG8_SA(1, 0), a3, voffA);
;             PG8_WAIT_V(8); PG8_WAIT_L(0); PG8_BAR; PG8_MMA(1, 0, At, B0); PG8_MMA(1, 1, At, B1); PG8_BAR; PG8_SCHED;
;     ...
;         if constexpr (ALIGN_EPI) { if (wr == 0) PG8_BAR; }
	s_add_i32 s5, s5, s66
	v_lshl_add_u64 v[214:215], v[214:215], 0, s[22:23]
	s_mov_b32 m0, s5
	ds_read_b128 v[164:167], v242 offset:49152
	ds_read_b128 v[172:175], v242 offset:50176
	ds_read_b128 v[176:179], v242 offset:51200
	ds_read_b128 v[180:183], v242 offset:52224
	ds_read_b128 v[184:187], v242 offset:53248
	ds_read_b128 v[188:191], v242 offset:54272
	ds_read_b128 v[192:195], v242 offset:55296
	ds_read_b128 v[210:213], v242 offset:56320
	global_load_lds_dwordx4 v[214:215], off
	s_add_i32 m0, s5, 0x2000
	s_add_u32 s20, s62, 0x40080
	v_lshl_add_u64 v[214:215], v[216:217], 0, s[22:23]
	s_addc_u32 s21, s63, 0
	s_add_i32 s5, s8, s66
	global_load_lds_dwordx4 v[214:215], off
	v_lshl_add_u64 v[214:215], s[20:21], 0, v[202:203]
	s_mov_b32 m0, s5
	s_nop 0
	global_load_lds_dwordx4 v[214:215], off
	v_lshl_add_u64 v[214:215], s[20:21], 0, v[146:147]
	s_add_i32 m0, s5, 0x2000
	s_nop 0
	global_load_lds_dwordx4 v[214:215], off
	v_lshl_add_u64 v[214:215], v[218:219], 0, s[22:23]
	s_mov_b32 m0, s34
	s_nop 0
	global_load_lds_dwordx4 v[214:215], off
	v_lshl_add_u64 v[214:215], v[220:221], 0, s[22:23]
	s_mov_b32 m0, s71
	s_nop 0
	global_load_lds_dwordx4 v[214:215], off
	s_waitcnt vmcnt(8)
	s_barrier
	s_setprio 1
	s_waitcnt lgkmcnt(0)
	v_mfma_f32_16x16x32_bf16 v[60:63], v[112:115], v[164:167], v[60:63]
	v_mfma_f32_16x16x32_bf16 v[56:59], v[120:123], v[164:167], v[56:59]
	v_mfma_f32_16x16x32_bf16 v[44:47], v[112:115], v[176:179], v[44:47]
	v_mfma_f32_16x16x32_bf16 v[40:43], v[120:123], v[176:179], v[40:43]
	v_mfma_f32_16x16x32_bf16 v[28:31], v[112:115], v[184:187], v[28:31]
	v_mfma_f32_16x16x32_bf16 v[24:27], v[120:123], v[184:187], v[24:27]
	v_mfma_f32_16x16x32_bf16 v[12:15], v[112:115], v[192:195], v[12:15]
	v_mfma_f32_16x16x32_bf16 v[8:11], v[120:123], v[192:195], v[8:11]
	v_mfma_f32_16x16x32_bf16 v[60:63], v[116:119], v[172:175], v[60:63]
	v_mfma_f32_16x16x32_bf16 v[56:59], v[124:127], v[172:175], v[56:59]
	v_mfma_f32_16x16x32_bf16 v[44:47], v[116:119], v[180:183], v[44:47]
	v_mfma_f32_16x16x32_bf16 v[40:43], v[124:127], v[180:183], v[40:43]
	v_mfma_f32_16x16x32_bf16 v[28:31], v[116:119], v[188:191], v[28:31]
	v_mfma_f32_16x16x32_bf16 v[24:27], v[124:127], v[188:191], v[24:27]
	v_mfma_f32_16x16x32_bf16 v[12:15], v[116:119], v[210:213], v[12:15]
	v_mfma_f32_16x16x32_bf16 v[8:11], v[124:127], v[210:213], v[8:11]
	s_setprio 0
	s_setprio 1
	v_mfma_f32_16x16x32_bf16 v[52:55], v[136:139], v[164:167], v[52:55]
	v_mfma_f32_16x16x32_bf16 v[48:51], v[152:155], v[164:167], v[48:51]
	v_mfma_f32_16x16x32_bf16 v[36:39], v[136:139], v[176:179], v[36:39]
	v_mfma_f32_16x16x32_bf16 v[32:35], v[152:155], v[176:179], v[32:35]
	v_mfma_f32_16x16x32_bf16 v[20:23], v[136:139], v[184:187], v[20:23]
	v_mfma_f32_16x16x32_bf16 v[16:19], v[152:155], v[184:187], v[16:19]
	v_mfma_f32_16x16x32_bf16 v[4:7], v[136:139], v[192:195], v[4:7]
	v_mfma_f32_16x16x32_bf16 v[0:3], v[152:155], v[192:195], v[0:3]
	v_mfma_f32_16x16x32_bf16 v[52:55], v[140:143], v[172:175], v[52:55]
	v_mfma_f32_16x16x32_bf16 v[48:51], v[156:159], v[172:175], v[48:51]
	v_mfma_f32_16x16x32_bf16 v[36:39], v[140:143], v[180:183], v[36:39]
	v_mfma_f32_16x16x32_bf16 v[32:35], v[156:159], v[180:183], v[32:35]
	v_mfma_f32_16x16x32_bf16 v[20:23], v[140:143], v[188:191], v[20:23]
	v_mfma_f32_16x16x32_bf16 v[16:19], v[156:159], v[188:191], v[16:19]
	v_mfma_f32_16x16x32_bf16 v[4:7], v[140:143], v[210:213], v[4:7]
	v_mfma_f32_16x16x32_bf16 v[0:3], v[156:159], v[210:213], v[0:3]
	s_setprio 0
	s_barrier
	s_add_i32 s74, s74, 2
	s_add_u32 s55, s55, 0x100
	s_addc_u32 s73, s73, 0
	s_add_u32 s60, s60, 0x100
	s_addc_u32 s61, s61, 0
	s_cmp_gt_u32 s74, 13
	s_cbranch_scc0 .LBB0_174
	s_and_b64 vcc, exec, s[50:51]
	s_cbranch_vccz .LBB0_177
	s_barrier

; #define PG8_STAGE(bufoff, gbase, voff) do { _Pragma("unroll") for (int _i = 0; _i < 2; ++_i) \
;         __builtin_amdgcn_global_load_lds((const unsigned*)((const char*)(gbase) + (voff)[_i]), (PG8_LAS unsigned*)(lds + (bufoff) + ldsw + _i * 8192), 16, 0, 0); } while (0)
; #define PG8_LDA(dst, b, h) do { _Pragma("unroll") for (int m = 0; m < 4; ++m) _Pragma("unroll") for (int k = 0; k < 2; ++k) dst[m][k] = *(const PG8_LAS bf16x8*)(lds + PG8_SA(b, h) + aoff + m * 2048 + k * 1024); } while (0)
; #define PG8_LDB(dst, b, h) do { _Pragma("unroll") for (int n = 0; n < 2; ++n) _Pragma("unroll") for (int k = 0; k < 2; ++k) dst[n][k] = *(const PG8_LAS bf16x8*)(lds + PG8_SB(b, h) + boff + n * 2048 + k * 1024); } while (0)
; #define PG8_MMA(ai, bj, At, Bt) do { __builtin_amdgcn_s_setprio(1); _Pragma("unroll") for (int m = 0; m < 4; ++m) _Pragma("unroll") for (int n = 0; n < 2; ++n) _Pragma("unroll") for (int k = 0; k < 2; ++k) \
;         acc[ai][bj][m][n] = __builtin_amdgcn_mfma_f32_16x16x32_bf16(Bt[n][k], At[m][k], acc[ai][bj][m][n], 0, 0, 0); __builtin_amdgcn_s_setprio(0); } while (0)
; #define PG8_WAIT_V(n) asm volatile("s_waitcnt vmcnt(" #n ")" ::: "memory")
; #define PG8_WAIT_L(n) asm volatile("s_waitcnt lgkmcnt(" #n ")" ::: "memory")
; template <class Epi, class Sched, bool ALIGN_EPI = false, bool SP2 = false>
; __device__ __forceinline__ void gemm_phase(PG8_LAS unsigned char* lds, const Gemm g, const Sched& S, const Epi& E) {
;     ...
;             const bool last = (t == nt - 2);
;             const char* a1 = cA + (size_t)(t + 1) * kstep;
;             const char* a2 = last ? nA : cA + (size_t)(t + 2) * kstep; const char* b2 = last ? nB : cB + (size_t)(t + 2) * kstep;
;             const char* a3 = a2 + kstep; const char* b3 = b2 + kstep;
;             if (last && has_next) S.a_ready(nxt);
;             if constexpr (SP2) {
;             PG8_LDB(B0, 0, 0); PG8_LDB(B1, 0, 1); PG8_SCHED; PG8_LDA(At, 0, 0); PG8_STAGE(PG8_SA(1, 1), a1 + hstep, voffA);
;             PG8_WAIT_V(8); PG8_WAIT_L(0); PG8_BAR; PG8_MMA(0, 0, At, B0); PG8_MMA(0, 1, At, B1); PG8_BAR; PG8_SCHED;
;             PG8_LDA(At, 0, 1); PG8_STAGE(PG8_SB(0, 0), b2, voffB); PG8_STAGE(PG8_SB(0, 1), b2 + hstep, voffB); PG8_STAGE(PG8_SA(0, 0), a2, voffA);
;             PG8_WAIT_V(8); PG8_WAIT_L(0); PG8_BAR; PG8_MMA(1, 0, At, B0); PG8_MMA(1, 1, At, B1); PG8_BAR; PG8_SCHED;
.Lpeel_g1e:
	s_add_u32 s8, s44, 0xfffc0080
	s_addc_u32 s10, s45, -1
	s_add_i32 s12, 0, 0x10000
	s_cmp_eq_u32 s69, 12
	s_cselect_b32 s57, s4, s10
	s_cselect_b32 s56, s26, s8
	v_add_u32_e32 v154, s12, v157
	s_cselect_b32 s55, s27, s49
	s_cselect_b32 s54, s36, s47
	s_add_i32 s8, 0, 0x14000
	ds_read_b128 v[162:165], v154
	ds_read_b128 v[166:169], v154 offset:1024
	ds_read_b128 v[170:173], v154 offset:2048
	ds_read_b128 v[174:177], v154 offset:3072
	v_add_u32_e32 v154, s8, v157
	ds_read_b128 v[178:181], v154
	ds_read_b128 v[182:185], v154 offset:1024
	ds_read_b128 v[186:189], v154 offset:2048
	ds_read_b128 v[190:193], v154 offset:3072
	v_lshl_add_u64 v[194:195], s[44:45], 0, v[140:141]
	s_add_i32 m0, s58, 0xc000
	ds_read_b128 v[200:203], v161
	ds_read_b128 v[204:207], v161 offset:1024
	ds_read_b128 v[208:211], v161 offset:2048
	ds_read_b128 v[212:215], v161 offset:3072
	ds_read_b128 v[216:219], v161 offset:4096
	ds_read_b128 v[220:223], v161 offset:5120
	ds_read_b128 v[224:227], v161 offset:6144
	ds_read_b128 v[228:231], v161 offset:7168
	global_load_lds_dwordx4 v[194:195], off
	v_lshl_add_u64 v[194:195], s[44:45], 0, v[138:139]
	s_add_i32 m0, s58, 0xe000
	s_nop 0
	global_load_lds_dwordx4 v[194:195], off
	s_waitcnt vmcnt(26)
	s_barrier
	s_setprio 1
	s_waitcnt lgkmcnt(0)
	v_mfma_f32_16x16x32_bf16 v[124:127], v[162:165], v[200:203], 0
	v_mfma_f32_16x16x32_bf16 v[120:123], v[170:173], v[200:203], 0
	v_mfma_f32_16x16x32_bf16 v[108:111], v[162:165], v[208:211], 0
	v_mfma_f32_16x16x32_bf16 v[104:107], v[170:173], v[208:211], 0
	v_mfma_f32_16x16x32_bf16 v[92:95], v[162:165], v[216:219], 0
	v_mfma_f32_16x16x32_bf16 v[88:91], v[170:173], v[216:219], 0
	v_mfma_f32_16x16x32_bf16 v[76:79], v[162:165], v[224:227], 0
	v_mfma_f32_16x16x32_bf16 v[72:75], v[170:173], v[224:227], 0
	v_mfma_f32_16x16x32_bf16 v[124:127], v[166:169], v[204:207], v[124:127]
	v_mfma_f32_16x16x32_bf16 v[120:123], v[174:177], v[204:207], v[120:123]
	v_mfma_f32_16x16x32_bf16 v[108:111], v[166:169], v[212:215], v[108:111]
	v_mfma_f32_16x16x32_bf16 v[104:107], v[174:177], v[212:215], v[104:107]
	v_mfma_f32_16x16x32_bf16 v[92:95], v[166:169], v[220:223], v[92:95]
	v_mfma_f32_16x16x32_bf16 v[88:91], v[174:177], v[220:223], v[88:91]
	v_mfma_f32_16x16x32_bf16 v[76:79], v[166:169], v[228:231], v[76:79]
	v_mfma_f32_16x16x32_bf16 v[72:75], v[174:177], v[228:231], v[72:75]
	s_setprio 0
	s_setprio 1
	v_mfma_f32_16x16x32_bf16 v[116:119], v[178:181], v[200:203], 0
	v_mfma_f32_16x16x32_bf16 v[112:115], v[186:189], v[200:203], 0
	v_mfma_f32_16x16x32_bf16 v[100:103], v[178:181], v[208:211], 0
	v_mfma_f32_16x16x32_bf16 v[96:99], v[186:189], v[208:211], 0
	v_mfma_f32_16x16x32_bf16 v[84:87], v[178:181], v[216:219], 0
	v_mfma_f32_16x16x32_bf16 v[80:83], v[186:189], v[216:219], 0
	v_mfma_f32_16x16x32_bf16 v[68:71], v[178:181], v[224:227], 0
	v_mfma_f32_16x16x32_bf16 v[64:67], v[186:189], v[224:227], 0
	v_mfma_f32_16x16x32_bf16 v[116:119], v[182:185], v[204:207], v[116:119]
	v_mfma_f32_16x16x32_bf16 v[112:115], v[190:193], v[204:207], v[112:115]
	v_mfma_f32_16x16x32_bf16 v[100:103], v[182:185], v[212:215], v[100:103]
	v_mfma_f32_16x16x32_bf16 v[96:99], v[190:193], v[212:215], v[96:99]
	v_mfma_f32_16x16x32_bf16 v[84:87], v[182:185], v[220:223], v[84:87]
	v_mfma_f32_16x16x32_bf16 v[80:83], v[190:193], v[220:223], v[80:83]
	v_mfma_f32_16x16x32_bf16 v[68:71], v[182:185], v[228:231], v[68:71]
	v_mfma_f32_16x16x32_bf16 v[64:67], v[190:193], v[228:231], v[64:67]
	s_setprio 0
	s_barrier
	s_add_i32 s10, s12, s39
	v_lshl_add_u64 v[194:195], s[54:55], 0, v[132:133]
	s_mov_b32 m0, s10
	ds_read_b128 v[200:203], v161 offset:16384
	ds_read_b128 v[204:207], v161 offset:17408
	ds_read_b128 v[208:211], v161 offset:18432
	ds_read_b128 v[212:215], v161 offset:19456
	ds_read_b128 v[216:219], v161 offset:20480
	ds_read_b128 v[220:223], v161 offset:21504
	ds_read_b128 v[224:227], v161 offset:22528
	ds_read_b128 v[228:231], v161 offset:23552
	global_load_lds_dwordx4 v[194:195], off
	s_add_i32 m0, s10, 0x2000
	s_add_u32 s70, s54, 0x40000
	v_lshl_add_u64 v[240:241], s[54:55], 0, v[128:129]
	s_addc_u32 s71, s55, 0
	s_add_i32 s8, s8, s39
	global_load_lds_dwordx4 v[240:241], off
	v_lshl_add_u64 v[242:243], s[70:71], 0, v[132:133]
	s_mov_b32 m0, s8
	v_lshl_add_u64 v[244:245], s[56:57], 0, v[130:131]
	global_load_lds_dwordx4 v[242:243], off
	v_lshl_add_u64 v[242:243], s[70:71], 0, v[128:129]
	s_add_i32 m0, s8, 0x2000
	s_nop 0
	global_load_lds_dwordx4 v[242:243], off
	v_lshl_add_u64 v[242:243], s[56:57], 0, v[134:135]
	s_mov_b32 m0, s58
	s_nop 0
	global_load_lds_dwordx4 v[242:243], off
	s_mov_b32 m0, s59
	s_nop 0
	global_load_lds_dwordx4 v[244:245], off
	s_waitcnt vmcnt(26)
	s_barrier
	s_setprio 1
	s_waitcnt lgkmcnt(0)
	v_mfma_f32_16x16x32_bf16 v[60:63], v[162:165], v[200:203], 0
	v_mfma_f32_16x16x32_bf16 v[56:59], v[170:173], v[200:203], 0
	v_mfma_f32_16x16x32_bf16 v[44:47], v[162:165], v[208:211], 0
	v_mfma_f32_16x16x32_bf16 v[40:43], v[170:173], v[208:211], 0
	v_mfma_f32_16x16x32_bf16 v[28:31], v[162:165], v[216:219], 0
	v_mfma_f32_16x16x32_bf16 v[24:27], v[170:173], v[216:219], 0
	v_mfma_f32_16x16x32_bf16 v[12:15], v[162:165], v[224:227], 0
	v_mfma_f32_16x16x32_bf16 v[8:11], v[170:173], v[224:227], 0
	v_mfma_f32_16x16x32_bf16 v[60:63], v[166:169], v[204:207], v[60:63]
	v_mfma_f32_16x16x32_bf16 v[56:59], v[174:177], v[204:207], v[56:59]
	v_mfma_f32_16x16x32_bf16 v[44:47], v[166:169], v[212:215], v[44:47]
	v_mfma_f32_16x16x32_bf16 v[40:43], v[174:177], v[212:215], v[40:43]
	v_mfma_f32_16x16x32_bf16 v[28:31], v[166:169], v[220:223], v[28:31]
	v_mfma_f32_16x16x32_bf16 v[24:27], v[174:177], v[220:223], v[24:27]
	v_mfma_f32_16x16x32_bf16 v[12:15], v[166:169], v[228:231], v[12:15]
	v_mfma_f32_16x16x32_bf16 v[8:11], v[174:177], v[228:231], v[8:11]
	s_setprio 0
	s_setprio 1
	v_mfma_f32_16x16x32_bf16 v[52:55], v[178:181], v[200:203], 0
	v_mfma_f32_16x16x32_bf16 v[48:51], v[186:189], v[200:203], 0
	v_mfma_f32_16x16x32_bf16 v[36:39], v[178:181], v[208:211], 0
	v_mfma_f32_16x16x32_bf16 v[32:35], v[186:189], v[208:211], 0
	v_mfma_f32_16x16x32_bf16 v[20:23], v[178:181], v[216:219], 0
	v_mfma_f32_16x16x32_bf16 v[16:19], v[186:189], v[216:219], 0
	v_mfma_f32_16x16x32_bf16 v[4:7], v[178:181], v[224:227], 0
	v_mfma_f32_16x16x32_bf16 v[0:3], v[186:189], v[224:227], 0
	v_mfma_f32_16x16x32_bf16 v[52:55], v[182:185], v[204:207], v[52:55]
	v_mfma_f32_16x16x32_bf16 v[48:51], v[190:193], v[204:207], v[48:51]
	v_mfma_f32_16x16x32_bf16 v[36:39], v[182:185], v[212:215], v[36:39]
	v_mfma_f32_16x16x32_bf16 v[32:35], v[190:193], v[212:215], v[32:35]
	v_mfma_f32_16x16x32_bf16 v[20:23], v[182:185], v[220:223], v[20:23]
	v_mfma_f32_16x16x32_bf16 v[16:19], v[190:193], v[220:223], v[16:19]
	v_mfma_f32_16x16x32_bf16 v[4:7], v[182:185], v[228:231], v[4:7]
	v_mfma_f32_16x16x32_bf16 v[0:3], v[190:193], v[228:231], v[0:3]
	s_setprio 0
	s_barrier
	s_branch .Lmid_g1e

; #define PG8_STAGE(bufoff, gbase, voff) do { _Pragma("unroll") for (int _i = 0; _i < 2; ++_i) \
;         __builtin_amdgcn_global_load_lds((const unsigned*)((const char*)(gbase) + (voff)[_i]), (PG8_LAS unsigned*)(lds + (bufoff) + ldsw + _i * 8192), 16, 0, 0); } while (0)
; #define PG8_LDA(dst, b, h) do { _Pragma("unroll") for (int m = 0; m < 4; ++m) _Pragma("unroll") for (int k = 0; k < 2; ++k) dst[m][k] = *(const PG8_LAS bf16x8*)(lds + PG8_SA(b, h) + aoff + m * 2048 + k * 1024); } while (0)
; #define PG8_LDB(dst, b, h) do { _Pragma("unroll") for (int n = 0; n < 2; ++n) _Pragma("unroll") for (int k = 0; k < 2; ++k) dst[n][k] = *(const PG8_LAS bf16x8*)(lds + PG8_SB(b, h) + boff + n * 2048 + k * 1024); } while (0)
; #define PG8_MMA(ai, bj, At, Bt) do { __builtin_amdgcn_s_setprio(1); _Pragma("unroll") for (int m = 0; m < 4; ++m) _Pragma("unroll") for (int n = 0; n < 2; ++n) _Pragma("unroll") for (int k = 0; k < 2; ++k) \
;         acc[ai][bj][m][n] = __builtin_amdgcn_mfma_f32_16x16x32_bf16(Bt[n][k], At[m][k], acc[ai][bj][m][n], 0, 0, 0); __builtin_amdgcn_s_setprio(0); } while (0)
; #define PG8_WAIT_V(n) asm volatile("s_waitcnt vmcnt(" #n ")" ::: "memory")
; #define PG8_WAIT_L(n) asm volatile("s_waitcnt lgkmcnt(" #n ")" ::: "memory")
; #define PG8_BAR __builtin_amdgcn_s_barrier()
; #define PG8_SCHED __builtin_amdgcn_sched_barrier(0)
; template <class Epi, class Sched, bool ALIGN_EPI = false, bool SP2 = false>
; __device__ __forceinline__ void gemm_phase(PG8_LAS unsigned char* lds, const Gemm g, const Sched& S, const Epi& E) {
;     ...
;             PG8_LDB(B0, 0, 0); PG8_LDB(B1, 0, 1); PG8_SCHED; PG8_LDA(At, 0, 0); PG8_STAGE(PG8_SA(1, 1), a1 + hstep, voffA);
;             PG8_WAIT_V(8); PG8_WAIT_L(0); PG8_BAR; PG8_MMA(0, 0, At, B0); PG8_MMA(0, 1, At, B1); PG8_BAR; PG8_SCHED;
;             PG8_LDA(At, 0, 1); PG8_STAGE(PG8_SB(0, 0), b2, voffB); PG8_STAGE(PG8_SB(0, 1), b2 + hstep, voffB); PG8_STAGE(PG8_SA(0, 0), a2, voffA);
;             PG8_WAIT_V(8); PG8_WAIT_L(0); PG8_BAR; PG8_MMA(1, 0, At, B0); PG8_MMA(1, 1, At, B1); PG8_BAR; PG8_SCHED;
.LBB0_414:
	s_add_u32 s8, s44, 0xfffc0080
	s_addc_u32 s10, s45, -1
	s_add_i32 s12, 0, 0x10000
	s_cmp_eq_u32 s69, 12
	s_cselect_b32 s57, s4, s10
	s_cselect_b32 s56, s26, s8
	v_add_u32_e32 v154, s12, v157
	s_cselect_b32 s55, s27, s49
	s_cselect_b32 s54, s36, s47
	s_add_i32 s8, 0, 0x14000
	ds_read_b128 v[162:165], v154
	ds_read_b128 v[166:169], v154 offset:1024
	ds_read_b128 v[170:173], v154 offset:2048
	ds_read_b128 v[174:177], v154 offset:3072
	v_add_u32_e32 v154, s8, v157
	ds_read_b128 v[178:181], v154
	ds_read_b128 v[182:185], v154 offset:1024
	ds_read_b128 v[186:189], v154 offset:2048
	ds_read_b128 v[190:193], v154 offset:3072
	v_lshl_add_u64 v[194:195], s[44:45], 0, v[140:141]
	s_add_i32 m0, s58, 0xc000
	ds_read_b128 v[200:203], v161
	ds_read_b128 v[204:207], v161 offset:1024
	ds_read_b128 v[208:211], v161 offset:2048
	ds_read_b128 v[212:215], v161 offset:3072
	ds_read_b128 v[216:219], v161 offset:4096
	ds_read_b128 v[220:223], v161 offset:5120
	ds_read_b128 v[224:227], v161 offset:6144
	ds_read_b128 v[228:231], v161 offset:7168
	global_load_lds_dwordx4 v[194:195], off
	v_lshl_add_u64 v[194:195], s[44:45], 0, v[138:139]
	s_add_i32 m0, s58, 0xe000
	s_nop 0
	global_load_lds_dwordx4 v[194:195], off
	s_waitcnt vmcnt(8)
	s_barrier
	s_setprio 1
	s_waitcnt lgkmcnt(0)
	v_mfma_f32_16x16x32_bf16 v[124:127], v[162:165], v[200:203], v[124:127]
	v_mfma_f32_16x16x32_bf16 v[120:123], v[170:173], v[200:203], v[120:123]
	v_mfma_f32_16x16x32_bf16 v[108:111], v[162:165], v[208:211], v[108:111]
	v_mfma_f32_16x16x32_bf16 v[104:107], v[170:173], v[208:211], v[104:107]
	v_mfma_f32_16x16x32_bf16 v[92:95], v[162:165], v[216:219], v[92:95]
	v_mfma_f32_16x16x32_bf16 v[88:91], v[170:173], v[216:219], v[88:91]
	v_mfma_f32_16x16x32_bf16 v[76:79], v[162:165], v[224:227], v[76:79]
	v_mfma_f32_16x16x32_bf16 v[72:75], v[170:173], v[224:227], v[72:75]
	v_mfma_f32_16x16x32_bf16 v[124:127], v[166:169], v[204:207], v[124:127]
	v_mfma_f32_16x16x32_bf16 v[120:123], v[174:177], v[204:207], v[120:123]
	v_mfma_f32_16x16x32_bf16 v[108:111], v[166:169], v[212:215], v[108:111]
	v_mfma_f32_16x16x32_bf16 v[104:107], v[174:177], v[212:215], v[104:107]
	v_mfma_f32_16x16x32_bf16 v[92:95], v[166:169], v[220:223], v[92:95]
	v_mfma_f32_16x16x32_bf16 v[88:91], v[174:177], v[220:223], v[88:91]
	v_mfma_f32_16x16x32_bf16 v[76:79], v[166:169], v[228:231], v[76:79]
	v_mfma_f32_16x16x32_bf16 v[72:75], v[174:177], v[228:231], v[72:75]
	s_setprio 0
	s_setprio 1
	v_mfma_f32_16x16x32_bf16 v[116:119], v[178:181], v[200:203], v[116:119]
	v_mfma_f32_16x16x32_bf16 v[112:115], v[186:189], v[200:203], v[112:115]
	v_mfma_f32_16x16x32_bf16 v[100:103], v[178:181], v[208:211], v[100:103]
	v_mfma_f32_16x16x32_bf16 v[96:99], v[186:189], v[208:211], v[96:99]
	v_mfma_f32_16x16x32_bf16 v[84:87], v[178:181], v[216:219], v[84:87]
	v_mfma_f32_16x16x32_bf16 v[80:83], v[186:189], v[216:219], v[80:83]
	v_mfma_f32_16x16x32_bf16 v[68:71], v[178:181], v[224:227], v[68:71]
	v_mfma_f32_16x16x32_bf16 v[64:67], v[186:189], v[224:227], v[64:67]
	v_mfma_f32_16x16x32_bf16 v[116:119], v[182:185], v[204:207], v[116:119]
	v_mfma_f32_16x16x32_bf16 v[112:115], v[190:193], v[204:207], v[112:115]
	v_mfma_f32_16x16x32_bf16 v[100:103], v[182:185], v[212:215], v[100:103]
	v_mfma_f32_16x16x32_bf16 v[96:99], v[190:193], v[212:215], v[96:99]
	v_mfma_f32_16x16x32_bf16 v[84:87], v[182:185], v[220:223], v[84:87]
	v_mfma_f32_16x16x32_bf16 v[80:83], v[190:193], v[220:223], v[80:83]
	v_mfma_f32_16x16x32_bf16 v[68:71], v[182:185], v[228:231], v[68:71]
	v_mfma_f32_16x16x32_bf16 v[64:67], v[190:193], v[228:231], v[64:67]
	s_setprio 0
	s_barrier
	s_add_i32 s10, s12, s39
	v_lshl_add_u64 v[194:195], s[54:55], 0, v[132:133]
	s_mov_b32 m0, s10
	ds_read_b128 v[200:203], v161 offset:16384
	ds_read_b128 v[204:207], v161 offset:17408
	ds_read_b128 v[208:211], v161 offset:18432
	ds_read_b128 v[212:215], v161 offset:19456
	ds_read_b128 v[216:219], v161 offset:20480
	ds_read_b128 v[220:223], v161 offset:21504
	ds_read_b128 v[224:227], v161 offset:22528
	ds_read_b128 v[228:231], v161 offset:23552
	global_load_lds_dwordx4 v[194:195], off
	s_add_i32 m0, s10, 0x2000
	s_add_u32 s70, s54, 0x40000
	v_lshl_add_u64 v[240:241], s[54:55], 0, v[128:129]
	s_addc_u32 s71, s55, 0
	s_add_i32 s8, s8, s39
	global_load_lds_dwordx4 v[240:241], off
	v_lshl_add_u64 v[242:243], s[70:71], 0, v[132:133]
	s_mov_b32 m0, s8
	v_lshl_add_u64 v[244:245], s[56:57], 0, v[130:131]
	global_load_lds_dwordx4 v[242:243], off
	v_lshl_add_u64 v[242:243], s[70:71], 0, v[128:129]
	s_add_i32 m0, s8, 0x2000
	s_nop 0
	global_load_lds_dwordx4 v[242:243], off
	v_lshl_add_u64 v[242:243], s[56:57], 0, v[134:135]
	s_mov_b32 m0, s58
	s_nop 0
	global_load_lds_dwordx4 v[242:243], off
	s_mov_b32 m0, s59
	s_nop 0
	global_load_lds_dwordx4 v[244:245], off
	s_waitcnt vmcnt(8)
	s_barrier
; #define PG8_STAGE(bufoff, gbase, voff) do { _Pragma("unroll") for (int _i = 0; _i < 2; ++_i) \
;         __builtin_amdgcn_global_load_lds((const unsigned*)((const char*)(gbase) + (voff)[_i]), (PG8_LAS unsigned*)(lds + (bufoff) + ldsw + _i * 8192), 16, 0, 0); } while (0)
; #define PG8_LDA(dst, b, h) do { _Pragma("unroll") for (int m = 0; m < 4; ++m) _Pragma("unroll") for (int k = 0; k < 2; ++k) dst[m][k] = *(const PG8_LAS bf16x8*)(lds + PG8_SA(b, h) + aoff + m * 2048 + k * 1024); } while (0)
; #define PG8_LDB(dst, b, h) do { _Pragma("unroll") for (int n = 0; n < 2; ++n) _Pragma("unroll") for (int k = 0; k < 2; ++k) dst[n][k] = *(const PG8_LAS bf16x8*)(lds + PG8_SB(b, h) + boff + n * 2048 + k * 1024); } while (0)
; #define PG8_MMA(ai, bj, At, Bt) do { __builtin_amdgcn_s_setprio(1); _Pragma("unroll") for (int m = 0; m < 4; ++m) _Pragma("unroll") for (int n = 0; n < 2; ++n) _Pragma("unroll") for (int k = 0; k < 2; ++k) \
;         acc[ai][bj][m][n] = __builtin_amdgcn_mfma_f32_16x16x32_bf16(Bt[n][k], At[m][k], acc[ai][bj][m][n], 0, 0, 0); __builtin_amdgcn_s_setprio(0); } while (0)
; #define PG8_WAIT_V(n) asm volatile("s_waitcnt vmcnt(" #n ")" ::: "memory")
; #define PG8_WAIT_L(n) asm volatile("s_waitcnt lgkmcnt(" #n ")" ::: "memory")
; #define PG8_BAR __builtin_amdgcn_s_barrier()
; #define PG8_SCHED __builtin_amdgcn_sched_barrier(0)
; template <class Epi, class Sched, bool ALIGN_EPI = false, bool SP2 = false>
; __device__ __forceinline__ void gemm_phase(PG8_LAS unsigned char* lds, const Gemm g, const Sched& S, const Epi& E) {
;     ...
;             PG8_WAIT_V(8); PG8_WAIT_L(0); PG8_BAR; PG8_MMA(1, 0, At, B0); PG8_MMA(1, 1, At, B1); PG8_BAR; PG8_SCHED;
;             PG8_LDB(B0, 1, 0); PG8_LDB(B1, 1, 1); PG8_SCHED; PG8_LDA(At, 1, 0); PG8_STAGE(PG8_SA(0, 1), a2 + hstep, voffA);
;             PG8_WAIT_V(8); PG8_WAIT_L(0); PG8_BAR; PG8_MMA(0, 0, At, B0); PG8_MMA(0, 1, At, B1); PG8_BAR; PG8_SCHED;
	s_setprio 1
	s_waitcnt lgkmcnt(0)
	v_mfma_f32_16x16x32_bf16 v[60:63], v[162:165], v[200:203], v[60:63]
	v_mfma_f32_16x16x32_bf16 v[56:59], v[170:173], v[200:203], v[56:59]
	v_mfma_f32_16x16x32_bf16 v[44:47], v[162:165], v[208:211], v[44:47]
	v_mfma_f32_16x16x32_bf16 v[40:43], v[170:173], v[208:211], v[40:43]
	v_mfma_f32_16x16x32_bf16 v[28:31], v[162:165], v[216:219], v[28:31]
	v_mfma_f32_16x16x32_bf16 v[24:27], v[170:173], v[216:219], v[24:27]
	v_mfma_f32_16x16x32_bf16 v[12:15], v[162:165], v[224:227], v[12:15]
	v_mfma_f32_16x16x32_bf16 v[8:11], v[170:173], v[224:227], v[8:11]
	v_mfma_f32_16x16x32_bf16 v[60:63], v[166:169], v[204:207], v[60:63]
	v_mfma_f32_16x16x32_bf16 v[56:59], v[174:177], v[204:207], v[56:59]
	v_mfma_f32_16x16x32_bf16 v[44:47], v[166:169], v[212:215], v[44:47]
	v_mfma_f32_16x16x32_bf16 v[40:43], v[174:177], v[212:215], v[40:43]
	v_mfma_f32_16x16x32_bf16 v[28:31], v[166:169], v[220:223], v[28:31]
	v_mfma_f32_16x16x32_bf16 v[24:27], v[174:177], v[220:223], v[24:27]
	v_mfma_f32_16x16x32_bf16 v[12:15], v[166:169], v[228:231], v[12:15]
	v_mfma_f32_16x16x32_bf16 v[8:11], v[174:177], v[228:231], v[8:11]
	s_setprio 0
	s_setprio 1
	v_mfma_f32_16x16x32_bf16 v[52:55], v[178:181], v[200:203], v[52:55]
	v_mfma_f32_16x16x32_bf16 v[48:51], v[186:189], v[200:203], v[48:51]
	v_mfma_f32_16x16x32_bf16 v[36:39], v[178:181], v[208:211], v[36:39]
	v_mfma_f32_16x16x32_bf16 v[32:35], v[186:189], v[208:211], v[32:35]
	v_mfma_f32_16x16x32_bf16 v[20:23], v[178:181], v[216:219], v[20:23]
	v_mfma_f32_16x16x32_bf16 v[16:19], v[186:189], v[216:219], v[16:19]
	v_mfma_f32_16x16x32_bf16 v[4:7], v[178:181], v[224:227], v[4:7]
	v_mfma_f32_16x16x32_bf16 v[0:3], v[186:189], v[224:227], v[0:3]
	v_mfma_f32_16x16x32_bf16 v[52:55], v[182:185], v[204:207], v[52:55]
	v_mfma_f32_16x16x32_bf16 v[48:51], v[190:193], v[204:207], v[48:51]
	v_mfma_f32_16x16x32_bf16 v[36:39], v[182:185], v[212:215], v[36:39]
	v_mfma_f32_16x16x32_bf16 v[32:35], v[190:193], v[212:215], v[32:35]
	v_mfma_f32_16x16x32_bf16 v[20:23], v[182:185], v[220:223], v[20:23]
	v_mfma_f32_16x16x32_bf16 v[16:19], v[190:193], v[220:223], v[16:19]
	v_mfma_f32_16x16x32_bf16 v[4:7], v[182:185], v[228:231], v[4:7]
	v_mfma_f32_16x16x32_bf16 v[0:3], v[190:193], v[228:231], v[0:3]
	s_setprio 0
	s_barrier
.Lmid_g1e:
	s_add_i32 s8, 0, 0x18000
	v_add_u32_e32 v154, s8, v157
	s_add_i32 s10, 0, 0x1c000
	ds_read_b128 v[162:165], v154
	ds_read_b128 v[166:169], v154 offset:1024
	ds_read_b128 v[170:173], v154 offset:2048
	ds_read_b128 v[174:177], v154 offset:3072
	v_add_u32_e32 v154, s10, v157
	ds_read_b128 v[178:181], v154
	ds_read_b128 v[182:185], v154 offset:1024
	ds_read_b128 v[186:189], v154 offset:2048
	ds_read_b128 v[190:193], v154 offset:3072
	s_add_u32 s56, s56, 0x40000
	s_addc_u32 s57, s57, 0
	s_mov_b32 m0, s60
	v_lshl_add_u64 v[246:247], s[56:57], 0, v[134:135]
	ds_read_b128 v[200:203], v161 offset:32768
	ds_read_b128 v[204:207], v161 offset:33792
	ds_read_b128 v[208:211], v161 offset:34816
	ds_read_b128 v[212:215], v161 offset:35840
	ds_read_b128 v[216:219], v161 offset:36864
	ds_read_b128 v[220:223], v161 offset:37888
	ds_read_b128 v[224:227], v161 offset:38912
	ds_read_b128 v[228:231], v161 offset:39936
	global_load_lds_dwordx4 v[246:247], off
	v_lshl_add_u64 v[246:247], s[56:57], 0, v[130:131]
	s_mov_b32 m0, s61
	s_nop 0
	global_load_lds_dwordx4 v[246:247], off
	s_waitcnt vmcnt(8)
	s_barrier
	s_setprio 1
	s_waitcnt lgkmcnt(0)
	v_mfma_f32_16x16x32_bf16 v[124:127], v[162:165], v[200:203], v[124:127]
	v_mfma_f32_16x16x32_bf16 v[120:123], v[170:173], v[200:203], v[120:123]
	v_mfma_f32_16x16x32_bf16 v[108:111], v[162:165], v[208:211], v[108:111]
	v_mfma_f32_16x16x32_bf16 v[104:107], v[170:173], v[208:211], v[104:107]
	v_mfma_f32_16x16x32_bf16 v[92:95], v[162:165], v[216:219], v[92:95]
	v_mfma_f32_16x16x32_bf16 v[88:91], v[170:173], v[216:219], v[88:91]
	v_mfma_f32_16x16x32_bf16 v[76:79], v[162:165], v[224:227], v[76:79]
	v_mfma_f32_16x16x32_bf16 v[72:75], v[170:173], v[224:227], v[72:75]
	v_mfma_f32_16x16x32_bf16 v[124:127], v[166:169], v[204:207], v[124:127]
	v_mfma_f32_16x16x32_bf16 v[120:123], v[174:177], v[204:207], v[120:123]
	v_mfma_f32_16x16x32_bf16 v[108:111], v[166:169], v[212:215], v[108:111]
	v_mfma_f32_16x16x32_bf16 v[104:107], v[174:177], v[212:215], v[104:107]
	v_mfma_f32_16x16x32_bf16 v[92:95], v[166:169], v[220:223], v[92:95]
	v_mfma_f32_16x16x32_bf16 v[88:91], v[174:177], v[220:223], v[88:91]
	v_mfma_f32_16x16x32_bf16 v[76:79], v[166:169], v[228:231], v[76:79]
	v_mfma_f32_16x16x32_bf16 v[72:75], v[174:177], v[228:231], v[72:75]
	s_setprio 0
	s_setprio 1
	v_mfma_f32_16x16x32_bf16 v[116:119], v[178:181], v[200:203], v[116:119]
	v_mfma_f32_16x16x32_bf16 v[112:115], v[186:189], v[200:203], v[112:115]
	v_mfma_f32_16x16x32_bf16 v[100:103], v[178:181], v[208:211], v[100:103]
	v_mfma_f32_16x16x32_bf16 v[96:99], v[186:189], v[208:211], v[96:99]
	v_mfma_f32_16x16x32_bf16 v[84:87], v[178:181], v[216:219], v[84:87]
	v_mfma_f32_16x16x32_bf16 v[80:83], v[186:189], v[216:219], v[80:83]
	v_mfma_f32_16x16x32_bf16 v[68:71], v[178:181], v[224:227], v[68:71]
	v_mfma_f32_16x16x32_bf16 v[64:67], v[186:189], v[224:227], v[64:67]
	v_mfma_f32_16x16x32_bf16 v[116:119], v[182:185], v[204:207], v[116:119]
	v_mfma_f32_16x16x32_bf16 v[112:115], v[190:193], v[204:207], v[112:115]
	v_mfma_f32_16x16x32_bf16 v[100:103], v[182:185], v[212:215], v[100:103]
	v_mfma_f32_16x16x32_bf16 v[96:99], v[190:193], v[212:215], v[96:99]
	v_mfma_f32_16x16x32_bf16 v[84:87], v[182:185], v[220:223], v[84:87]
	v_mfma_f32_16x16x32_bf16 v[80:83], v[190:193], v[220:223], v[80:83]
	v_mfma_f32_16x16x32_bf16 v[68:71], v[182:185], v[228:231], v[68:71]
	v_mfma_f32_16x16x32_bf16 v[64:67], v[190:193], v[228:231], v[64:67]
	s_setprio 0
	s_barrier
; #define PG8_STAGE(bufoff, gbase, voff) do { _Pragma("unroll") for (int _i = 0; _i < 2; ++_i) \
;         __builtin_amdgcn_global_load_lds((const unsigned*)((const char*)(gbase) + (voff)[_i]), (PG8_LAS unsigned*)(lds + (bufoff) + ldsw + _i * 8192), 16, 0, 0); } while (0)
; #define PG8_LDA(dst, b, h) do { _Pragma("unroll") for (int m = 0; m < 4; ++m) _Pragma("unroll") for (int k = 0; k < 2; ++k) dst[m][k] = *(const PG8_LAS bf16x8*)(lds + PG8_SA(b, h) + aoff + m * 2048 + k * 1024); } while (0)
; #define PG8_MMA(ai, bj, At, Bt) do { __builtin_amdgcn_s_setprio(1); _Pragma("unroll") for (int m = 0; m < 4; ++m) _Pragma("unroll") for (int n = 0; n < 2; ++n) _Pragma("unroll") for (int k = 0; k < 2; ++k) \
;         acc[ai][bj][m][n] = __builtin_amdgcn_mfma_f32_16x16x32_bf16(Bt[n][k], At[m][k], acc[ai][bj][m][n], 0, 0, 0); __builtin_amdgcn_s_setprio(0); } while (0)
; #define PG8_WAIT_V(n) asm volatile("s_waitcnt vmcnt(" #n ")" ::: "memory")
; #define PG8_WAIT_L(n) asm volatile("s_waitcnt lgkmcnt(" #n ")" ::: "memory")
; #define PG8_BAR __builtin_amdgcn_s_barrier()
; #define PG8_SCHED __builtin_amdgcn_sched_barrier(0)
; template <class Epi, class Sched, bool ALIGN_EPI = false, bool SP2 = false>
; __device__ __forceinline__ void gemm_phase(PG8_LAS unsigned char* lds, const Gemm g, const Sched& S, const Epi& E) {
;     ...
;             PG8_LDA(At, 1, 1); PG8_STAGE(PG8_SB(1, 0), b3, voffB); PG8_STAGE(PG8_SB(1, 1), b3 + hstep, voffB); PG8_STAGE(PG8_SA(1, 0), a3, voffA);
;             PG8_WAIT_V(8); PG8_WAIT_L(0); PG8_BAR; PG8_MMA(1, 0, At, B0); PG8_MMA(1, 1, At, B1); PG8_BAR; PG8_SCHED;
;     ...
;         if constexpr (ALIGN_EPI) { if (wr == 0) PG8_BAR; }
	s_add_i32 s8, s8, s39
	v_lshl_add_u64 v[194:195], v[194:195], 0, s[22:23]
	s_mov_b32 m0, s8
	ds_read_b128 v[200:203], v161 offset:49152
	ds_read_b128 v[204:207], v161 offset:50176
	ds_read_b128 v[208:211], v161 offset:51200
	ds_read_b128 v[212:215], v161 offset:52224
	ds_read_b128 v[216:219], v161 offset:53248
	ds_read_b128 v[220:223], v161 offset:54272
	ds_read_b128 v[224:227], v161 offset:55296
	ds_read_b128 v[228:231], v161 offset:56320
	global_load_lds_dwordx4 v[194:195], off
	s_add_i32 m0, s8, 0x2000
	s_add_u32 s54, s54, 0x40080
	v_lshl_add_u64 v[194:195], v[240:241], 0, s[22:23]
	s_addc_u32 s55, s55, 0
	s_add_i32 s8, s10, s39
	global_load_lds_dwordx4 v[194:195], off
	v_lshl_add_u64 v[194:195], s[54:55], 0, v[132:133]
	s_mov_b32 m0, s8
	s_nop 0
	global_load_lds_dwordx4 v[194:195], off
	v_lshl_add_u64 v[194:195], s[54:55], 0, v[128:129]
	s_add_i32 m0, s8, 0x2000
	s_nop 0
	global_load_lds_dwordx4 v[194:195], off
	v_lshl_add_u64 v[194:195], v[242:243], 0, s[22:23]
	s_mov_b32 m0, s64
	s_nop 0
	global_load_lds_dwordx4 v[194:195], off
	v_lshl_add_u64 v[194:195], v[244:245], 0, s[22:23]
	s_mov_b32 m0, s65
	s_nop 0
	global_load_lds_dwordx4 v[194:195], off
	s_waitcnt vmcnt(8)
	s_barrier
	s_setprio 1
	s_waitcnt lgkmcnt(0)
	v_mfma_f32_16x16x32_bf16 v[60:63], v[162:165], v[200:203], v[60:63]
	v_mfma_f32_16x16x32_bf16 v[56:59], v[170:173], v[200:203], v[56:59]
	v_mfma_f32_16x16x32_bf16 v[44:47], v[162:165], v[208:211], v[44:47]
	v_mfma_f32_16x16x32_bf16 v[40:43], v[170:173], v[208:211], v[40:43]
	v_mfma_f32_16x16x32_bf16 v[28:31], v[162:165], v[216:219], v[28:31]
	v_mfma_f32_16x16x32_bf16 v[24:27], v[170:173], v[216:219], v[24:27]
	v_mfma_f32_16x16x32_bf16 v[12:15], v[162:165], v[224:227], v[12:15]
	v_mfma_f32_16x16x32_bf16 v[8:11], v[170:173], v[224:227], v[8:11]
	v_mfma_f32_16x16x32_bf16 v[60:63], v[166:169], v[204:207], v[60:63]
	v_mfma_f32_16x16x32_bf16 v[56:59], v[174:177], v[204:207], v[56:59]
	v_mfma_f32_16x16x32_bf16 v[44:47], v[166:169], v[212:215], v[44:47]
	v_mfma_f32_16x16x32_bf16 v[40:43], v[174:177], v[212:215], v[40:43]
	v_mfma_f32_16x16x32_bf16 v[28:31], v[166:169], v[220:223], v[28:31]
	v_mfma_f32_16x16x32_bf16 v[24:27], v[174:177], v[220:223], v[24:27]
	v_mfma_f32_16x16x32_bf16 v[12:15], v[166:169], v[228:231], v[12:15]
	v_mfma_f32_16x16x32_bf16 v[8:11], v[174:177], v[228:231], v[8:11]
	s_setprio 0
	s_setprio 1
	v_mfma_f32_16x16x32_bf16 v[52:55], v[178:181], v[200:203], v[52:55]
	v_mfma_f32_16x16x32_bf16 v[48:51], v[186:189], v[200:203], v[48:51]
	v_mfma_f32_16x16x32_bf16 v[36:39], v[178:181], v[208:211], v[36:39]
	v_mfma_f32_16x16x32_bf16 v[32:35], v[186:189], v[208:211], v[32:35]
	v_mfma_f32_16x16x32_bf16 v[20:23], v[178:181], v[216:219], v[20:23]
	v_mfma_f32_16x16x32_bf16 v[16:19], v[186:189], v[216:219], v[16:19]
	v_mfma_f32_16x16x32_bf16 v[4:7], v[178:181], v[224:227], v[4:7]
	v_mfma_f32_16x16x32_bf16 v[0:3], v[186:189], v[224:227], v[0:3]
	v_mfma_f32_16x16x32_bf16 v[52:55], v[182:185], v[204:207], v[52:55]
	v_mfma_f32_16x16x32_bf16 v[48:51], v[190:193], v[204:207], v[48:51]
	v_mfma_f32_16x16x32_bf16 v[36:39], v[182:185], v[212:215], v[36:39]
	v_mfma_f32_16x16x32_bf16 v[32:35], v[190:193], v[212:215], v[32:35]
	v_mfma_f32_16x16x32_bf16 v[20:23], v[182:185], v[220:223], v[20:23]
	v_mfma_f32_16x16x32_bf16 v[16:19], v[190:193], v[220:223], v[16:19]
	v_mfma_f32_16x16x32_bf16 v[4:7], v[182:185], v[228:231], v[4:7]
	v_mfma_f32_16x16x32_bf16 v[0:3], v[190:193], v[228:231], v[0:3]
	s_setprio 0
	s_barrier
	s_add_i32 s69, s69, 2
	s_add_u32 s47, s47, 0x100
	s_addc_u32 s49, s49, 0
	s_add_u32 s44, s44, 0x100
	s_addc_u32 s45, s45, 0
	s_cmp_gt_u32 s69, 13
	s_cbranch_scc0 .LBB0_414
	s_and_b64 vcc, exec, s[20:21]
	s_cbranch_vccz .LBB0_417
	s_barrier
